# v8: plus conversion-loop cache-touch prefetch, EpiIn ssq hoists, gate_unit batched gv loads
# speedup vs baseline: 1.0419x; 1.0165x over previous
; template <bool UPMAP = false>
; DI void transpose_item(const float* W, int K, int N, bf16_t* WT, const float* gain, LAS float* scr, int item, int lane) {
;     const int nblk = N / 32, kb = item / nblk, nb = item % nblk, k0 = 64 * kb, n0 = 32 * nb;
;     const int r0 = !UPMAP ? n0 : (n0 < DFF ? ((n0 >> 7) << 8) + (n0 & 127) : (((n0 - DFF) >> 7) << 8) + 128 + ((n0 - DFF) & 127));
; #pragma unroll
;     for (int i = 0; i < 32; ++i) { const int kk = 2 * i + (lane >> 5); float v = W[(size_t)(k0 + kk) * N + n0 + (lane & 31)]; if (gain) v *= gain[k0 + kk]; scr[kk * 33 + (lane & 31)] = v; }
.LBB0_6:
	s_mul_hi_i32 s6, s17, 0x66666667
	s_lshr_b32 s7, s6, 31
	s_ashr_i32 s6, s6, 5
	s_add_i32 s6, s6, s7
	s_lshl_b32 s14, s6, 6
	s_mulk_i32 s6, 0xf600
	s_add_i32 s6, s12, s6
	s_ashr_i32 s7, s6, 31
	v_lshl_add_u64 v[6:7], s[6:7], 2, v[2:3]
	v_or_b32_e32 v8, s14, v12
	v_mad_i64_i32 v[10:11], s[18:19], v8, s16, v[6:7]
	v_mov_b32_e32 v102, 0x5000
	v_mov_b32_e32 v103, 0
	v_mov_b64_e32 v[100:101], v[10:11]
	v_lshl_add_u64 v[100:101], v[102:103], 0, v[100:101]
	global_load_dword v104, v[100:101], off
	v_lshl_add_u64 v[100:101], v[102:103], 0, v[100:101]
	global_load_dword v104, v[100:101], off
	v_lshl_add_u64 v[100:101], v[102:103], 0, v[100:101]
	global_load_dword v104, v[100:101], off
	v_lshl_add_u64 v[100:101], v[102:103], 0, v[100:101]
	global_load_dword v104, v[100:101], off
	v_lshl_add_u64 v[100:101], v[102:103], 0, v[100:101]
	global_load_dword v104, v[100:101], off
	v_lshl_add_u64 v[100:101], v[102:103], 0, v[100:101]
	global_load_dword v104, v[100:101], off
	v_lshl_add_u64 v[100:101], v[102:103], 0, v[100:101]
	global_load_dword v104, v[100:101], off
	v_lshl_add_u64 v[100:101], v[102:103], 0, v[100:101]
	global_load_dword v104, v[100:101], off
	v_lshl_add_u64 v[100:101], v[102:103], 0, v[100:101]
	global_load_dword v104, v[100:101], off
	v_lshl_add_u64 v[100:101], v[102:103], 0, v[100:101]
	global_load_dword v104, v[100:101], off
	v_lshl_add_u64 v[100:101], v[102:103], 0, v[100:101]
	global_load_dword v104, v[100:101], off
	v_lshl_add_u64 v[100:101], v[102:103], 0, v[100:101]
	global_load_dword v104, v[100:101], off
	v_lshl_add_u64 v[100:101], v[102:103], 0, v[100:101]
	global_load_dword v104, v[100:101], off
	v_lshl_add_u64 v[100:101], v[102:103], 0, v[100:101]
	global_load_dword v104, v[100:101], off
	v_lshl_add_u64 v[100:101], v[102:103], 0, v[100:101]
	global_load_dword v104, v[100:101], off
	v_lshl_add_u64 v[100:101], v[102:103], 0, v[100:101]
	global_load_dword v104, v[100:101], off
	v_lshl_add_u64 v[100:101], v[102:103], 0, v[100:101]
	global_load_dword v104, v[100:101], off
	v_lshl_add_u64 v[100:101], v[102:103], 0, v[100:101]
	global_load_dword v104, v[100:101], off
	v_lshl_add_u64 v[100:101], v[102:103], 0, v[100:101]
	global_load_dword v104, v[100:101], off
	v_lshl_add_u64 v[100:101], v[102:103], 0, v[100:101]
	global_load_dword v104, v[100:101], off
	v_lshl_add_u64 v[100:101], v[102:103], 0, v[100:101]
	global_load_dword v104, v[100:101], off
	v_lshl_add_u64 v[100:101], v[102:103], 0, v[100:101]
	global_load_dword v104, v[100:101], off
	v_lshl_add_u64 v[100:101], v[102:103], 0, v[100:101]
	global_load_dword v104, v[100:101], off
	v_lshl_add_u64 v[100:101], v[102:103], 0, v[100:101]
	global_load_dword v104, v[100:101], off
	v_lshl_add_u64 v[100:101], v[102:103], 0, v[100:101]
	global_load_dword v104, v[100:101], off
	v_lshl_add_u64 v[100:101], v[102:103], 0, v[100:101]
	global_load_dword v104, v[100:101], off
	v_lshl_add_u64 v[100:101], v[102:103], 0, v[100:101]
	global_load_dword v104, v[100:101], off
	v_lshl_add_u64 v[100:101], v[102:103], 0, v[100:101]
	global_load_dword v104, v[100:101], off
	v_lshl_add_u64 v[100:101], v[102:103], 0, v[100:101]
	global_load_dword v104, v[100:101], off
	v_lshl_add_u64 v[100:101], v[102:103], 0, v[100:101]
	global_load_dword v104, v[100:101], off
	v_lshl_add_u64 v[100:101], v[102:103], 0, v[100:101]
	global_load_dword v104, v[100:101], off
	global_load_dword v17, v[10:11], off
	v_ashrrev_i32_e32 v9, 31, v8
	s_and_b64 vcc, exec, s[2:3]
	v_lshl_add_u64 v[10:11], v[8:9], 2, s[4:5]
	s_cbranch_vccnz .LBB0_8
	global_load_dword v9, v[10:11], off
	s_waitcnt vmcnt(0)
	v_mul_f32_e32 v17, v17, v9

; template <bool UPMAP = false>
; DI void transpose_item(const float* W, int K, int N, bf16_t* WT, const float* gain, LAS float* scr, int item, int lane) {
;     const int nblk = N / 32, kb = item / nblk, nb = item % nblk, k0 = 64 * kb, n0 = 32 * nb;
;     const int r0 = !UPMAP ? n0 : (n0 < DFF ? ((n0 >> 7) << 8) + (n0 & 127) : (((n0 - DFF) >> 7) << 8) + 128 + ((n0 - DFF) & 127));
; #pragma unroll
;     for (int i = 0; i < 32; ++i) { const int kk = 2 * i + (lane >> 5); float v = W[(size_t)(k0 + kk) * N + n0 + (lane & 31)]; if (gain) v *= gain[k0 + kk]; scr[kk * 33 + (lane & 31)] = v; }
.LBB0_76:
	s_ashr_i32 s14, s16, 31
	s_lshr_b32 s14, s14, 27
	s_add_i32 s14, s16, s14
	s_ashr_i32 s15, s14, 5
	s_lshl_b32 s14, s15, 6
	s_lshl_b32 s15, s15, 10
	s_sub_i32 s18, s12, s15
	v_or_b32_e32 v10, s14, v12
	s_ashr_i32 s19, s18, 31
	v_ashrrev_i32_e32 v11, 31, v10
	v_lshl_add_u64 v[6:7], s[18:19], 2, v[2:3]
	v_lshlrev_b64 v[8:9], 12, v[10:11]
	v_lshl_add_u64 v[8:9], v[6:7], 0, v[8:9]
	v_mov_b32_e32 v102, 0x2000
	v_mov_b32_e32 v103, 0
	v_mov_b64_e32 v[100:101], v[8:9]
	v_lshl_add_u64 v[100:101], v[102:103], 0, v[100:101]
	global_load_dword v104, v[100:101], off
	v_lshl_add_u64 v[100:101], v[102:103], 0, v[100:101]
	global_load_dword v104, v[100:101], off
	v_lshl_add_u64 v[100:101], v[102:103], 0, v[100:101]
	global_load_dword v104, v[100:101], off
	v_lshl_add_u64 v[100:101], v[102:103], 0, v[100:101]
	global_load_dword v104, v[100:101], off
	v_lshl_add_u64 v[100:101], v[102:103], 0, v[100:101]
	global_load_dword v104, v[100:101], off
	v_lshl_add_u64 v[100:101], v[102:103], 0, v[100:101]
	global_load_dword v104, v[100:101], off
	v_lshl_add_u64 v[100:101], v[102:103], 0, v[100:101]
	global_load_dword v104, v[100:101], off
	v_lshl_add_u64 v[100:101], v[102:103], 0, v[100:101]
	global_load_dword v104, v[100:101], off
	v_lshl_add_u64 v[100:101], v[102:103], 0, v[100:101]
	global_load_dword v104, v[100:101], off
	v_lshl_add_u64 v[100:101], v[102:103], 0, v[100:101]
	global_load_dword v104, v[100:101], off
	v_lshl_add_u64 v[100:101], v[102:103], 0, v[100:101]
	global_load_dword v104, v[100:101], off
	v_lshl_add_u64 v[100:101], v[102:103], 0, v[100:101]
	global_load_dword v104, v[100:101], off
	v_lshl_add_u64 v[100:101], v[102:103], 0, v[100:101]
	global_load_dword v104, v[100:101], off
	v_lshl_add_u64 v[100:101], v[102:103], 0, v[100:101]
	global_load_dword v104, v[100:101], off
	v_lshl_add_u64 v[100:101], v[102:103], 0, v[100:101]
	global_load_dword v104, v[100:101], off
	v_lshl_add_u64 v[100:101], v[102:103], 0, v[100:101]
	global_load_dword v104, v[100:101], off
	v_lshl_add_u64 v[100:101], v[102:103], 0, v[100:101]
	global_load_dword v104, v[100:101], off
	v_lshl_add_u64 v[100:101], v[102:103], 0, v[100:101]
	global_load_dword v104, v[100:101], off
	v_lshl_add_u64 v[100:101], v[102:103], 0, v[100:101]
	global_load_dword v104, v[100:101], off
	v_lshl_add_u64 v[100:101], v[102:103], 0, v[100:101]
	global_load_dword v104, v[100:101], off
	v_lshl_add_u64 v[100:101], v[102:103], 0, v[100:101]
	global_load_dword v104, v[100:101], off
	v_lshl_add_u64 v[100:101], v[102:103], 0, v[100:101]
	global_load_dword v104, v[100:101], off
	v_lshl_add_u64 v[100:101], v[102:103], 0, v[100:101]
	global_load_dword v104, v[100:101], off
	v_lshl_add_u64 v[100:101], v[102:103], 0, v[100:101]
	global_load_dword v104, v[100:101], off
	v_lshl_add_u64 v[100:101], v[102:103], 0, v[100:101]
	global_load_dword v104, v[100:101], off
	v_lshl_add_u64 v[100:101], v[102:103], 0, v[100:101]
	global_load_dword v104, v[100:101], off
	v_lshl_add_u64 v[100:101], v[102:103], 0, v[100:101]
	global_load_dword v104, v[100:101], off
	v_lshl_add_u64 v[100:101], v[102:103], 0, v[100:101]
	global_load_dword v104, v[100:101], off
	v_lshl_add_u64 v[100:101], v[102:103], 0, v[100:101]
	global_load_dword v104, v[100:101], off
	v_lshl_add_u64 v[100:101], v[102:103], 0, v[100:101]
	global_load_dword v104, v[100:101], off
	v_lshl_add_u64 v[100:101], v[102:103], 0, v[100:101]
	global_load_dword v104, v[100:101], off
	global_load_dword v17, v[8:9], off
	s_and_b64 vcc, exec, s[4:5]
	v_lshl_add_u64 v[8:9], v[10:11], 2, s[6:7]
	s_cbranch_vccnz .LBB0_78
	global_load_dword v11, v[8:9], off
	s_waitcnt vmcnt(0)
	v_mul_f32_e32 v17, v17, v11

; template <bool UPMAP = false>
; DI void transpose_item(const float* W, int K, int N, bf16_t* WT, const float* gain, LAS float* scr, int item, int lane) {
;     const int nblk = N / 32, kb = item / nblk, nb = item % nblk, k0 = 64 * kb, n0 = 32 * nb;
;     const int r0 = !UPMAP ? n0 : (n0 < DFF ? ((n0 >> 7) << 8) + (n0 & 127) : (((n0 - DFF) >> 7) << 8) + 128 + ((n0 - DFF) & 127));
; #pragma unroll
;     for (int i = 0; i < 32; ++i) { const int kk = 2 * i + (lane >> 5); float v = W[(size_t)(k0 + kk) * N + n0 + (lane & 31)]; if (gain) v *= gain[k0 + kk]; scr[kk * 33 + (lane & 31)] = v; }
.LBB0_280:
	s_mul_hi_i32 s6, s19, 0x2e8ba2e9
	s_lshr_b32 s7, s6, 31
	s_ashr_i32 s6, s6, 5
	s_add_i32 s7, s6, s7
	s_mul_i32 s14, s7, 0xffffea00
	s_add_i32 s14, s12, s14
	s_lshl_b32 s6, s7, 6
	s_ashr_i32 s15, s14, 31
	v_lshl_add_u64 v[6:7], s[14:15], 2, v[2:3]
	v_or_b32_e32 v8, s6, v12
	v_mad_i64_i32 v[10:11], s[20:21], v8, s18, v[6:7]
	v_mov_b32_e32 v102, 0xb000
	v_mov_b32_e32 v103, 0
	v_mov_b64_e32 v[100:101], v[10:11]
	v_lshl_add_u64 v[100:101], v[102:103], 0, v[100:101]
	global_load_dword v104, v[100:101], off
	v_lshl_add_u64 v[100:101], v[102:103], 0, v[100:101]
	global_load_dword v104, v[100:101], off
	v_lshl_add_u64 v[100:101], v[102:103], 0, v[100:101]
	global_load_dword v104, v[100:101], off
	v_lshl_add_u64 v[100:101], v[102:103], 0, v[100:101]
	global_load_dword v104, v[100:101], off
	v_lshl_add_u64 v[100:101], v[102:103], 0, v[100:101]
	global_load_dword v104, v[100:101], off
	v_lshl_add_u64 v[100:101], v[102:103], 0, v[100:101]
	global_load_dword v104, v[100:101], off
	v_lshl_add_u64 v[100:101], v[102:103], 0, v[100:101]
	global_load_dword v104, v[100:101], off
	v_lshl_add_u64 v[100:101], v[102:103], 0, v[100:101]
	global_load_dword v104, v[100:101], off
	v_lshl_add_u64 v[100:101], v[102:103], 0, v[100:101]
	global_load_dword v104, v[100:101], off
	v_lshl_add_u64 v[100:101], v[102:103], 0, v[100:101]
	global_load_dword v104, v[100:101], off
	v_lshl_add_u64 v[100:101], v[102:103], 0, v[100:101]
	global_load_dword v104, v[100:101], off
	v_lshl_add_u64 v[100:101], v[102:103], 0, v[100:101]
	global_load_dword v104, v[100:101], off
	v_lshl_add_u64 v[100:101], v[102:103], 0, v[100:101]
	global_load_dword v104, v[100:101], off
	v_lshl_add_u64 v[100:101], v[102:103], 0, v[100:101]
	global_load_dword v104, v[100:101], off
	v_lshl_add_u64 v[100:101], v[102:103], 0, v[100:101]
	global_load_dword v104, v[100:101], off
	v_lshl_add_u64 v[100:101], v[102:103], 0, v[100:101]
	global_load_dword v104, v[100:101], off
	v_lshl_add_u64 v[100:101], v[102:103], 0, v[100:101]
	global_load_dword v104, v[100:101], off
	v_lshl_add_u64 v[100:101], v[102:103], 0, v[100:101]
	global_load_dword v104, v[100:101], off
	v_lshl_add_u64 v[100:101], v[102:103], 0, v[100:101]
	global_load_dword v104, v[100:101], off
	v_lshl_add_u64 v[100:101], v[102:103], 0, v[100:101]
	global_load_dword v104, v[100:101], off
	v_lshl_add_u64 v[100:101], v[102:103], 0, v[100:101]
	global_load_dword v104, v[100:101], off
	v_lshl_add_u64 v[100:101], v[102:103], 0, v[100:101]
	global_load_dword v104, v[100:101], off
	v_lshl_add_u64 v[100:101], v[102:103], 0, v[100:101]
	global_load_dword v104, v[100:101], off
	v_lshl_add_u64 v[100:101], v[102:103], 0, v[100:101]
	global_load_dword v104, v[100:101], off
	v_lshl_add_u64 v[100:101], v[102:103], 0, v[100:101]
	global_load_dword v104, v[100:101], off
	v_lshl_add_u64 v[100:101], v[102:103], 0, v[100:101]
	global_load_dword v104, v[100:101], off
	v_lshl_add_u64 v[100:101], v[102:103], 0, v[100:101]
	global_load_dword v104, v[100:101], off
	v_lshl_add_u64 v[100:101], v[102:103], 0, v[100:101]
	global_load_dword v104, v[100:101], off
	v_lshl_add_u64 v[100:101], v[102:103], 0, v[100:101]
	global_load_dword v104, v[100:101], off
	v_lshl_add_u64 v[100:101], v[102:103], 0, v[100:101]
	global_load_dword v104, v[100:101], off
	v_lshl_add_u64 v[100:101], v[102:103], 0, v[100:101]
	global_load_dword v104, v[100:101], off
	global_load_dword v17, v[10:11], off
	v_ashrrev_i32_e32 v9, 31, v8
	s_and_b64 vcc, exec, s[2:3]
	v_lshl_add_u64 v[10:11], v[8:9], 2, s[4:5]
	s_cbranch_vccnz .LBB0_282
	global_load_dword v9, v[10:11], off
	s_waitcnt vmcnt(0)
	v_mul_f32_e32 v17, v17, v9

; DI unsigned pk2(float lo, float hi) { f32x2 v = {lo, hi}; bf16x2_t b = __builtin_convertvector(v, bf16x2_t); return __builtin_bit_cast(unsigned, b); }
; DI float rstd_of(float ssq, float inv_n) { return 1.0f / sqrtf(ssq * inv_n + EPS); }
; DI float acc_get(const acc_t* p, float inv_scale) { return (float)(*p) * inv_scale; }
;     DI void operator()(const f32x4 (&acc)[2][2][4][2], const Unit& u, int wr, int wc, int fr, int fq) const {
;     ...
;         EPI_ROWS_BEGIN
;             const float rs = rstd_of(acc_get(ssq + row, 1.0f / SSQ_SCALE), 1.0f / DM);
; #pragma unroll
;             for (int bj = 0; bj < 2; ++bj) { const int col = colb + bj * HALF; f32x4 v0 = acc[ai][bj][m][0] * rs, v1 = acc[ai][bj][m][1] * rs;
;                 if (u.pn == 4 || u.pn == 5) { float* dst = (row < RP ? dvp + (size_t)row * 512 : dvs + (size_t)(row - RP) * 512) + (col - 1024); *(f32x4*)dst = v0; *(f32x4*)(dst + 4) = v1;
;                     if (u.pm < RP / BM) store_pair_transposed(VT + ((size_t)(row >> 11) * 512 + (col - 1024)) * SEQ, SEQ, ((row & (SEQ - 1)) & ~12) | ((row & 4) << 1) | ((row & 8) >> 1)  , fr, pk2(v0[0], v0[1]), pk2(v0[2], v0[3]), pk2(v1[0], v1[1]), pk2(v1[2], v1[3])); }
;                 else {
; #pragma unroll
;                     for (int j = 0; j < 4; ++j) { v0[j] = gelu_t(v0[j]); v1[j] = gelu_t(v1[j]); }
;                     u32x4 w; w.x = pk2(v0[0], v0[1]); w.y = pk2(v0[2], v0[3]); w.z = pk2(v1[0], v1[1]); w.w = pk2(v1[2], v1[3]);
;                     *(u32x4*)(Z + (size_t)row * INC + col) = w; } }
.LBB0_425:
	s_lshl_b32 s45, s78, 8
	s_add_i32 s45, s45, s87
	v_or_b32_e32 v144, s45, v230
	v_ashrrev_i32_e32 v145, 31, v144
	v_lshl_add_u64 v[146:147], v[144:145], 3, s[46:47]
	global_load_dwordx2 v[182:183], v[146:147], off
	global_load_dwordx2 v[184:185], v[146:147], off offset:128
	global_load_dwordx2 v[186:187], v[146:147], off offset:256
	global_load_dwordx2 v[188:189], v[146:147], off offset:384
	global_load_dwordx2 v[190:191], v[146:147], off offset:1024
	global_load_dwordx2 v[192:193], v[146:147], off offset:1152
	global_load_dwordx2 v[194:195], v[146:147], off offset:1280
	global_load_dwordx2 v[196:197], v[146:147], off offset:1408
	s_and_b32 s0, s44, 0x7ffffffe
	s_cmp_lg_u32 s0, 4
	s_cselect_b64 s[14:15], -1, 0
	s_cmpk_lt_i32 s78, 0x100
	v_mad_i64_i32 v[148:149], s[0:1], v144, s12, 0
	v_or_b32_e32 v0, s33, v242
	s_cselect_b64 s[24:25], -1, 0
	s_mov_b64 s[28:29], -1
	v_lshl_add_u64 v[148:149], s[10:11], 0, v[148:149]
	s_waitcnt vmcnt(0)
	v_mov_b64_e32 v[74:75], v[182:183]
	v_ffbh_u32_e32 v1, v75
	v_min_u32_e32 v1, 32, v1
	v_lshlrev_b64 v[74:75], v1, v[74:75]
	v_min_u32_e32 v74, 1, v74
	v_or_b32_e32 v74, v75, v74
	v_cvt_f32_u32_e32 v74, v74
	v_sub_u32_e32 v1, 32, v1
	v_ldexp_f32 v1, v74, v1
	v_mul_f32_e32 v1, 0x35800000, v1
	v_fmamk_f32 v1, v1, 0x3a800000, v222
	s_nop 7
	v_rsq_f32_e32 v142, v1
	s_nop 0
	v_mul_f32_e32 v74, v1, v142
	v_fma_f32 v74, -v74, v142, 1.0
	v_mul_f32_e32 v74, 0.5, v74
	v_fmac_f32_e32 v142, v74, v142
	v_cmp_gt_i32_e64 s[2:3], s71, v144
	s_nop 0
	v_pk_mul_f32 v[80:81], v[4:5], v[142:143] op_sel_hi:[1,0]
	v_pk_mul_f32 v[78:79], v[2:3], v[142:143] op_sel_hi:[1,0]
	v_pk_mul_f32 v[76:77], v[8:9], v[142:143] op_sel_hi:[1,0]
	v_pk_mul_f32 v[74:75], v[6:7], v[142:143] op_sel_hi:[1,0]
	s_and_b64 vcc, exec, s[14:15]
	s_cbranch_vccz .LBB0_427
	v_mul_f32_e32 v1, 0x3d372713, v78
	v_mul_f32_e32 v1, v78, v1
	v_mul_f32_e32 v96, 0x3d372713, v74
	v_fma_f32 v1, v78, v1, v78
	v_mul_f32_e32 v96, v74, v96
	v_mul_f32_e32 v1, 0x3f4c422a, v1
	v_fma_f32 v96, v74, v96, v74
	v_mul_f32_e32 v1, 0xc038aa3b, v1
	v_mul_f32_e32 v96, 0x3f4c422a, v96
	v_exp_f32_e32 v1, v1
	v_mul_f32_e32 v96, 0xc038aa3b, v96
	v_exp_f32_e32 v96, v96
	v_mul_f32_e32 v143, 0x3d372713, v75
	v_add_f32_e32 v1, 1.0, v1
	v_rcp_f32_e32 v150, v1
	v_add_f32_e32 v1, 1.0, v96
	v_mul_f32_e32 v96, 0x3d372713, v79
	v_mul_f32_e32 v96, v79, v96
	v_fma_f32 v96, v79, v96, v79
	v_mul_f32_e32 v143, v75, v143
	v_mul_f32_e32 v96, 0x3f4c422a, v96
	v_fma_f32 v143, v75, v143, v75
	v_mul_f32_e32 v96, 0xc038aa3b, v96
	v_mul_f32_e32 v143, 0x3f4c422a, v143
	v_exp_f32_e32 v96, v96
	v_mul_f32_e32 v143, 0xc038aa3b, v143
	v_exp_f32_e32 v143, v143
	v_rcp_f32_e32 v152, v1
	v_add_f32_e32 v1, 1.0, v96
	v_mul_f32_e32 v96, 0x3d372713, v80
	v_rcp_f32_e32 v151, v1
	v_add_f32_e32 v1, 1.0, v143
	v_mul_f32_e32 v96, v80, v96
	v_mul_f32_e32 v143, 0x3d372713, v76
	v_fma_f32 v96, v80, v96, v80
	v_mul_f32_e32 v143, v76, v143
	v_mul_f32_e32 v96, 0x3f4c422a, v96
	v_fma_f32 v143, v76, v143, v76
	v_mul_f32_e32 v96, 0xc038aa3b, v96
	v_mul_f32_e32 v143, 0x3f4c422a, v143
	v_exp_f32_e32 v96, v96
	v_mul_f32_e32 v143, 0xc038aa3b, v143
	v_exp_f32_e32 v143, v143
	v_rcp_f32_e32 v153, v1
	v_add_f32_e32 v1, 1.0, v96
	v_mul_f32_e32 v96, 0x3d372713, v81
	v_rcp_f32_e32 v174, v1
	v_add_f32_e32 v1, 1.0, v143
	v_mul_f32_e32 v96, v81, v96
	v_mul_f32_e32 v143, 0x3d372713, v77
	v_fma_f32 v96, v81, v96, v81
	v_mul_f32_e32 v143, v77, v143
	v_mul_f32_e32 v96, 0x3f4c422a, v96
	v_fma_f32 v143, v77, v143, v77
	v_mul_f32_e32 v96, 0xc038aa3b, v96
	v_mul_f32_e32 v143, 0x3f4c422a, v143
	v_exp_f32_e32 v96, v96
	v_mul_f32_e32 v143, 0xc038aa3b, v143
	v_exp_f32_e32 v143, v143
	v_rcp_f32_e32 v176, v1
	v_add_f32_e32 v1, 1.0, v96
	v_rcp_f32_e32 v175, v1
	v_add_f32_e32 v1, 1.0, v143
	v_rcp_f32_e32 v177, v1
	v_pk_mul_f32 v[150:151], v[78:79], v[150:151]
	v_pk_mul_f32 v[152:153], v[74:75], v[152:153]
	v_pk_mul_f32 v[174:175], v[80:81], v[174:175]
	v_pk_mul_f32 v[176:177], v[76:77], v[176:177]
	v_mov_b32_e32 v1, v97
	v_cvt_pk_bf16_f32 v150, v150, v151
	v_cvt_pk_bf16_f32 v151, v174, v175
	v_cvt_pk_bf16_f32 v152, v152, v153
	v_cvt_pk_bf16_f32 v153, v176, v177
	v_lshl_add_u64 v[174:175], v[0:1], 1, v[148:149]
	s_mov_b64 s[28:29], 0
	global_store_dwordx4 v[174:175], v[150:153], off

; DI unsigned pk2(float lo, float hi) { f32x2 v = {lo, hi}; bf16x2_t b = __builtin_convertvector(v, bf16x2_t); return __builtin_bit_cast(unsigned, b); }
; DI float rstd_of(float ssq, float inv_n) { return 1.0f / sqrtf(ssq * inv_n + EPS); }
; DI float acc_get(const acc_t* p, float inv_scale) { return (float)(*p) * inv_scale; }
;     DI void operator()(const f32x4 (&acc)[2][2][4][2], const Unit& u, int wr, int wc, int fr, int fq) const {
;     ...
;         EPI_ROWS_BEGIN
;             const float rs = rstd_of(acc_get(ssq + row, 1.0f / SSQ_SCALE), 1.0f / DM);
; #pragma unroll
;             for (int bj = 0; bj < 2; ++bj) { const int col = colb + bj * HALF; f32x4 v0 = acc[ai][bj][m][0] * rs, v1 = acc[ai][bj][m][1] * rs;
;                 if (u.pn == 4 || u.pn == 5) { float* dst = (row < RP ? dvp + (size_t)row * 512 : dvs + (size_t)(row - RP) * 512) + (col - 1024); *(f32x4*)dst = v0; *(f32x4*)(dst + 4) = v1;
;                     if (u.pm < RP / BM) store_pair_transposed(VT + ((size_t)(row >> 11) * 512 + (col - 1024)) * SEQ, SEQ, ((row & (SEQ - 1)) & ~12) | ((row & 4) << 1) | ((row & 8) >> 1)  , fr, pk2(v0[0], v0[1]), pk2(v0[2], v0[3]), pk2(v1[0], v1[1]), pk2(v1[2], v1[3])); }
;                 else {
; #pragma unroll
;                     for (int j = 0; j < 4; ++j) { v0[j] = gelu_t(v0[j]); v1[j] = gelu_t(v1[j]); }
;                     u32x4 w; w.x = pk2(v0[0], v0[1]); w.y = pk2(v0[2], v0[3]); w.z = pk2(v1[0], v1[1]); w.w = pk2(v1[2], v1[3]);
;                     *(u32x4*)(Z + (size_t)row * INC + col) = w; } }
.LBB0_435:
	v_or_b32_e32 v174, 16, v144
	s_mov_b64 s[14:15], -1
	s_nop 1
	v_mov_b64_e32 v[74:75], v[184:185]
	v_ffbh_u32_e32 v1, v75
	v_min_u32_e32 v1, 32, v1
	v_lshlrev_b64 v[74:75], v1, v[74:75]
	v_min_u32_e32 v74, 1, v74
	v_or_b32_e32 v74, v75, v74
	v_cvt_f32_u32_e32 v74, v74
	v_sub_u32_e32 v1, 32, v1
	v_ldexp_f32 v1, v74, v1
	v_mul_f32_e32 v1, 0x35800000, v1
	v_fmamk_f32 v1, v1, 0x3a800000, v222
	v_rsq_f32_e32 v148, v1
	s_nop 0
	v_mul_f32_e32 v74, v1, v148
	v_fma_f32 v74, -v74, v148, 1.0
	v_mul_f32_e32 v74, 0.5, v74
	v_fmac_f32_e32 v148, v74, v148
	v_mad_i64_i32 v[176:177], s[2:3], v174, s12, 0
	s_nop 0
	v_cmp_gt_i32_e64 s[2:3], s71, v174
	v_lshl_add_u64 v[176:177], s[10:11], 0, v[176:177]
	v_pk_mul_f32 v[80:81], v[132:133], v[148:149] op_sel_hi:[1,0]
	v_pk_mul_f32 v[78:79], v[130:131], v[148:149] op_sel_hi:[1,0]
	v_pk_mul_f32 v[76:77], v[128:129], v[148:149] op_sel_hi:[1,0]
	v_pk_mul_f32 v[74:75], v[126:127], v[148:149] op_sel_hi:[1,0]
	s_and_b64 vcc, exec, s[42:43]
	s_cbranch_vccnz .LBB0_437
	v_mul_f32_e32 v1, 0x3d372713, v78
	v_mul_f32_e32 v1, v78, v1
	v_mul_f32_e32 v143, 0x3d372713, v74
	v_fma_f32 v1, v78, v1, v78
	v_mul_f32_e32 v143, v74, v143
	v_mul_f32_e32 v1, 0x3f4c422a, v1
	v_fma_f32 v143, v74, v143, v74
	v_mul_f32_e32 v1, 0xc038aa3b, v1
	v_mul_f32_e32 v143, 0x3f4c422a, v143
	v_exp_f32_e32 v1, v1
	v_mul_f32_e32 v143, 0xc038aa3b, v143
	v_exp_f32_e32 v143, v143
	v_mul_f32_e32 v145, 0x3d372713, v75
	v_add_f32_e32 v1, 1.0, v1
	v_rcp_f32_e32 v150, v1
	v_add_f32_e32 v1, 1.0, v143
	v_mul_f32_e32 v143, 0x3d372713, v79
	v_mul_f32_e32 v143, v79, v143
	v_fma_f32 v143, v79, v143, v79
	v_mul_f32_e32 v145, v75, v145
	v_mul_f32_e32 v143, 0x3f4c422a, v143
	v_fma_f32 v145, v75, v145, v75
	v_mul_f32_e32 v143, 0xc038aa3b, v143
	v_mul_f32_e32 v145, 0x3f4c422a, v145
	v_exp_f32_e32 v143, v143
	v_mul_f32_e32 v145, 0xc038aa3b, v145
	v_exp_f32_e32 v145, v145
	v_rcp_f32_e32 v152, v1
	v_add_f32_e32 v1, 1.0, v143
	v_mul_f32_e32 v143, 0x3d372713, v80
	v_rcp_f32_e32 v151, v1
	v_add_f32_e32 v1, 1.0, v145
	v_mul_f32_e32 v143, v80, v143
	v_mul_f32_e32 v145, 0x3d372713, v76
	v_fma_f32 v143, v80, v143, v80
	v_mul_f32_e32 v145, v76, v145
	v_mul_f32_e32 v143, 0x3f4c422a, v143
	v_fma_f32 v145, v76, v145, v76
	v_mul_f32_e32 v143, 0xc038aa3b, v143
	v_mul_f32_e32 v145, 0x3f4c422a, v145
	v_exp_f32_e32 v143, v143
	v_mul_f32_e32 v145, 0xc038aa3b, v145
	v_exp_f32_e32 v145, v145
	v_rcp_f32_e32 v153, v1
	v_add_f32_e32 v1, 1.0, v143
	v_mul_f32_e32 v143, 0x3d372713, v81
	v_rcp_f32_e32 v178, v1
	v_add_f32_e32 v1, 1.0, v145
	v_mul_f32_e32 v143, v81, v143
	v_mul_f32_e32 v145, 0x3d372713, v77
	v_fma_f32 v143, v81, v143, v81
	v_mul_f32_e32 v145, v77, v145
	v_mul_f32_e32 v143, 0x3f4c422a, v143
	v_fma_f32 v145, v77, v145, v77
	v_mul_f32_e32 v143, 0xc038aa3b, v143
	v_mul_f32_e32 v145, 0x3f4c422a, v145
	v_exp_f32_e32 v143, v143
	v_mul_f32_e32 v145, 0xc038aa3b, v145
	v_exp_f32_e32 v145, v145
	v_rcp_f32_e32 v180, v1
	v_add_f32_e32 v1, 1.0, v143
	v_rcp_f32_e32 v179, v1
	v_add_f32_e32 v1, 1.0, v145
	v_rcp_f32_e32 v181, v1
	v_pk_mul_f32 v[150:151], v[78:79], v[150:151]
	v_pk_mul_f32 v[152:153], v[74:75], v[152:153]
	v_pk_mul_f32 v[178:179], v[80:81], v[178:179]
	v_pk_mul_f32 v[180:181], v[76:77], v[180:181]
	v_mov_b32_e32 v1, v97
	v_cvt_pk_bf16_f32 v150, v150, v151
	v_cvt_pk_bf16_f32 v151, v178, v179
	v_cvt_pk_bf16_f32 v152, v152, v153
	v_cvt_pk_bf16_f32 v153, v180, v181
	v_lshl_add_u64 v[178:179], v[0:1], 1, v[176:177]
	s_mov_b64 s[14:15], 0
	global_store_dwordx4 v[178:179], v[150:153], off

; DI unsigned pk2(float lo, float hi) { f32x2 v = {lo, hi}; bf16x2_t b = __builtin_convertvector(v, bf16x2_t); return __builtin_bit_cast(unsigned, b); }
; DI float rstd_of(float ssq, float inv_n) { return 1.0f / sqrtf(ssq * inv_n + EPS); }
; DI float acc_get(const acc_t* p, float inv_scale) { return (float)(*p) * inv_scale; }
;     DI void operator()(const f32x4 (&acc)[2][2][4][2], const Unit& u, int wr, int wc, int fr, int fq) const {
;     ...
;         EPI_ROWS_BEGIN
;             const float rs = rstd_of(acc_get(ssq + row, 1.0f / SSQ_SCALE), 1.0f / DM);
; #pragma unroll
;             for (int bj = 0; bj < 2; ++bj) { const int col = colb + bj * HALF; f32x4 v0 = acc[ai][bj][m][0] * rs, v1 = acc[ai][bj][m][1] * rs;
;                 if (u.pn == 4 || u.pn == 5) { float* dst = (row < RP ? dvp + (size_t)row * 512 : dvs + (size_t)(row - RP) * 512) + (col - 1024); *(f32x4*)dst = v0; *(f32x4*)(dst + 4) = v1;
;                     if (u.pm < RP / BM) store_pair_transposed(VT + ((size_t)(row >> 11) * 512 + (col - 1024)) * SEQ, SEQ, ((row & (SEQ - 1)) & ~12) | ((row & 4) << 1) | ((row & 8) >> 1)  , fr, pk2(v0[0], v0[1]), pk2(v0[2], v0[3]), pk2(v1[0], v1[1]), pk2(v1[2], v1[3])); }
;                 else {
; #pragma unroll
;                     for (int j = 0; j < 4; ++j) { v0[j] = gelu_t(v0[j]); v1[j] = gelu_t(v1[j]); }
;                     u32x4 w; w.x = pk2(v0[0], v0[1]); w.y = pk2(v0[2], v0[3]); w.z = pk2(v1[0], v1[1]); w.w = pk2(v1[2], v1[3]);
;                     *(u32x4*)(Z + (size_t)row * INC + col) = w; } }
.LBB0_445:
	v_or_b32_e32 v174, 32, v144
	s_mov_b64 s[14:15], -1
	s_nop 1
	v_mov_b64_e32 v[74:75], v[186:187]
	v_ffbh_u32_e32 v1, v75
	v_min_u32_e32 v1, 32, v1
	v_lshlrev_b64 v[74:75], v1, v[74:75]
	v_min_u32_e32 v74, 1, v74
	v_or_b32_e32 v74, v75, v74
	v_cvt_f32_u32_e32 v74, v74
	v_sub_u32_e32 v1, 32, v1
	v_ldexp_f32 v1, v74, v1
	v_mul_f32_e32 v1, 0x35800000, v1
	v_fmamk_f32 v1, v1, 0x3a800000, v222
	v_rsq_f32_e32 v148, v1
	s_nop 0
	v_mul_f32_e32 v74, v1, v148
	v_fma_f32 v74, -v74, v148, 1.0
	v_mul_f32_e32 v74, 0.5, v74
	v_fmac_f32_e32 v148, v74, v148
	v_mad_i64_i32 v[176:177], s[2:3], v174, s12, 0
	s_nop 0
	v_cmp_gt_i32_e64 s[2:3], s71, v174
	v_lshl_add_u64 v[176:177], s[10:11], 0, v[176:177]
	v_pk_mul_f32 v[80:81], v[116:117], v[148:149] op_sel_hi:[1,0]
	v_pk_mul_f32 v[78:79], v[114:115], v[148:149] op_sel_hi:[1,0]
	v_pk_mul_f32 v[76:77], v[112:113], v[148:149] op_sel_hi:[1,0]
	v_pk_mul_f32 v[74:75], v[110:111], v[148:149] op_sel_hi:[1,0]
	s_and_b64 vcc, exec, s[42:43]
	s_cbranch_vccnz .LBB0_447
	v_mul_f32_e32 v1, 0x3d372713, v78
	v_mul_f32_e32 v1, v78, v1
	v_mul_f32_e32 v143, 0x3d372713, v74
	v_fma_f32 v1, v78, v1, v78
	v_mul_f32_e32 v143, v74, v143
	v_mul_f32_e32 v1, 0x3f4c422a, v1
	v_fma_f32 v143, v74, v143, v74
	v_mul_f32_e32 v1, 0xc038aa3b, v1
	v_mul_f32_e32 v143, 0x3f4c422a, v143
	v_exp_f32_e32 v1, v1
	v_mul_f32_e32 v143, 0xc038aa3b, v143
	v_exp_f32_e32 v143, v143
	v_mul_f32_e32 v145, 0x3d372713, v75
	v_add_f32_e32 v1, 1.0, v1
	v_rcp_f32_e32 v150, v1
	v_add_f32_e32 v1, 1.0, v143
	v_mul_f32_e32 v143, 0x3d372713, v79
	v_mul_f32_e32 v143, v79, v143
	v_fma_f32 v143, v79, v143, v79
	v_mul_f32_e32 v145, v75, v145
	v_mul_f32_e32 v143, 0x3f4c422a, v143
	v_fma_f32 v145, v75, v145, v75
	v_mul_f32_e32 v143, 0xc038aa3b, v143
	v_mul_f32_e32 v145, 0x3f4c422a, v145
	v_exp_f32_e32 v143, v143
	v_mul_f32_e32 v145, 0xc038aa3b, v145
	v_exp_f32_e32 v145, v145
	v_rcp_f32_e32 v152, v1
	v_add_f32_e32 v1, 1.0, v143
	v_mul_f32_e32 v143, 0x3d372713, v80
	v_rcp_f32_e32 v151, v1
	v_add_f32_e32 v1, 1.0, v145
	v_mul_f32_e32 v143, v80, v143
	v_mul_f32_e32 v145, 0x3d372713, v76
	v_fma_f32 v143, v80, v143, v80
	v_mul_f32_e32 v145, v76, v145
	v_mul_f32_e32 v143, 0x3f4c422a, v143
	v_fma_f32 v145, v76, v145, v76
	v_mul_f32_e32 v143, 0xc038aa3b, v143
	v_mul_f32_e32 v145, 0x3f4c422a, v145
	v_exp_f32_e32 v143, v143
	v_mul_f32_e32 v145, 0xc038aa3b, v145
	v_exp_f32_e32 v145, v145
	v_rcp_f32_e32 v153, v1
	v_add_f32_e32 v1, 1.0, v143
	v_mul_f32_e32 v143, 0x3d372713, v81
	v_rcp_f32_e32 v178, v1
	v_add_f32_e32 v1, 1.0, v145
	v_mul_f32_e32 v143, v81, v143
	v_mul_f32_e32 v145, 0x3d372713, v77
	v_fma_f32 v143, v81, v143, v81
	v_mul_f32_e32 v145, v77, v145
	v_mul_f32_e32 v143, 0x3f4c422a, v143
	v_fma_f32 v145, v77, v145, v77
	v_mul_f32_e32 v143, 0xc038aa3b, v143
	v_mul_f32_e32 v145, 0x3f4c422a, v145
	v_exp_f32_e32 v143, v143
	v_mul_f32_e32 v145, 0xc038aa3b, v145
	v_exp_f32_e32 v145, v145
	v_rcp_f32_e32 v180, v1
	v_add_f32_e32 v1, 1.0, v143
	v_rcp_f32_e32 v179, v1
	v_add_f32_e32 v1, 1.0, v145
	v_rcp_f32_e32 v181, v1
	v_pk_mul_f32 v[150:151], v[78:79], v[150:151]
	v_pk_mul_f32 v[152:153], v[74:75], v[152:153]
	v_pk_mul_f32 v[178:179], v[80:81], v[178:179]
	v_pk_mul_f32 v[180:181], v[76:77], v[180:181]
	v_mov_b32_e32 v1, v97
	v_cvt_pk_bf16_f32 v150, v150, v151
	v_cvt_pk_bf16_f32 v151, v178, v179
	v_cvt_pk_bf16_f32 v152, v152, v153
	v_cvt_pk_bf16_f32 v153, v180, v181
	v_lshl_add_u64 v[178:179], v[0:1], 1, v[176:177]
	s_mov_b64 s[14:15], 0
	global_store_dwordx4 v[178:179], v[150:153], off

; DI unsigned pk2(float lo, float hi) { f32x2 v = {lo, hi}; bf16x2_t b = __builtin_convertvector(v, bf16x2_t); return __builtin_bit_cast(unsigned, b); }
; DI float rstd_of(float ssq, float inv_n) { return 1.0f / sqrtf(ssq * inv_n + EPS); }
; DI float acc_get(const acc_t* p, float inv_scale) { return (float)(*p) * inv_scale; }
;     DI void operator()(const f32x4 (&acc)[2][2][4][2], const Unit& u, int wr, int wc, int fr, int fq) const {
;     ...
;         EPI_ROWS_BEGIN
;             const float rs = rstd_of(acc_get(ssq + row, 1.0f / SSQ_SCALE), 1.0f / DM);
; #pragma unroll
;             for (int bj = 0; bj < 2; ++bj) { const int col = colb + bj * HALF; f32x4 v0 = acc[ai][bj][m][0] * rs, v1 = acc[ai][bj][m][1] * rs;
;                 if (u.pn == 4 || u.pn == 5) { float* dst = (row < RP ? dvp + (size_t)row * 512 : dvs + (size_t)(row - RP) * 512) + (col - 1024); *(f32x4*)dst = v0; *(f32x4*)(dst + 4) = v1;
;                     if (u.pm < RP / BM) store_pair_transposed(VT + ((size_t)(row >> 11) * 512 + (col - 1024)) * SEQ, SEQ, ((row & (SEQ - 1)) & ~12) | ((row & 4) << 1) | ((row & 8) >> 1)  , fr, pk2(v0[0], v0[1]), pk2(v0[2], v0[3]), pk2(v1[0], v1[1]), pk2(v1[2], v1[3])); }
;                 else {
; #pragma unroll
;                     for (int j = 0; j < 4; ++j) { v0[j] = gelu_t(v0[j]); v1[j] = gelu_t(v1[j]); }
;                     u32x4 w; w.x = pk2(v0[0], v0[1]); w.y = pk2(v0[2], v0[3]); w.z = pk2(v1[0], v1[1]); w.w = pk2(v1[2], v1[3]);
;                     *(u32x4*)(Z + (size_t)row * INC + col) = w; } }
.LBB0_455:
	v_or_b32_e32 v148, 48, v144
	s_mov_b64 s[14:15], -1
	s_nop 1
	v_mov_b64_e32 v[74:75], v[188:189]
	v_ffbh_u32_e32 v1, v75
	v_min_u32_e32 v1, 32, v1
	v_lshlrev_b64 v[74:75], v1, v[74:75]
	v_min_u32_e32 v74, 1, v74
	v_or_b32_e32 v74, v75, v74
	v_cvt_f32_u32_e32 v74, v74
	v_sub_u32_e32 v1, 32, v1
	v_ldexp_f32 v1, v74, v1
	v_mul_f32_e32 v1, 0x35800000, v1
	v_fmamk_f32 v1, v1, 0x3a800000, v222
	v_rsq_f32_e32 v146, v1
	s_nop 0
	v_mul_f32_e32 v74, v1, v146
	v_fma_f32 v74, -v74, v146, 1.0
	v_mul_f32_e32 v74, 0.5, v74
	v_fmac_f32_e32 v146, v74, v146
	v_mad_i64_i32 v[174:175], s[2:3], v148, s12, 0
	s_nop 0
	v_cmp_gt_i32_e64 s[2:3], s71, v148
	v_lshl_add_u64 v[174:175], s[10:11], 0, v[174:175]
	v_pk_mul_f32 v[80:81], v[100:101], v[146:147] op_sel_hi:[1,0]
	v_pk_mul_f32 v[78:79], v[98:99], v[146:147] op_sel_hi:[1,0]
	v_pk_mul_f32 v[76:77], v[92:93], v[146:147] op_sel_hi:[1,0]
	v_pk_mul_f32 v[74:75], v[90:91], v[146:147] op_sel_hi:[1,0]
	s_and_b64 vcc, exec, s[42:43]
	s_cbranch_vccnz .LBB0_457
	v_mul_f32_e32 v1, 0x3d372713, v78
	v_mul_f32_e32 v1, v78, v1
	v_mul_f32_e32 v143, 0x3d372713, v74
	v_fma_f32 v1, v78, v1, v78
	v_mul_f32_e32 v143, v74, v143
	v_mul_f32_e32 v1, 0x3f4c422a, v1
	v_fma_f32 v143, v74, v143, v74
	v_mul_f32_e32 v1, 0xc038aa3b, v1
	v_mul_f32_e32 v143, 0x3f4c422a, v143
	v_exp_f32_e32 v1, v1
	v_mul_f32_e32 v143, 0xc038aa3b, v143
	v_exp_f32_e32 v143, v143
	v_mul_f32_e32 v145, 0x3d372713, v75
	v_add_f32_e32 v1, 1.0, v1
	v_rcp_f32_e32 v150, v1
	v_add_f32_e32 v1, 1.0, v143
	v_mul_f32_e32 v143, 0x3d372713, v79
	v_mul_f32_e32 v143, v79, v143
	v_fma_f32 v143, v79, v143, v79
	v_mul_f32_e32 v145, v75, v145
	v_mul_f32_e32 v143, 0x3f4c422a, v143
	v_fma_f32 v145, v75, v145, v75
	v_mul_f32_e32 v143, 0xc038aa3b, v143
	v_mul_f32_e32 v145, 0x3f4c422a, v145
	v_exp_f32_e32 v143, v143
	v_mul_f32_e32 v145, 0xc038aa3b, v145
	v_exp_f32_e32 v145, v145
	v_rcp_f32_e32 v152, v1
	v_add_f32_e32 v1, 1.0, v143
	v_mul_f32_e32 v143, 0x3d372713, v80
	v_rcp_f32_e32 v151, v1
	v_add_f32_e32 v1, 1.0, v145
	v_mul_f32_e32 v143, v80, v143
	v_mul_f32_e32 v145, 0x3d372713, v76
	v_fma_f32 v143, v80, v143, v80
	v_mul_f32_e32 v145, v76, v145
	v_mul_f32_e32 v143, 0x3f4c422a, v143
	v_fma_f32 v145, v76, v145, v76
	v_mul_f32_e32 v143, 0xc038aa3b, v143
	v_mul_f32_e32 v145, 0x3f4c422a, v145
	v_exp_f32_e32 v143, v143
	v_mul_f32_e32 v145, 0xc038aa3b, v145
	v_exp_f32_e32 v145, v145
	v_rcp_f32_e32 v153, v1
	v_add_f32_e32 v1, 1.0, v143
	v_mul_f32_e32 v143, 0x3d372713, v81
	v_rcp_f32_e32 v176, v1
	v_add_f32_e32 v1, 1.0, v145
	v_mul_f32_e32 v143, v81, v143
	v_mul_f32_e32 v145, 0x3d372713, v77
	v_fma_f32 v143, v81, v143, v81
	v_mul_f32_e32 v145, v77, v145
	v_mul_f32_e32 v143, 0x3f4c422a, v143
	v_fma_f32 v145, v77, v145, v77
	v_mul_f32_e32 v143, 0xc038aa3b, v143
	v_mul_f32_e32 v145, 0x3f4c422a, v145
	v_exp_f32_e32 v143, v143
	v_mul_f32_e32 v145, 0xc038aa3b, v145
	v_exp_f32_e32 v145, v145
	v_rcp_f32_e32 v178, v1
	v_add_f32_e32 v1, 1.0, v143
	v_rcp_f32_e32 v177, v1
	v_add_f32_e32 v1, 1.0, v145
	v_rcp_f32_e32 v179, v1
	v_pk_mul_f32 v[150:151], v[78:79], v[150:151]
	v_pk_mul_f32 v[152:153], v[74:75], v[152:153]
	v_pk_mul_f32 v[176:177], v[80:81], v[176:177]
	v_pk_mul_f32 v[178:179], v[76:77], v[178:179]
	v_mov_b32_e32 v1, v97
	v_cvt_pk_bf16_f32 v150, v150, v151
	v_cvt_pk_bf16_f32 v151, v176, v177
	v_cvt_pk_bf16_f32 v152, v152, v153
	v_cvt_pk_bf16_f32 v153, v178, v179
	v_lshl_add_u64 v[176:177], v[0:1], 1, v[174:175]
	s_mov_b64 s[14:15], 0
	global_store_dwordx4 v[176:177], v[150:153], off

; DI unsigned pk2(float lo, float hi) { f32x2 v = {lo, hi}; bf16x2_t b = __builtin_convertvector(v, bf16x2_t); return __builtin_bit_cast(unsigned, b); }
; DI float rstd_of(float ssq, float inv_n) { return 1.0f / sqrtf(ssq * inv_n + EPS); }
; DI float acc_get(const acc_t* p, float inv_scale) { return (float)(*p) * inv_scale; }
;     DI void operator()(const f32x4 (&acc)[2][2][4][2], const Unit& u, int wr, int wc, int fr, int fq) const {
;     ...
;         EPI_ROWS_BEGIN
;             const float rs = rstd_of(acc_get(ssq + row, 1.0f / SSQ_SCALE), 1.0f / DM);
; #pragma unroll
;             for (int bj = 0; bj < 2; ++bj) { const int col = colb + bj * HALF; f32x4 v0 = acc[ai][bj][m][0] * rs, v1 = acc[ai][bj][m][1] * rs;
;                 if (u.pn == 4 || u.pn == 5) { float* dst = (row < RP ? dvp + (size_t)row * 512 : dvs + (size_t)(row - RP) * 512) + (col - 1024); *(f32x4*)dst = v0; *(f32x4*)(dst + 4) = v1;
;                     if (u.pm < RP / BM) store_pair_transposed(VT + ((size_t)(row >> 11) * 512 + (col - 1024)) * SEQ, SEQ, ((row & (SEQ - 1)) & ~12) | ((row & 4) << 1) | ((row & 8) >> 1)  , fr, pk2(v0[0], v0[1]), pk2(v0[2], v0[3]), pk2(v1[0], v1[1]), pk2(v1[2], v1[3])); }
;                 else {
; #pragma unroll
;                     for (int j = 0; j < 4; ++j) { v0[j] = gelu_t(v0[j]); v1[j] = gelu_t(v1[j]); }
;                     u32x4 w; w.x = pk2(v0[0], v0[1]); w.y = pk2(v0[2], v0[3]); w.z = pk2(v1[0], v1[1]); w.w = pk2(v1[2], v1[3]);
;                     *(u32x4*)(Z + (size_t)row * INC + col) = w; } }
.LBB0_465:
	s_addk_i32 s45, 0x80
	v_or_b32_e32 v144, s45, v230
	v_ashrrev_i32_e32 v145, 31, v144
	v_lshl_add_u64 v[146:147], v[144:145], 3, s[46:47]
	v_mad_i64_i32 v[174:175], s[0:1], v144, s12, 0
	s_mov_b64 s[14:15], -1
	v_lshl_add_u64 v[174:175], s[10:11], 0, v[174:175]
	s_nop 1
	v_mov_b64_e32 v[74:75], v[190:191]
	v_ffbh_u32_e32 v1, v75
	v_min_u32_e32 v1, 32, v1
	v_lshlrev_b64 v[74:75], v1, v[74:75]
	v_min_u32_e32 v74, 1, v74
	v_or_b32_e32 v74, v75, v74
	v_cvt_f32_u32_e32 v74, v74
	v_sub_u32_e32 v1, 32, v1
	v_ldexp_f32 v1, v74, v1
	v_mul_f32_e32 v1, 0x35800000, v1
	v_fmamk_f32 v1, v1, 0x3a800000, v222
	v_rsq_f32_e32 v148, v1
	s_nop 0
	v_mul_f32_e32 v74, v1, v148
	v_fma_f32 v74, -v74, v148, 1.0
	v_mul_f32_e32 v74, 0.5, v74
	v_fmac_f32_e32 v148, v74, v148
	v_cmp_gt_i32_e64 s[2:3], s71, v144
	s_nop 0
	v_pk_mul_f32 v[80:81], v[72:73], v[148:149] op_sel_hi:[1,0]
	v_pk_mul_f32 v[78:79], v[70:71], v[148:149] op_sel_hi:[1,0]
	v_pk_mul_f32 v[76:77], v[68:69], v[148:149] op_sel_hi:[1,0]
	v_pk_mul_f32 v[74:75], v[66:67], v[148:149] op_sel_hi:[1,0]
	s_and_b64 vcc, exec, s[42:43]
	s_cbranch_vccnz .LBB0_467
	v_mul_f32_e32 v1, 0x3d372713, v78
	v_mul_f32_e32 v1, v78, v1
	v_mul_f32_e32 v143, 0x3d372713, v74
	v_fma_f32 v1, v78, v1, v78
	v_mul_f32_e32 v143, v74, v143
	v_mul_f32_e32 v1, 0x3f4c422a, v1
	v_fma_f32 v143, v74, v143, v74
	v_mul_f32_e32 v1, 0xc038aa3b, v1
	v_mul_f32_e32 v143, 0x3f4c422a, v143
	v_exp_f32_e32 v1, v1
	v_mul_f32_e32 v143, 0xc038aa3b, v143
	v_exp_f32_e32 v143, v143
	v_mul_f32_e32 v149, 0x3d372713, v75
	v_add_f32_e32 v1, 1.0, v1
	v_rcp_f32_e32 v150, v1
	v_add_f32_e32 v1, 1.0, v143
	v_mul_f32_e32 v143, 0x3d372713, v79
	v_mul_f32_e32 v143, v79, v143
	v_fma_f32 v143, v79, v143, v79
	v_mul_f32_e32 v149, v75, v149
	v_mul_f32_e32 v143, 0x3f4c422a, v143
	v_fma_f32 v149, v75, v149, v75
	v_mul_f32_e32 v143, 0xc038aa3b, v143
	v_mul_f32_e32 v149, 0x3f4c422a, v149
	v_exp_f32_e32 v143, v143
	v_mul_f32_e32 v149, 0xc038aa3b, v149
	v_exp_f32_e32 v149, v149
	v_rcp_f32_e32 v152, v1
	v_add_f32_e32 v1, 1.0, v143
	v_mul_f32_e32 v143, 0x3d372713, v80
	v_rcp_f32_e32 v151, v1
	v_add_f32_e32 v1, 1.0, v149
	v_mul_f32_e32 v143, v80, v143
	v_mul_f32_e32 v149, 0x3d372713, v76
	v_fma_f32 v143, v80, v143, v80
	v_mul_f32_e32 v149, v76, v149
	v_mul_f32_e32 v143, 0x3f4c422a, v143
	v_fma_f32 v149, v76, v149, v76
	v_mul_f32_e32 v143, 0xc038aa3b, v143
	v_mul_f32_e32 v149, 0x3f4c422a, v149
	v_exp_f32_e32 v143, v143
	v_mul_f32_e32 v149, 0xc038aa3b, v149
	v_exp_f32_e32 v149, v149
	v_rcp_f32_e32 v153, v1
	v_add_f32_e32 v1, 1.0, v143
	v_mul_f32_e32 v143, 0x3d372713, v81
	v_rcp_f32_e32 v176, v1
	v_add_f32_e32 v1, 1.0, v149
	v_mul_f32_e32 v143, v81, v143
	v_mul_f32_e32 v149, 0x3d372713, v77
	v_fma_f32 v143, v81, v143, v81
	v_mul_f32_e32 v149, v77, v149
	v_mul_f32_e32 v143, 0x3f4c422a, v143
	v_fma_f32 v149, v77, v149, v77
	v_mul_f32_e32 v143, 0xc038aa3b, v143
	v_mul_f32_e32 v149, 0x3f4c422a, v149
	v_exp_f32_e32 v143, v143
	v_mul_f32_e32 v149, 0xc038aa3b, v149
	v_exp_f32_e32 v149, v149
	v_rcp_f32_e32 v178, v1
	v_add_f32_e32 v1, 1.0, v143
	v_rcp_f32_e32 v177, v1
	v_add_f32_e32 v1, 1.0, v149
	v_rcp_f32_e32 v179, v1
	v_pk_mul_f32 v[150:151], v[78:79], v[150:151]
	v_pk_mul_f32 v[152:153], v[74:75], v[152:153]
	v_pk_mul_f32 v[176:177], v[80:81], v[176:177]
	v_pk_mul_f32 v[178:179], v[76:77], v[178:179]
	v_mov_b32_e32 v1, v97
	v_cvt_pk_bf16_f32 v150, v150, v151
	v_cvt_pk_bf16_f32 v151, v176, v177
	v_cvt_pk_bf16_f32 v152, v152, v153
	v_cvt_pk_bf16_f32 v153, v178, v179
	v_lshl_add_u64 v[176:177], v[0:1], 1, v[174:175]
	s_mov_b64 s[14:15], 0
	global_store_dwordx4 v[176:177], v[150:153], off

; DI unsigned pk2(float lo, float hi) { f32x2 v = {lo, hi}; bf16x2_t b = __builtin_convertvector(v, bf16x2_t); return __builtin_bit_cast(unsigned, b); }
; DI float rstd_of(float ssq, float inv_n) { return 1.0f / sqrtf(ssq * inv_n + EPS); }
; DI float acc_get(const acc_t* p, float inv_scale) { return (float)(*p) * inv_scale; }
;     DI void operator()(const f32x4 (&acc)[2][2][4][2], const Unit& u, int wr, int wc, int fr, int fq) const {
;     ...
;         EPI_ROWS_BEGIN
;             const float rs = rstd_of(acc_get(ssq + row, 1.0f / SSQ_SCALE), 1.0f / DM);
; #pragma unroll
;             for (int bj = 0; bj < 2; ++bj) { const int col = colb + bj * HALF; f32x4 v0 = acc[ai][bj][m][0] * rs, v1 = acc[ai][bj][m][1] * rs;
;                 if (u.pn == 4 || u.pn == 5) { float* dst = (row < RP ? dvp + (size_t)row * 512 : dvs + (size_t)(row - RP) * 512) + (col - 1024); *(f32x4*)dst = v0; *(f32x4*)(dst + 4) = v1;
;                     if (u.pm < RP / BM) store_pair_transposed(VT + ((size_t)(row >> 11) * 512 + (col - 1024)) * SEQ, SEQ, ((row & (SEQ - 1)) & ~12) | ((row & 4) << 1) | ((row & 8) >> 1)  , fr, pk2(v0[0], v0[1]), pk2(v0[2], v0[3]), pk2(v1[0], v1[1]), pk2(v1[2], v1[3])); }
;                 else {
; #pragma unroll
;                     for (int j = 0; j < 4; ++j) { v0[j] = gelu_t(v0[j]); v1[j] = gelu_t(v1[j]); }
;                     u32x4 w; w.x = pk2(v0[0], v0[1]); w.y = pk2(v0[2], v0[3]); w.z = pk2(v1[0], v1[1]); w.w = pk2(v1[2], v1[3]);
;                     *(u32x4*)(Z + (size_t)row * INC + col) = w; } }
.LBB0_475:
	v_or_b32_e32 v174, 16, v144
	s_mov_b64 s[14:15], -1
	s_nop 1
	v_mov_b64_e32 v[74:75], v[192:193]
	v_ffbh_u32_e32 v1, v75
	v_min_u32_e32 v1, 32, v1
	v_lshlrev_b64 v[74:75], v1, v[74:75]
	v_min_u32_e32 v74, 1, v74
	v_or_b32_e32 v74, v75, v74
	v_cvt_f32_u32_e32 v74, v74
	v_sub_u32_e32 v1, 32, v1
	v_ldexp_f32 v1, v74, v1
	v_mul_f32_e32 v1, 0x35800000, v1
	v_fmamk_f32 v1, v1, 0x3a800000, v222
	v_rsq_f32_e32 v148, v1
	s_nop 0
	v_mul_f32_e32 v74, v1, v148
	v_fma_f32 v74, -v74, v148, 1.0
	v_mul_f32_e32 v74, 0.5, v74
	v_fmac_f32_e32 v148, v74, v148
	v_mad_i64_i32 v[176:177], s[2:3], v174, s12, 0
	s_nop 0
	v_cmp_gt_i32_e64 s[2:3], s71, v174
	v_lshl_add_u64 v[176:177], s[10:11], 0, v[176:177]
	v_pk_mul_f32 v[80:81], v[56:57], v[148:149] op_sel_hi:[1,0]
	v_pk_mul_f32 v[78:79], v[54:55], v[148:149] op_sel_hi:[1,0]
	v_pk_mul_f32 v[76:77], v[52:53], v[148:149] op_sel_hi:[1,0]
	v_pk_mul_f32 v[74:75], v[50:51], v[148:149] op_sel_hi:[1,0]
	s_and_b64 vcc, exec, s[42:43]
	s_cbranch_vccnz .LBB0_477
	v_mul_f32_e32 v1, 0x3d372713, v78
	v_mul_f32_e32 v1, v78, v1
	v_mul_f32_e32 v143, 0x3d372713, v74
	v_fma_f32 v1, v78, v1, v78
	v_mul_f32_e32 v143, v74, v143
	v_mul_f32_e32 v1, 0x3f4c422a, v1
	v_fma_f32 v143, v74, v143, v74
	v_mul_f32_e32 v1, 0xc038aa3b, v1
	v_mul_f32_e32 v143, 0x3f4c422a, v143
	v_exp_f32_e32 v1, v1
	v_mul_f32_e32 v143, 0xc038aa3b, v143
	v_exp_f32_e32 v143, v143
	v_mul_f32_e32 v145, 0x3d372713, v75
	v_add_f32_e32 v1, 1.0, v1
	v_rcp_f32_e32 v150, v1
	v_add_f32_e32 v1, 1.0, v143
	v_mul_f32_e32 v143, 0x3d372713, v79
	v_mul_f32_e32 v143, v79, v143
	v_fma_f32 v143, v79, v143, v79
	v_mul_f32_e32 v145, v75, v145
	v_mul_f32_e32 v143, 0x3f4c422a, v143
	v_fma_f32 v145, v75, v145, v75
	v_mul_f32_e32 v143, 0xc038aa3b, v143
	v_mul_f32_e32 v145, 0x3f4c422a, v145
	v_exp_f32_e32 v143, v143
	v_mul_f32_e32 v145, 0xc038aa3b, v145
	v_exp_f32_e32 v145, v145
	v_rcp_f32_e32 v152, v1
	v_add_f32_e32 v1, 1.0, v143
	v_mul_f32_e32 v143, 0x3d372713, v80
	v_rcp_f32_e32 v151, v1
	v_add_f32_e32 v1, 1.0, v145
	v_mul_f32_e32 v143, v80, v143
	v_mul_f32_e32 v145, 0x3d372713, v76
	v_fma_f32 v143, v80, v143, v80
	v_mul_f32_e32 v145, v76, v145
	v_mul_f32_e32 v143, 0x3f4c422a, v143
	v_fma_f32 v145, v76, v145, v76
	v_mul_f32_e32 v143, 0xc038aa3b, v143
	v_mul_f32_e32 v145, 0x3f4c422a, v145
	v_exp_f32_e32 v143, v143
	v_mul_f32_e32 v145, 0xc038aa3b, v145
	v_exp_f32_e32 v145, v145
	v_rcp_f32_e32 v153, v1
	v_add_f32_e32 v1, 1.0, v143
	v_mul_f32_e32 v143, 0x3d372713, v81
	v_rcp_f32_e32 v178, v1
	v_add_f32_e32 v1, 1.0, v145
	v_mul_f32_e32 v143, v81, v143
	v_mul_f32_e32 v145, 0x3d372713, v77
	v_fma_f32 v143, v81, v143, v81
	v_mul_f32_e32 v145, v77, v145
	v_mul_f32_e32 v143, 0x3f4c422a, v143
	v_fma_f32 v145, v77, v145, v77
	v_mul_f32_e32 v143, 0xc038aa3b, v143
	v_mul_f32_e32 v145, 0x3f4c422a, v145
	v_exp_f32_e32 v143, v143
	v_mul_f32_e32 v145, 0xc038aa3b, v145
	v_exp_f32_e32 v145, v145
	v_rcp_f32_e32 v180, v1
	v_add_f32_e32 v1, 1.0, v143
	v_rcp_f32_e32 v179, v1
	v_add_f32_e32 v1, 1.0, v145
	v_rcp_f32_e32 v181, v1
	v_pk_mul_f32 v[150:151], v[78:79], v[150:151]
	v_pk_mul_f32 v[152:153], v[74:75], v[152:153]
	v_pk_mul_f32 v[178:179], v[80:81], v[178:179]
	v_pk_mul_f32 v[180:181], v[76:77], v[180:181]
	v_mov_b32_e32 v1, v97
	v_cvt_pk_bf16_f32 v150, v150, v151
	v_cvt_pk_bf16_f32 v151, v178, v179
	v_cvt_pk_bf16_f32 v152, v152, v153
	v_cvt_pk_bf16_f32 v153, v180, v181
	v_lshl_add_u64 v[178:179], v[0:1], 1, v[176:177]
	s_mov_b64 s[14:15], 0
	global_store_dwordx4 v[178:179], v[150:153], off

; DI unsigned pk2(float lo, float hi) { f32x2 v = {lo, hi}; bf16x2_t b = __builtin_convertvector(v, bf16x2_t); return __builtin_bit_cast(unsigned, b); }
; DI float rstd_of(float ssq, float inv_n) { return 1.0f / sqrtf(ssq * inv_n + EPS); }
; DI float acc_get(const acc_t* p, float inv_scale) { return (float)(*p) * inv_scale; }
;     DI void operator()(const f32x4 (&acc)[2][2][4][2], const Unit& u, int wr, int wc, int fr, int fq) const {
;     ...
;         EPI_ROWS_BEGIN
;             const float rs = rstd_of(acc_get(ssq + row, 1.0f / SSQ_SCALE), 1.0f / DM);
; #pragma unroll
;             for (int bj = 0; bj < 2; ++bj) { const int col = colb + bj * HALF; f32x4 v0 = acc[ai][bj][m][0] * rs, v1 = acc[ai][bj][m][1] * rs;
;                 if (u.pn == 4 || u.pn == 5) { float* dst = (row < RP ? dvp + (size_t)row * 512 : dvs + (size_t)(row - RP) * 512) + (col - 1024); *(f32x4*)dst = v0; *(f32x4*)(dst + 4) = v1;
;                     if (u.pm < RP / BM) store_pair_transposed(VT + ((size_t)(row >> 11) * 512 + (col - 1024)) * SEQ, SEQ, ((row & (SEQ - 1)) & ~12) | ((row & 4) << 1) | ((row & 8) >> 1)  , fr, pk2(v0[0], v0[1]), pk2(v0[2], v0[3]), pk2(v1[0], v1[1]), pk2(v1[2], v1[3])); }
;                 else {
; #pragma unroll
;                     for (int j = 0; j < 4; ++j) { v0[j] = gelu_t(v0[j]); v1[j] = gelu_t(v1[j]); }
;                     u32x4 w; w.x = pk2(v0[0], v0[1]); w.y = pk2(v0[2], v0[3]); w.z = pk2(v1[0], v1[1]); w.w = pk2(v1[2], v1[3]);
;                     *(u32x4*)(Z + (size_t)row * INC + col) = w; } }
.LBB0_485:
	v_or_b32_e32 v174, 32, v144
	s_mov_b64 s[14:15], -1
	s_nop 1
	v_mov_b64_e32 v[74:75], v[194:195]
	v_ffbh_u32_e32 v1, v75
	v_min_u32_e32 v1, 32, v1
	v_lshlrev_b64 v[74:75], v1, v[74:75]
	v_min_u32_e32 v74, 1, v74
	v_or_b32_e32 v74, v75, v74
	v_cvt_f32_u32_e32 v74, v74
	v_sub_u32_e32 v1, 32, v1
	v_ldexp_f32 v1, v74, v1
	v_mul_f32_e32 v1, 0x35800000, v1
	v_fmamk_f32 v1, v1, 0x3a800000, v222
	v_rsq_f32_e32 v148, v1
	s_nop 0
	v_mul_f32_e32 v74, v1, v148
	v_fma_f32 v74, -v74, v148, 1.0
	v_mul_f32_e32 v74, 0.5, v74
	v_fmac_f32_e32 v148, v74, v148
	v_mad_i64_i32 v[176:177], s[2:3], v174, s12, 0
	s_nop 0
	v_cmp_gt_i32_e64 s[2:3], s71, v174
	v_lshl_add_u64 v[176:177], s[10:11], 0, v[176:177]
	v_pk_mul_f32 v[80:81], v[40:41], v[148:149] op_sel_hi:[1,0]
	v_pk_mul_f32 v[78:79], v[38:39], v[148:149] op_sel_hi:[1,0]
	v_pk_mul_f32 v[76:77], v[36:37], v[148:149] op_sel_hi:[1,0]
	v_pk_mul_f32 v[74:75], v[34:35], v[148:149] op_sel_hi:[1,0]
	s_and_b64 vcc, exec, s[42:43]
	s_cbranch_vccnz .LBB0_487
	v_mul_f32_e32 v1, 0x3d372713, v78
	v_mul_f32_e32 v1, v78, v1
	v_mul_f32_e32 v143, 0x3d372713, v74
	v_fma_f32 v1, v78, v1, v78
	v_mul_f32_e32 v143, v74, v143
	v_mul_f32_e32 v1, 0x3f4c422a, v1
	v_fma_f32 v143, v74, v143, v74
	v_mul_f32_e32 v1, 0xc038aa3b, v1
	v_mul_f32_e32 v143, 0x3f4c422a, v143
	v_exp_f32_e32 v1, v1
	v_mul_f32_e32 v143, 0xc038aa3b, v143
	v_exp_f32_e32 v143, v143
	v_mul_f32_e32 v145, 0x3d372713, v75
	v_add_f32_e32 v1, 1.0, v1
	v_rcp_f32_e32 v150, v1
	v_add_f32_e32 v1, 1.0, v143
	v_mul_f32_e32 v143, 0x3d372713, v79
	v_mul_f32_e32 v143, v79, v143
	v_fma_f32 v143, v79, v143, v79
	v_mul_f32_e32 v145, v75, v145
	v_mul_f32_e32 v143, 0x3f4c422a, v143
	v_fma_f32 v145, v75, v145, v75
	v_mul_f32_e32 v143, 0xc038aa3b, v143
	v_mul_f32_e32 v145, 0x3f4c422a, v145
	v_exp_f32_e32 v143, v143
	v_mul_f32_e32 v145, 0xc038aa3b, v145
	v_exp_f32_e32 v145, v145
	v_rcp_f32_e32 v152, v1
	v_add_f32_e32 v1, 1.0, v143
	v_mul_f32_e32 v143, 0x3d372713, v80
	v_rcp_f32_e32 v151, v1
	v_add_f32_e32 v1, 1.0, v145
	v_mul_f32_e32 v143, v80, v143
	v_mul_f32_e32 v145, 0x3d372713, v76
	v_fma_f32 v143, v80, v143, v80
	v_mul_f32_e32 v145, v76, v145
	v_mul_f32_e32 v143, 0x3f4c422a, v143
	v_fma_f32 v145, v76, v145, v76
	v_mul_f32_e32 v143, 0xc038aa3b, v143
	v_mul_f32_e32 v145, 0x3f4c422a, v145
	v_exp_f32_e32 v143, v143
	v_mul_f32_e32 v145, 0xc038aa3b, v145
	v_exp_f32_e32 v145, v145
	v_rcp_f32_e32 v153, v1
	v_add_f32_e32 v1, 1.0, v143
	v_mul_f32_e32 v143, 0x3d372713, v81
	v_rcp_f32_e32 v178, v1
	v_add_f32_e32 v1, 1.0, v145
	v_mul_f32_e32 v143, v81, v143
	v_mul_f32_e32 v145, 0x3d372713, v77
	v_fma_f32 v143, v81, v143, v81
	v_mul_f32_e32 v145, v77, v145
	v_mul_f32_e32 v143, 0x3f4c422a, v143
	v_fma_f32 v145, v77, v145, v77
	v_mul_f32_e32 v143, 0xc038aa3b, v143
	v_mul_f32_e32 v145, 0x3f4c422a, v145
	v_exp_f32_e32 v143, v143
	v_mul_f32_e32 v145, 0xc038aa3b, v145
	v_exp_f32_e32 v145, v145
	v_rcp_f32_e32 v180, v1
	v_add_f32_e32 v1, 1.0, v143
	v_rcp_f32_e32 v179, v1
	v_add_f32_e32 v1, 1.0, v145
	v_rcp_f32_e32 v181, v1
	v_pk_mul_f32 v[150:151], v[78:79], v[150:151]
	v_pk_mul_f32 v[152:153], v[74:75], v[152:153]
	v_pk_mul_f32 v[178:179], v[80:81], v[178:179]
	v_pk_mul_f32 v[180:181], v[76:77], v[180:181]
	v_mov_b32_e32 v1, v97
	v_cvt_pk_bf16_f32 v150, v150, v151
	v_cvt_pk_bf16_f32 v151, v178, v179
	v_cvt_pk_bf16_f32 v152, v152, v153
	v_cvt_pk_bf16_f32 v153, v180, v181
	v_lshl_add_u64 v[178:179], v[0:1], 1, v[176:177]
	s_mov_b64 s[14:15], 0
	global_store_dwordx4 v[178:179], v[150:153], off

; DI unsigned pk2(float lo, float hi) { f32x2 v = {lo, hi}; bf16x2_t b = __builtin_convertvector(v, bf16x2_t); return __builtin_bit_cast(unsigned, b); }
; DI float rstd_of(float ssq, float inv_n) { return 1.0f / sqrtf(ssq * inv_n + EPS); }
; DI float acc_get(const acc_t* p, float inv_scale) { return (float)(*p) * inv_scale; }
;     DI void operator()(const f32x4 (&acc)[2][2][4][2], const Unit& u, int wr, int wc, int fr, int fq) const {
;     ...
;         EPI_ROWS_BEGIN
;             const float rs = rstd_of(acc_get(ssq + row, 1.0f / SSQ_SCALE), 1.0f / DM);
; #pragma unroll
;             for (int bj = 0; bj < 2; ++bj) { const int col = colb + bj * HALF; f32x4 v0 = acc[ai][bj][m][0] * rs, v1 = acc[ai][bj][m][1] * rs;
;                 if (u.pn == 4 || u.pn == 5) { float* dst = (row < RP ? dvp + (size_t)row * 512 : dvs + (size_t)(row - RP) * 512) + (col - 1024); *(f32x4*)dst = v0; *(f32x4*)(dst + 4) = v1;
;                     if (u.pm < RP / BM) store_pair_transposed(VT + ((size_t)(row >> 11) * 512 + (col - 1024)) * SEQ, SEQ, ((row & (SEQ - 1)) & ~12) | ((row & 4) << 1) | ((row & 8) >> 1)  , fr, pk2(v0[0], v0[1]), pk2(v0[2], v0[3]), pk2(v1[0], v1[1]), pk2(v1[2], v1[3])); }
;                 else {
; #pragma unroll
;                     for (int j = 0; j < 4; ++j) { v0[j] = gelu_t(v0[j]); v1[j] = gelu_t(v1[j]); }
;                     u32x4 w; w.x = pk2(v0[0], v0[1]); w.y = pk2(v0[2], v0[3]); w.z = pk2(v1[0], v1[1]); w.w = pk2(v1[2], v1[3]);
;                     *(u32x4*)(Z + (size_t)row * INC + col) = w; } }
.LBB0_495:
	v_or_b32_e32 v148, 48, v144
	s_mov_b64 s[14:15], -1
	s_nop 1
	v_mov_b64_e32 v[74:75], v[196:197]
	v_ffbh_u32_e32 v1, v75
	v_min_u32_e32 v1, 32, v1
	v_lshlrev_b64 v[74:75], v1, v[74:75]
	v_min_u32_e32 v74, 1, v74
	v_or_b32_e32 v74, v75, v74
	v_cvt_f32_u32_e32 v74, v74
	v_sub_u32_e32 v1, 32, v1
	v_ldexp_f32 v1, v74, v1
	v_mul_f32_e32 v1, 0x35800000, v1
	v_fmamk_f32 v1, v1, 0x3a800000, v222
	v_rsq_f32_e32 v146, v1
	s_nop 0
	v_mul_f32_e32 v74, v1, v146
	v_fma_f32 v74, -v74, v146, 1.0
	v_mul_f32_e32 v74, 0.5, v74
	v_fmac_f32_e32 v146, v74, v146
	v_mad_i64_i32 v[174:175], s[2:3], v148, s12, 0
	s_nop 0
	v_cmp_gt_i32_e64 s[2:3], s71, v148
	v_lshl_add_u64 v[174:175], s[10:11], 0, v[174:175]
	v_pk_mul_f32 v[80:81], v[24:25], v[146:147] op_sel_hi:[1,0]
	v_pk_mul_f32 v[78:79], v[22:23], v[146:147] op_sel_hi:[1,0]
	v_pk_mul_f32 v[76:77], v[20:21], v[146:147] op_sel_hi:[1,0]
	v_pk_mul_f32 v[74:75], v[18:19], v[146:147] op_sel_hi:[1,0]
	s_and_b64 vcc, exec, s[42:43]
	s_cbranch_vccnz .LBB0_497
	v_mul_f32_e32 v1, 0x3d372713, v78
	v_mul_f32_e32 v1, v78, v1
	v_mul_f32_e32 v143, 0x3d372713, v74
	v_fma_f32 v1, v78, v1, v78
	v_mul_f32_e32 v143, v74, v143
	v_mul_f32_e32 v1, 0x3f4c422a, v1
	v_fma_f32 v143, v74, v143, v74
	v_mul_f32_e32 v1, 0xc038aa3b, v1
	v_mul_f32_e32 v143, 0x3f4c422a, v143
	v_exp_f32_e32 v1, v1
	v_mul_f32_e32 v143, 0xc038aa3b, v143
	v_exp_f32_e32 v143, v143
	v_mul_f32_e32 v145, 0x3d372713, v75
	v_add_f32_e32 v1, 1.0, v1
	v_rcp_f32_e32 v150, v1
	v_add_f32_e32 v1, 1.0, v143
	v_mul_f32_e32 v143, 0x3d372713, v79
	v_mul_f32_e32 v143, v79, v143
	v_fma_f32 v143, v79, v143, v79
	v_mul_f32_e32 v145, v75, v145
	v_mul_f32_e32 v143, 0x3f4c422a, v143
	v_fma_f32 v145, v75, v145, v75
	v_mul_f32_e32 v143, 0xc038aa3b, v143
	v_mul_f32_e32 v145, 0x3f4c422a, v145
	v_exp_f32_e32 v143, v143
	v_mul_f32_e32 v145, 0xc038aa3b, v145
	v_exp_f32_e32 v145, v145
	v_rcp_f32_e32 v152, v1
	v_add_f32_e32 v1, 1.0, v143
	v_mul_f32_e32 v143, 0x3d372713, v80
	v_rcp_f32_e32 v151, v1
	v_add_f32_e32 v1, 1.0, v145
	v_mul_f32_e32 v143, v80, v143
	v_mul_f32_e32 v145, 0x3d372713, v76
	v_fma_f32 v143, v80, v143, v80
	v_mul_f32_e32 v145, v76, v145
	v_mul_f32_e32 v143, 0x3f4c422a, v143
	v_fma_f32 v145, v76, v145, v76
	v_mul_f32_e32 v143, 0xc038aa3b, v143
	v_mul_f32_e32 v145, 0x3f4c422a, v145
	v_exp_f32_e32 v143, v143
	v_mul_f32_e32 v145, 0xc038aa3b, v145
	v_exp_f32_e32 v145, v145
	v_rcp_f32_e32 v153, v1
	v_add_f32_e32 v1, 1.0, v143
	v_mul_f32_e32 v143, 0x3d372713, v81
	v_rcp_f32_e32 v176, v1
	v_add_f32_e32 v1, 1.0, v145
	v_mul_f32_e32 v143, v81, v143
	v_mul_f32_e32 v145, 0x3d372713, v77
	v_fma_f32 v143, v81, v143, v81
	v_mul_f32_e32 v145, v77, v145
	v_mul_f32_e32 v143, 0x3f4c422a, v143
	v_fma_f32 v145, v77, v145, v77
	v_mul_f32_e32 v143, 0xc038aa3b, v143
	v_mul_f32_e32 v145, 0x3f4c422a, v145
	v_exp_f32_e32 v143, v143
	v_mul_f32_e32 v145, 0xc038aa3b, v145
	v_exp_f32_e32 v145, v145
	v_rcp_f32_e32 v178, v1
	v_add_f32_e32 v1, 1.0, v143
	v_rcp_f32_e32 v177, v1
	v_add_f32_e32 v1, 1.0, v145
	v_rcp_f32_e32 v179, v1
	v_pk_mul_f32 v[150:151], v[78:79], v[150:151]
	v_pk_mul_f32 v[152:153], v[74:75], v[152:153]
	v_pk_mul_f32 v[176:177], v[80:81], v[176:177]
	v_pk_mul_f32 v[178:179], v[76:77], v[178:179]
	v_mov_b32_e32 v1, v97
	v_cvt_pk_bf16_f32 v150, v150, v151
	v_cvt_pk_bf16_f32 v151, v176, v177
	v_cvt_pk_bf16_f32 v152, v152, v153
	v_cvt_pk_bf16_f32 v153, v178, v179
	v_lshl_add_u64 v[176:177], v[0:1], 1, v[174:175]
	s_mov_b64 s[14:15], 0
	global_store_dwordx4 v[176:177], v[150:153], off

; DI float rstd_of(float ssq, float inv_n) { return 1.0f / sqrtf(ssq * inv_n + EPS); }
; DI float acc_get_i(const acc_t* base, unsigned idx, float inv_scale) { return (float)(*(const acc_t*)((const char*)base + idx * 8u)) * inv_scale; }
;     DI void operator()(const f32x4 (&acc)[2][2][4][2], const Unit& u, int wr, int wc, int fr, int fq) const {
;     ...
;             const int wv = wr_ * 4 + wc_;
;             _Pragma("unroll") for (int ai = 0; ai < 2; ++ai) _Pragma("unroll") for (int m = 0; m < 4; ++m) { const int row = u.pm * BM + ai * HALF + wr_ * 64 + m * 16 + fr_;
;                 const float rs = rstd_of(acc_get_i(ssq, (unsigned)row, 1.0f / SSQ_SCALE), 1.0f / DM);
; #pragma unroll
;                 for (int bj = 0; bj < 2; ++bj) { const f32x4 v0 = acc[ai][bj][m][0] * rs, v1 = acc[ai][bj][m][1] * rs;
;                     float ss = (v0[0] * v0[0] + v0[1] * v0[1]) + (v0[2] * v0[2] + v0[3] * v0[3]) + (v1[0] * v1[0] + v1[1] * v1[1]) + (v1[2] * v1[2] + v1[3] * v1[3]);
;                     ss += __shfl_xor(ss, 16); ss += __shfl_xor(ss, 32);
;                     if (fq_ == 0) xl[(wv * 2 + bj) * 128 + ai * 64 + m * 16 + fr_] = ss; }
.LBB0_506:
	v_mov_b32_e32 v245, v240
	s_mov_b32 s0, s80
	v_mov_b32_e32 v175, v230
	s_mov_b32 s42, s86
	s_lshl_b32 s1, s78, 8
	s_lshl_b32 s2, s0, 6
	s_add_i32 s2, s2, s1
	v_add_u32_e32 v174, s2, v175
	v_lshlrev_b32_e32 v96, 3, v174
	global_load_dwordx2 v[144:145], v96, s[46:47]
	global_load_dwordx2 v[146:147], v96, s[46:47] offset:128
	global_load_dwordx2 v[148:149], v96, s[46:47] offset:256
	global_load_dwordx2 v[194:195], v96, s[46:47] offset:384
	global_load_dwordx2 v[198:199], v96, s[46:47] offset:1024
	global_load_dwordx2 v[202:203], v96, s[46:47] offset:1152
	global_load_dwordx2 v[204:205], v96, s[46:47] offset:1280
	global_load_dwordx2 v[206:207], v96, s[46:47] offset:1408
	v_and_b32_e32 v75, 64, v225
	v_xor_b32_e32 v74, 16, v225
	s_lshl_b32 s0, s0, 2
	s_add_i32 s14, s0, s42
	v_xor_b32_e32 v142, 32, v225
	s_lshl_b32 s24, s14, 10
	s_waitcnt vmcnt(0)
	v_mov_b64_e32 v[0:1], v[144:145]
	v_ffbh_u32_e32 v76, v1
	v_min_u32_e32 v76, 32, v76
	v_lshlrev_b64 v[0:1], v76, v[0:1]
	v_min_u32_e32 v0, 1, v0
	v_or_b32_e32 v0, v1, v0
	v_cvt_f32_u32_e32 v0, v0
	v_add_u32_e32 v1, 64, v75
	v_sub_u32_e32 v75, 32, v76
	v_cmp_lt_i32_e64 s[2:3], v74, v1
	v_ldexp_f32 v0, v0, v75
	v_mul_f32_e32 v0, 0x35800000, v0
	v_fmamk_f32 v0, v0, 0x3a800000, v222
	v_rsq_f32_e32 v76, v0
	s_nop 0
	v_mul_f32_e32 v75, v0, v76
	v_fma_f32 v75, -v75, v76, 1.0
	v_mul_f32_e32 v75, 0.5, v75
	v_fma_f32 v0, v75, v76, v76
	v_cndmask_b32_e64 v74, v225, v74, s[2:3]
	v_lshlrev_b32_e32 v246, 2, v74
	v_cmp_eq_u32_e64 s[2:3], 0, v245
	s_nop 0
	s_add_i32 s0, s24, 0
	v_pk_mul_f32 v[74:75], v[4:5], v[0:1] op_sel_hi:[1,0]
	v_pk_mul_f32 v[76:77], v[2:3], v[0:1] op_sel_hi:[1,0]
	v_pk_mul_f32 v[80:81], v[6:7], v[0:1] op_sel_hi:[1,0]
	v_mul_f32_e32 v77, v77, v77
	v_mul_f32_e32 v75, v75, v75
	v_pk_mul_f32 v[78:79], v[8:9], v[0:1] op_sel_hi:[1,0]
	v_mul_f32_e32 v81, v81, v81
	v_fmac_f32_e32 v77, v76, v76
	v_fmac_f32_e32 v75, v74, v74
	v_mul_f32_e32 v79, v79, v79
	v_fmac_f32_e32 v81, v80, v80
	v_add_f32_e32 v74, v77, v75
	v_add_f32_e32 v74, v81, v74
	v_fmac_f32_e32 v79, v78, v78
	v_add_f32_e32 v74, v79, v74
	ds_bpermute_b32 v76, v246, v74
	v_cmp_lt_i32_e32 vcc, v142, v1
	s_add_i32 s0, s0, 0x20400
	s_nop 0
	v_cndmask_b32_e32 v1, v225, v142, vcc
	v_lshlrev_b32_e32 v75, 2, v1
	s_waitcnt lgkmcnt(0)
	v_add_f32_e32 v1, v74, v76
	ds_bpermute_b32 v76, v75, v1
	v_lshl_add_u32 v74, v175, 2, s0
	s_and_saveexec_b64 s[0:1], s[2:3]
	s_cbranch_execz .LBB0_508
	s_waitcnt lgkmcnt(0)
	v_add_f32_e32 v1, v1, v76
	ds_write_b32 v74, v1

; DI float rstd_of(float ssq, float inv_n) { return 1.0f / sqrtf(ssq * inv_n + EPS); }
; DI float acc_get_i(const acc_t* base, unsigned idx, float inv_scale) { return (float)(*(const acc_t*)((const char*)base + idx * 8u)) * inv_scale; }
;     DI void operator()(const f32x4 (&acc)[2][2][4][2], const Unit& u, int wr, int wc, int fr, int fq) const {
;     ...
;             _Pragma("unroll") for (int ai = 0; ai < 2; ++ai) _Pragma("unroll") for (int m = 0; m < 4; ++m) { const int row = u.pm * BM + ai * HALF + wr_ * 64 + m * 16 + fr_;
;                 const float rs = rstd_of(acc_get_i(ssq, (unsigned)row, 1.0f / SSQ_SCALE), 1.0f / DM);
; #pragma unroll
;                 for (int bj = 0; bj < 2; ++bj) { const f32x4 v0 = acc[ai][bj][m][0] * rs, v1 = acc[ai][bj][m][1] * rs;
;                     float ss = (v0[0] * v0[0] + v0[1] * v0[1]) + (v0[2] * v0[2] + v0[3] * v0[3]) + (v1[0] * v1[0] + v1[1] * v1[1]) + (v1[2] * v1[2] + v1[3] * v1[3]);
;                     ss += __shfl_xor(ss, 16); ss += __shfl_xor(ss, 32);
;                     if (fq_ == 0) xl[(wv * 2 + bj) * 128 + ai * 64 + m * 16 + fr_] = ss; }
.LBB0_510:
	s_or_b64 exec, exec, s[0:1]
	v_add_u32_e32 v200, 16, v174
	v_lshlrev_b32_e32 v178, 3, v200
	s_waitcnt lgkmcnt(0)
	s_nop 1
	v_mov_b64_e32 v[0:1], v[146:147]
	v_ffbh_u32_e32 v76, v1
	v_min_u32_e32 v76, 32, v76
	v_lshlrev_b64 v[0:1], v76, v[0:1]
	v_min_u32_e32 v0, 1, v0
	v_or_b32_e32 v0, v1, v0
	v_cvt_f32_u32_e32 v0, v0
	v_sub_u32_e32 v1, 32, v76
	v_ldexp_f32 v0, v0, v1
	v_mul_f32_e32 v0, 0x35800000, v0
	v_fmamk_f32 v0, v0, 0x3a800000, v222
	v_rsq_f32_e32 v76, v0
	s_nop 0
	v_mul_f32_e32 v1, v0, v76
	v_fma_f32 v1, -v1, v76, 1.0
	v_mul_f32_e32 v1, 0.5, v1
	v_fma_f32 v0, v1, v76, v76
	v_pk_mul_f32 v[76:77], v[132:133], v[0:1] op_sel_hi:[1,0]
	v_pk_mul_f32 v[78:79], v[130:131], v[0:1] op_sel_hi:[1,0]
	v_pk_mul_f32 v[80:81], v[128:129], v[0:1] op_sel_hi:[1,0]
	v_pk_mul_f32 v[142:143], v[126:127], v[0:1] op_sel_hi:[1,0]
	v_mul_f32_e32 v1, v79, v79
	v_mul_f32_e32 v77, v77, v77
	v_mul_f32_e32 v79, v143, v143
	v_fmac_f32_e32 v1, v78, v78
	v_fmac_f32_e32 v77, v76, v76
	v_mul_f32_e32 v81, v81, v81
	v_fmac_f32_e32 v79, v142, v142
	v_add_f32_e32 v1, v1, v77
	v_add_f32_e32 v1, v79, v1
	v_fmac_f32_e32 v81, v80, v80
	v_add_f32_e32 v1, v81, v1
	ds_bpermute_b32 v76, v246, v1
	s_waitcnt lgkmcnt(0)
	v_add_f32_e32 v1, v1, v76
	ds_bpermute_b32 v76, v75, v1
	s_and_saveexec_b64 s[0:1], s[2:3]
	s_cbranch_execz .LBB0_512
	s_waitcnt lgkmcnt(0)
	v_add_f32_e32 v1, v1, v76
	ds_write_b32 v74, v1 offset:64

; DI float rstd_of(float ssq, float inv_n) { return 1.0f / sqrtf(ssq * inv_n + EPS); }
; DI float acc_get_i(const acc_t* base, unsigned idx, float inv_scale) { return (float)(*(const acc_t*)((const char*)base + idx * 8u)) * inv_scale; }
;     DI void operator()(const f32x4 (&acc)[2][2][4][2], const Unit& u, int wr, int wc, int fr, int fq) const {
;     ...
;             _Pragma("unroll") for (int ai = 0; ai < 2; ++ai) _Pragma("unroll") for (int m = 0; m < 4; ++m) { const int row = u.pm * BM + ai * HALF + wr_ * 64 + m * 16 + fr_;
;                 const float rs = rstd_of(acc_get_i(ssq, (unsigned)row, 1.0f / SSQ_SCALE), 1.0f / DM);
; #pragma unroll
;                 for (int bj = 0; bj < 2; ++bj) { const f32x4 v0 = acc[ai][bj][m][0] * rs, v1 = acc[ai][bj][m][1] * rs;
;                     float ss = (v0[0] * v0[0] + v0[1] * v0[1]) + (v0[2] * v0[2] + v0[3] * v0[3]) + (v1[0] * v1[0] + v1[1] * v1[1]) + (v1[2] * v1[2] + v1[3] * v1[3]);
;                     ss += __shfl_xor(ss, 16); ss += __shfl_xor(ss, 32);
;                     if (fq_ == 0) xl[(wv * 2 + bj) * 128 + ai * 64 + m * 16 + fr_] = ss; }
.LBB0_514:
	s_or_b64 exec, exec, s[0:1]
	v_add_u32_e32 v196, 32, v174
	v_lshlrev_b32_e32 v182, 3, v196
	s_waitcnt lgkmcnt(0)
	s_nop 1
	v_mov_b64_e32 v[0:1], v[148:149]
	v_ffbh_u32_e32 v76, v1
	v_min_u32_e32 v76, 32, v76
	v_lshlrev_b64 v[0:1], v76, v[0:1]
	v_min_u32_e32 v0, 1, v0
	v_or_b32_e32 v0, v1, v0
	v_cvt_f32_u32_e32 v0, v0
	v_sub_u32_e32 v1, 32, v76
	v_ldexp_f32 v0, v0, v1
	v_mul_f32_e32 v0, 0x35800000, v0
	v_fmamk_f32 v0, v0, 0x3a800000, v222
	v_rsq_f32_e32 v76, v0
	s_nop 0
	v_mul_f32_e32 v1, v0, v76
	v_fma_f32 v1, -v1, v76, 1.0
	v_mul_f32_e32 v1, 0.5, v1
	v_fma_f32 v0, v1, v76, v76
	v_pk_mul_f32 v[76:77], v[116:117], v[0:1] op_sel_hi:[1,0]
	v_pk_mul_f32 v[78:79], v[114:115], v[0:1] op_sel_hi:[1,0]
	v_pk_mul_f32 v[80:81], v[112:113], v[0:1] op_sel_hi:[1,0]
	v_pk_mul_f32 v[142:143], v[110:111], v[0:1] op_sel_hi:[1,0]
	v_mul_f32_e32 v1, v79, v79
	v_mul_f32_e32 v77, v77, v77
	v_mul_f32_e32 v79, v143, v143
	v_fmac_f32_e32 v1, v78, v78
	v_fmac_f32_e32 v77, v76, v76
	v_mul_f32_e32 v81, v81, v81
	v_fmac_f32_e32 v79, v142, v142
	v_add_f32_e32 v1, v1, v77
	v_add_f32_e32 v1, v79, v1
	v_fmac_f32_e32 v81, v80, v80
	v_add_f32_e32 v1, v81, v1
	ds_bpermute_b32 v76, v246, v1
	s_waitcnt lgkmcnt(0)
	v_add_f32_e32 v1, v1, v76
	ds_bpermute_b32 v76, v75, v1
	s_and_saveexec_b64 s[0:1], s[2:3]
	s_cbranch_execz .LBB0_516
	s_waitcnt lgkmcnt(0)
	v_add_f32_e32 v1, v1, v76
	ds_write_b32 v74, v1 offset:128

; DI float rstd_of(float ssq, float inv_n) { return 1.0f / sqrtf(ssq * inv_n + EPS); }
; DI float acc_get_i(const acc_t* base, unsigned idx, float inv_scale) { return (float)(*(const acc_t*)((const char*)base + idx * 8u)) * inv_scale; }
;     DI void operator()(const f32x4 (&acc)[2][2][4][2], const Unit& u, int wr, int wc, int fr, int fq) const {
;     ...
;             _Pragma("unroll") for (int ai = 0; ai < 2; ++ai) _Pragma("unroll") for (int m = 0; m < 4; ++m) { const int row = u.pm * BM + ai * HALF + wr_ * 64 + m * 16 + fr_;
;                 const float rs = rstd_of(acc_get_i(ssq, (unsigned)row, 1.0f / SSQ_SCALE), 1.0f / DM);
; #pragma unroll
;                 for (int bj = 0; bj < 2; ++bj) { const f32x4 v0 = acc[ai][bj][m][0] * rs, v1 = acc[ai][bj][m][1] * rs;
;                     float ss = (v0[0] * v0[0] + v0[1] * v0[1]) + (v0[2] * v0[2] + v0[3] * v0[3]) + (v1[0] * v1[0] + v1[1] * v1[1]) + (v1[2] * v1[2] + v1[3] * v1[3]);
;                     ss += __shfl_xor(ss, 16); ss += __shfl_xor(ss, 32);
;                     if (fq_ == 0) xl[(wv * 2 + bj) * 128 + ai * 64 + m * 16 + fr_] = ss; }
.LBB0_518:
	s_or_b64 exec, exec, s[0:1]
	v_add_u32_e32 v192, 48, v174
	v_lshlrev_b32_e32 v186, 3, v192
	s_waitcnt lgkmcnt(0)
	s_nop 1
	v_mov_b64_e32 v[0:1], v[194:195]
	v_ffbh_u32_e32 v76, v1
	v_min_u32_e32 v76, 32, v76
	v_lshlrev_b64 v[0:1], v76, v[0:1]
	v_min_u32_e32 v0, 1, v0
	v_or_b32_e32 v0, v1, v0
	v_cvt_f32_u32_e32 v0, v0
	v_sub_u32_e32 v1, 32, v76
	v_ldexp_f32 v0, v0, v1
	v_mul_f32_e32 v0, 0x35800000, v0
	v_fmamk_f32 v0, v0, 0x3a800000, v222
	v_rsq_f32_e32 v76, v0
	s_nop 0
	v_mul_f32_e32 v1, v0, v76
	v_fma_f32 v1, -v1, v76, 1.0
	v_mul_f32_e32 v1, 0.5, v1
	v_fma_f32 v0, v1, v76, v76
	v_pk_mul_f32 v[76:77], v[100:101], v[0:1] op_sel_hi:[1,0]
	v_pk_mul_f32 v[78:79], v[98:99], v[0:1] op_sel_hi:[1,0]
	v_pk_mul_f32 v[80:81], v[92:93], v[0:1] op_sel_hi:[1,0]
	v_pk_mul_f32 v[142:143], v[90:91], v[0:1] op_sel_hi:[1,0]
	v_mul_f32_e32 v1, v79, v79
	v_mul_f32_e32 v77, v77, v77
	v_mul_f32_e32 v79, v143, v143
	v_fmac_f32_e32 v1, v78, v78
	v_fmac_f32_e32 v77, v76, v76
	v_mul_f32_e32 v81, v81, v81
	v_fmac_f32_e32 v79, v142, v142
	v_add_f32_e32 v1, v1, v77
	v_add_f32_e32 v1, v79, v1
	v_fmac_f32_e32 v81, v80, v80
	v_add_f32_e32 v1, v81, v1
	ds_bpermute_b32 v76, v246, v1
	s_waitcnt lgkmcnt(0)
	v_add_f32_e32 v1, v1, v76
	ds_bpermute_b32 v76, v75, v1
	s_and_saveexec_b64 s[0:1], s[2:3]
	s_cbranch_execz .LBB0_520
	s_waitcnt lgkmcnt(0)
	v_add_f32_e32 v1, v1, v76
	ds_write_b32 v74, v1 offset:192

; DI float rstd_of(float ssq, float inv_n) { return 1.0f / sqrtf(ssq * inv_n + EPS); }
; DI float acc_get_i(const acc_t* base, unsigned idx, float inv_scale) { return (float)(*(const acc_t*)((const char*)base + idx * 8u)) * inv_scale; }
;     DI void operator()(const f32x4 (&acc)[2][2][4][2], const Unit& u, int wr, int wc, int fr, int fq) const {
;     ...
;             _Pragma("unroll") for (int ai = 0; ai < 2; ++ai) _Pragma("unroll") for (int m = 0; m < 4; ++m) { const int row = u.pm * BM + ai * HALF + wr_ * 64 + m * 16 + fr_;
;                 const float rs = rstd_of(acc_get_i(ssq, (unsigned)row, 1.0f / SSQ_SCALE), 1.0f / DM);
; #pragma unroll
;                 for (int bj = 0; bj < 2; ++bj) { const f32x4 v0 = acc[ai][bj][m][0] * rs, v1 = acc[ai][bj][m][1] * rs;
;                     float ss = (v0[0] * v0[0] + v0[1] * v0[1]) + (v0[2] * v0[2] + v0[3] * v0[3]) + (v1[0] * v1[0] + v1[1] * v1[1]) + (v1[2] * v1[2] + v1[3] * v1[3]);
;                     ss += __shfl_xor(ss, 16); ss += __shfl_xor(ss, 32);
;                     if (fq_ == 0) xl[(wv * 2 + bj) * 128 + ai * 64 + m * 16 + fr_] = ss; }
.LBB0_522:
	s_or_b64 exec, exec, s[0:1]
	v_add_u32_e32 v188, 0x80, v174
	v_lshlrev_b32_e32 v190, 3, v188
	s_waitcnt lgkmcnt(0)
	s_nop 1
	v_mov_b64_e32 v[0:1], v[198:199]
	v_ffbh_u32_e32 v76, v1
	v_min_u32_e32 v76, 32, v76
	v_lshlrev_b64 v[0:1], v76, v[0:1]
	v_min_u32_e32 v0, 1, v0
	v_or_b32_e32 v0, v1, v0
	v_cvt_f32_u32_e32 v0, v0
	v_sub_u32_e32 v1, 32, v76
	v_ldexp_f32 v0, v0, v1
	v_mul_f32_e32 v0, 0x35800000, v0
	v_fmamk_f32 v0, v0, 0x3a800000, v222
	v_rsq_f32_e32 v76, v0
	s_nop 0
	v_mul_f32_e32 v1, v0, v76
	v_fma_f32 v1, -v1, v76, 1.0
	v_mul_f32_e32 v1, 0.5, v1
	v_fma_f32 v0, v1, v76, v76
	v_pk_mul_f32 v[76:77], v[72:73], v[0:1] op_sel_hi:[1,0]
	v_pk_mul_f32 v[78:79], v[70:71], v[0:1] op_sel_hi:[1,0]
	v_pk_mul_f32 v[80:81], v[68:69], v[0:1] op_sel_hi:[1,0]
	v_pk_mul_f32 v[142:143], v[66:67], v[0:1] op_sel_hi:[1,0]
	v_mul_f32_e32 v1, v79, v79
	v_mul_f32_e32 v77, v77, v77
	v_mul_f32_e32 v79, v143, v143
	v_fmac_f32_e32 v1, v78, v78
	v_fmac_f32_e32 v77, v76, v76
	v_mul_f32_e32 v81, v81, v81
	v_fmac_f32_e32 v79, v142, v142
	v_add_f32_e32 v1, v1, v77
	v_add_f32_e32 v1, v79, v1
	v_fmac_f32_e32 v81, v80, v80
	v_add_f32_e32 v1, v81, v1
	ds_bpermute_b32 v76, v246, v1
	s_waitcnt lgkmcnt(0)
	v_add_f32_e32 v1, v1, v76
	ds_bpermute_b32 v76, v75, v1
	s_and_saveexec_b64 s[0:1], s[2:3]
	s_cbranch_execz .LBB0_524
	s_waitcnt lgkmcnt(0)
	v_add_f32_e32 v1, v1, v76
	ds_write_b32 v74, v1 offset:256

; DI float rstd_of(float ssq, float inv_n) { return 1.0f / sqrtf(ssq * inv_n + EPS); }
; DI float acc_get_i(const acc_t* base, unsigned idx, float inv_scale) { return (float)(*(const acc_t*)((const char*)base + idx * 8u)) * inv_scale; }
;     DI void operator()(const f32x4 (&acc)[2][2][4][2], const Unit& u, int wr, int wc, int fr, int fq) const {
;     ...
;             _Pragma("unroll") for (int ai = 0; ai < 2; ++ai) _Pragma("unroll") for (int m = 0; m < 4; ++m) { const int row = u.pm * BM + ai * HALF + wr_ * 64 + m * 16 + fr_;
;                 const float rs = rstd_of(acc_get_i(ssq, (unsigned)row, 1.0f / SSQ_SCALE), 1.0f / DM);
; #pragma unroll
;                 for (int bj = 0; bj < 2; ++bj) { const f32x4 v0 = acc[ai][bj][m][0] * rs, v1 = acc[ai][bj][m][1] * rs;
;                     float ss = (v0[0] * v0[0] + v0[1] * v0[1]) + (v0[2] * v0[2] + v0[3] * v0[3]) + (v1[0] * v1[0] + v1[1] * v1[1]) + (v1[2] * v1[2] + v1[3] * v1[3]);
;                     ss += __shfl_xor(ss, 16); ss += __shfl_xor(ss, 32);
;                     if (fq_ == 0) xl[(wv * 2 + bj) * 128 + ai * 64 + m * 16 + fr_] = ss; }
.LBB0_526:
	s_or_b64 exec, exec, s[0:1]
	v_add_u32_e32 v184, 0x90, v174
	v_lshlrev_b32_e32 v208, 3, v184
	s_waitcnt lgkmcnt(0)
	s_nop 1
	v_mov_b64_e32 v[0:1], v[202:203]
	v_ffbh_u32_e32 v76, v1
	v_min_u32_e32 v76, 32, v76
	v_lshlrev_b64 v[0:1], v76, v[0:1]
	v_min_u32_e32 v0, 1, v0
	v_or_b32_e32 v0, v1, v0
	v_cvt_f32_u32_e32 v0, v0
	v_sub_u32_e32 v1, 32, v76
	v_ldexp_f32 v0, v0, v1
	v_mul_f32_e32 v0, 0x35800000, v0
	v_fmamk_f32 v0, v0, 0x3a800000, v222
	v_rsq_f32_e32 v76, v0
	s_nop 0
	v_mul_f32_e32 v1, v0, v76
	v_fma_f32 v1, -v1, v76, 1.0
	v_mul_f32_e32 v1, 0.5, v1
	v_fma_f32 v0, v1, v76, v76
	v_pk_mul_f32 v[76:77], v[56:57], v[0:1] op_sel_hi:[1,0]
	v_pk_mul_f32 v[78:79], v[54:55], v[0:1] op_sel_hi:[1,0]
	v_pk_mul_f32 v[80:81], v[52:53], v[0:1] op_sel_hi:[1,0]
	v_pk_mul_f32 v[142:143], v[50:51], v[0:1] op_sel_hi:[1,0]
	v_mul_f32_e32 v1, v79, v79
	v_mul_f32_e32 v77, v77, v77
	v_mul_f32_e32 v79, v143, v143
	v_fmac_f32_e32 v1, v78, v78
	v_fmac_f32_e32 v77, v76, v76
	v_mul_f32_e32 v81, v81, v81
	v_fmac_f32_e32 v79, v142, v142
	v_add_f32_e32 v1, v1, v77
	v_add_f32_e32 v1, v79, v1
	v_fmac_f32_e32 v81, v80, v80
	v_add_f32_e32 v1, v81, v1
	ds_bpermute_b32 v76, v246, v1
	s_waitcnt lgkmcnt(0)
	v_add_f32_e32 v1, v1, v76
	ds_bpermute_b32 v76, v75, v1
	s_and_saveexec_b64 s[0:1], s[2:3]
	s_cbranch_execz .LBB0_528
	s_waitcnt lgkmcnt(0)
	v_add_f32_e32 v1, v1, v76
	ds_write_b32 v74, v1 offset:320

; DI float rstd_of(float ssq, float inv_n) { return 1.0f / sqrtf(ssq * inv_n + EPS); }
; DI float acc_get_i(const acc_t* base, unsigned idx, float inv_scale) { return (float)(*(const acc_t*)((const char*)base + idx * 8u)) * inv_scale; }
;     DI void operator()(const f32x4 (&acc)[2][2][4][2], const Unit& u, int wr, int wc, int fr, int fq) const {
;     ...
;             _Pragma("unroll") for (int ai = 0; ai < 2; ++ai) _Pragma("unroll") for (int m = 0; m < 4; ++m) { const int row = u.pm * BM + ai * HALF + wr_ * 64 + m * 16 + fr_;
;                 const float rs = rstd_of(acc_get_i(ssq, (unsigned)row, 1.0f / SSQ_SCALE), 1.0f / DM);
; #pragma unroll
;                 for (int bj = 0; bj < 2; ++bj) { const f32x4 v0 = acc[ai][bj][m][0] * rs, v1 = acc[ai][bj][m][1] * rs;
;                     float ss = (v0[0] * v0[0] + v0[1] * v0[1]) + (v0[2] * v0[2] + v0[3] * v0[3]) + (v1[0] * v1[0] + v1[1] * v1[1]) + (v1[2] * v1[2] + v1[3] * v1[3]);
;                     ss += __shfl_xor(ss, 16); ss += __shfl_xor(ss, 32);
;                     if (fq_ == 0) xl[(wv * 2 + bj) * 128 + ai * 64 + m * 16 + fr_] = ss; }
.LBB0_530:
	s_or_b64 exec, exec, s[0:1]
	v_add_u32_e32 v180, 0xa0, v174
	v_lshlrev_b32_e32 v212, 3, v180
	s_waitcnt lgkmcnt(0)
	s_nop 1
	v_mov_b64_e32 v[0:1], v[204:205]
	v_ffbh_u32_e32 v76, v1
	v_min_u32_e32 v76, 32, v76
	v_lshlrev_b64 v[0:1], v76, v[0:1]
	v_min_u32_e32 v0, 1, v0
	v_or_b32_e32 v0, v1, v0
	v_cvt_f32_u32_e32 v0, v0
	v_sub_u32_e32 v1, 32, v76
	v_ldexp_f32 v0, v0, v1
	v_mul_f32_e32 v0, 0x35800000, v0
	v_fmamk_f32 v0, v0, 0x3a800000, v222
	v_rsq_f32_e32 v76, v0
	s_nop 0
	v_mul_f32_e32 v1, v0, v76
	v_fma_f32 v1, -v1, v76, 1.0
	v_mul_f32_e32 v1, 0.5, v1
	v_fma_f32 v0, v1, v76, v76
	v_pk_mul_f32 v[76:77], v[40:41], v[0:1] op_sel_hi:[1,0]
	v_pk_mul_f32 v[78:79], v[38:39], v[0:1] op_sel_hi:[1,0]
	v_pk_mul_f32 v[80:81], v[36:37], v[0:1] op_sel_hi:[1,0]
	v_pk_mul_f32 v[142:143], v[34:35], v[0:1] op_sel_hi:[1,0]
	v_mul_f32_e32 v1, v79, v79
	v_mul_f32_e32 v77, v77, v77
	v_mul_f32_e32 v79, v143, v143
	v_fmac_f32_e32 v1, v78, v78
	v_fmac_f32_e32 v77, v76, v76
	v_mul_f32_e32 v81, v81, v81
	v_fmac_f32_e32 v79, v142, v142
	v_add_f32_e32 v1, v1, v77
	v_add_f32_e32 v1, v79, v1
	v_fmac_f32_e32 v81, v80, v80
	v_add_f32_e32 v1, v81, v1
	ds_bpermute_b32 v76, v246, v1
	s_waitcnt lgkmcnt(0)
	v_add_f32_e32 v1, v1, v76
	ds_bpermute_b32 v76, v75, v1
	s_and_saveexec_b64 s[0:1], s[2:3]
	s_cbranch_execz .LBB0_532
	s_waitcnt lgkmcnt(0)
	v_add_f32_e32 v1, v1, v76
	ds_write_b32 v74, v1 offset:384

; DI float rstd_of(float ssq, float inv_n) { return 1.0f / sqrtf(ssq * inv_n + EPS); }
; DI float acc_get_i(const acc_t* base, unsigned idx, float inv_scale) { return (float)(*(const acc_t*)((const char*)base + idx * 8u)) * inv_scale; }
;     DI void operator()(const f32x4 (&acc)[2][2][4][2], const Unit& u, int wr, int wc, int fr, int fq) const {
;     ...
;             _Pragma("unroll") for (int ai = 0; ai < 2; ++ai) _Pragma("unroll") for (int m = 0; m < 4; ++m) { const int row = u.pm * BM + ai * HALF + wr_ * 64 + m * 16 + fr_;
;                 const float rs = rstd_of(acc_get_i(ssq, (unsigned)row, 1.0f / SSQ_SCALE), 1.0f / DM);
; #pragma unroll
;                 for (int bj = 0; bj < 2; ++bj) { const f32x4 v0 = acc[ai][bj][m][0] * rs, v1 = acc[ai][bj][m][1] * rs;
;                     float ss = (v0[0] * v0[0] + v0[1] * v0[1]) + (v0[2] * v0[2] + v0[3] * v0[3]) + (v1[0] * v1[0] + v1[1] * v1[1]) + (v1[2] * v1[2] + v1[3] * v1[3]);
;                     ss += __shfl_xor(ss, 16); ss += __shfl_xor(ss, 32);
;                     if (fq_ == 0) xl[(wv * 2 + bj) * 128 + ai * 64 + m * 16 + fr_] = ss; }
.LBB0_534:
	s_or_b64 exec, exec, s[0:1]
	v_add_u32_e32 v176, 0xb0, v174
	v_lshlrev_b32_e32 v216, 3, v176
	s_waitcnt lgkmcnt(0)
	s_nop 1
	v_mov_b64_e32 v[0:1], v[206:207]
	v_ffbh_u32_e32 v76, v1
	v_min_u32_e32 v76, 32, v76
	v_lshlrev_b64 v[0:1], v76, v[0:1]
	v_min_u32_e32 v0, 1, v0
	v_or_b32_e32 v0, v1, v0
	v_cvt_f32_u32_e32 v0, v0
	v_sub_u32_e32 v1, 32, v76
	v_ldexp_f32 v0, v0, v1
	v_mul_f32_e32 v0, 0x35800000, v0
	v_fmamk_f32 v0, v0, 0x3a800000, v222
	v_rsq_f32_e32 v76, v0
	s_nop 0
	v_mul_f32_e32 v1, v0, v76
	v_fma_f32 v1, -v1, v76, 1.0
	v_mul_f32_e32 v1, 0.5, v1
	v_fma_f32 v0, v1, v76, v76
	v_pk_mul_f32 v[76:77], v[24:25], v[0:1] op_sel_hi:[1,0]
	v_pk_mul_f32 v[78:79], v[22:23], v[0:1] op_sel_hi:[1,0]
	v_pk_mul_f32 v[80:81], v[20:21], v[0:1] op_sel_hi:[1,0]
	v_pk_mul_f32 v[142:143], v[18:19], v[0:1] op_sel_hi:[1,0]
	v_mul_f32_e32 v1, v79, v79
	v_mul_f32_e32 v77, v77, v77
	v_mul_f32_e32 v79, v143, v143
	v_fmac_f32_e32 v1, v78, v78
	v_fmac_f32_e32 v77, v76, v76
	v_mul_f32_e32 v81, v81, v81
	v_fmac_f32_e32 v79, v142, v142
	v_add_f32_e32 v1, v1, v77
	v_add_f32_e32 v1, v79, v1
	v_fmac_f32_e32 v81, v80, v80
	v_add_f32_e32 v1, v81, v1
	ds_bpermute_b32 v76, v246, v1
	s_waitcnt lgkmcnt(0)
	v_add_f32_e32 v1, v1, v76
	ds_bpermute_b32 v76, v75, v1
	s_and_saveexec_b64 s[0:1], s[2:3]
	s_cbranch_execz .LBB0_536
	s_waitcnt lgkmcnt(0)
	v_add_f32_e32 v1, v1, v76
	ds_write_b32 v74, v1 offset:448

; #define LAS __attribute__((address_space(3)))
; DI unsigned pk2(float lo, float hi) { f32x2 v = {lo, hi}; bf16x2_t b = __builtin_convertvector(v, bf16x2_t); return __builtin_bit_cast(unsigned, b); }
; DI float rstd_of(float ssq, float inv_n) { return 1.0f / sqrtf(ssq * inv_n + EPS); }
; DI void gate_unit(int un, int& cached_g, const bf16_t* Z, bf16_t* H, const float* Wsl, const float* gmb, const float* gmg, LAS unsigned char* lds, int tid, int wid, int lane) {
;     ...
;     for (int i = 0; i < 4; ++i) { const int idx = tid + NTHR * i, s = idx >> 4, ch = idx & 15;
;         const u32x4 w = *(const u32x4*)(Z + (size_t)(row0 + s) * INC + 2048 + g * 128 + ch * 8); float v[8]; unpack8(w, v);
;         float ss = 0.f;
; #pragma unroll
;         for (int j = 0; j < 8; ++j) ss += v[j] * v[j];
;         ss += __shfl_xor(ss, 1); ss += __shfl_xor(ss, 2); ss += __shfl_xor(ss, 4); ss += __shfl_xor(ss, 8);
;         const float rs = rstd_of(ss, 1.0f / 128.f);
; #pragma unroll
;         for (int j = 0; j < 8; j += 2) { const unsigned pw = pk2(v[j] * rs * gmg[ch * 8 + j], v[j + 1] * rs * gmg[ch * 8 + j + 1]);
;             *(LAS bf16_t*)(Gt + (ch * 8 + j) * 272 + ((s ^ (ch << 3)) << 1)) = (bf16_t)(pw & 0xffffu); *(LAS bf16_t*)(Gt + (ch * 8 + j + 1) * 272 + ((s ^ (ch << 3)) << 1)) = (bf16_t)(pw >> 16); } }
.LBB0_1861:
	v_add_u32_e32 v0, s15, v91
	v_mov_b64_e32 v[10:11], s[28:29]
	v_mad_i64_i32 v[0:1], vcc, v0, s12, v[10:11]
	s_lshl_b32 s6, s4, 1
	v_lshl_add_u64 v[0:1], v[0:1], 0, s[6:7]
	v_mov_b32_e32 v57, v97
	v_lshl_add_u64 v[0:1], v[0:1], 0, v[56:57]
	v_add_co_u32_e32 v0, vcc, 0x1000, v0
	s_movk_i32 s95, 0x1000
	s_nop 0
	v_addc_co_u32_e32 v1, vcc, 0, v1, vcc
	v_mov_b32_e32 v146, 0x28000
	v_mov_b32_e32 v147, 0
	global_load_dwordx4 v[130:133], v[0:1], off
	v_lshl_add_u64 v[148:149], v[146:147], 0, v[0:1]
	global_load_dwordx4 v[134:137], v[148:149], off
	v_lshl_add_u64 v[148:149], v[146:147], 1, v[0:1]
	global_load_dwordx4 v[138:141], v[148:149], off
	v_lshl_add_u64 v[148:149], v[146:147], 0, v[148:149]
	global_load_dwordx4 v[142:145], v[148:149], off
	v_ashrrev_i32_e32 v75, 31, v74
	v_mov_b32_e32 v116, v85
	s_waitcnt vmcnt(0)
	v_mov_b64_e32 v[0:1], v[130:131]
	v_mov_b64_e32 v[2:3], v[132:133]
	v_and_b32_e32 v12, 0xffff0000, v2
	v_lshlrev_b32_e32 v13, 16, v2
	v_and_b32_e32 v16, 0xffff0000, v3
	v_lshlrev_b32_e32 v17, 16, v3
	global_load_dwordx4 v[2:5], v[52:53], off offset:16
	global_load_dwordx4 v[6:9], v[52:53], off
	v_lshlrev_b32_e32 v20, 16, v0
	v_and_b32_e32 v21, 0xffff0000, v0
	v_pk_mul_f32 v[22:23], v[20:21], v[20:21]
	v_lshlrev_b32_e32 v24, 16, v1
	v_and_b32_e32 v25, 0xffff0000, v1
	v_pk_mul_f32 v[0:1], v[24:25], v[24:25]
	v_add_f32_e32 v22, v22, v23
	v_add_f32_e32 v0, v0, v22
	v_pk_mul_f32 v[14:15], v[12:13], v[12:13]
	v_add_f32_e32 v0, v1, v0
	v_add_f32_e32 v0, v15, v0
	v_pk_mul_f32 v[18:19], v[16:17], v[16:17]
	v_add_f32_e32 v0, v14, v0
	v_add_f32_e32 v0, v19, v0
	v_add_f32_e32 v0, v18, v0
	ds_bpermute_b32 v1, v87, v0
	s_waitcnt lgkmcnt(0)
	v_add_f32_e32 v0, v0, v1
	ds_bpermute_b32 v1, v88, v0
	s_waitcnt lgkmcnt(0)
	v_add_f32_e32 v0, v0, v1
	ds_bpermute_b32 v1, v89, v0
	s_waitcnt lgkmcnt(0)
	v_add_f32_e32 v0, v0, v1
	ds_bpermute_b32 v1, v90, v0
	s_waitcnt lgkmcnt(0)
	v_add_f32_e32 v0, v0, v1
	v_fmamk_f32 v0, v0, 0x3c000000, v222
	v_cmp_gt_f32_e64 s[4:5], s13, v0
	v_mul_f32_e32 v1, 0x4f800000, v0
	s_nop 0
	v_cndmask_b32_e64 v1, v0, v1, s[4:5]
	v_sqrt_f32_e32 v14, v1
	v_mov_b32_e32 v0, 0
	v_mov_b32_e32 v28, v0
	v_mov_b32_e32 v29, v0
	v_add_u32_e32 v15, -1, v14
	v_fma_f32 v18, -v15, v14, v1
	v_cmp_ge_f32_e32 vcc, 0, v18
	v_add_u32_e32 v18, 1, v14
	v_mov_b32_e32 v30, v0
	v_cndmask_b32_e32 v15, v14, v15, vcc
	v_fma_f32 v14, -v18, v14, v1
	v_cmp_lt_f32_e32 vcc, 0, v14
	v_mov_b32_e32 v31, v0
	s_nop 0
	v_cndmask_b32_e32 v14, v15, v18, vcc
	v_mul_f32_e32 v15, 0x37800000, v14
	v_cndmask_b32_e64 v14, v14, v15, s[4:5]
	v_cmp_class_f32_e32 vcc, v1, v223
	s_nop 1
	v_cndmask_b32_e32 v1, v14, v1, vcc
	v_div_scale_f32 v14, s[4:5], v1, v1, 1.0
	v_rcp_f32_e32 v15, v14
	s_nop 0
	v_fma_f32 v18, -v14, v15, 1.0
	v_fmac_f32_e32 v15, v18, v15
	v_div_scale_f32 v18, vcc, 1.0, v1, 1.0
	v_mul_f32_e32 v19, v18, v15
	v_fma_f32 v22, -v14, v19, v18
	v_fmac_f32_e32 v19, v22, v15
	v_fma_f32 v14, -v14, v19, v18
	v_div_fmas_f32 v14, v14, v15, v19
	v_div_fixup_f32 v14, v14, v1, 1.0
	v_pk_mul_f32 v[18:19], v[14:15], v[20:21] op_sel_hi:[0,1]
	s_waitcnt vmcnt(0)
	v_pk_mul_f32 v[18:19], v[6:7], v[18:19]
	v_add_u32_e32 v15, v92, v93
	v_cvt_pk_bf16_f32 v1, v18, v19
	v_pk_mul_f32 v[18:19], v[14:15], v[24:25] op_sel_hi:[0,1]
	v_pk_mul_f32 v[18:19], v[8:9], v[18:19]
	v_pk_mul_f32 v[12:13], v[14:15], v[12:13] op_sel_hi:[0,1]
	ds_write_b16 v15, v1 offset:34816
	ds_write_b16_d16_hi v15, v1 offset:35088
	v_cvt_pk_bf16_f32 v1, v18, v19
	v_add_u32_e32 v18, v92, v94
	v_pk_mul_f32 v[12:13], v[2:3], v[12:13] op_sel:[0,1] op_sel_hi:[1,0]
	ds_write_b16 v18, v1 offset:34816
	ds_write_b16_d16_hi v15, v1 offset:35632
	v_cvt_pk_bf16_f32 v1, v12, v13
	v_pk_mul_f32 v[12:13], v[14:15], v[16:17] op_sel_hi:[0,1]
	v_pk_mul_f32 v[12:13], v[4:5], v[12:13] op_sel:[0,1] op_sel_hi:[1,0]
	ds_write_b16 v18, v1 offset:35360
	ds_write_b16_d16_hi v15, v1 offset:36176
	v_cvt_pk_bf16_f32 v1, v12, v13
	ds_write_b16 v18, v1 offset:35904
	ds_write_b16_d16_hi v15, v1 offset:36720
	v_add_u32_e32 v1, s15, v102
	v_mad_i64_i32 v[12:13], s[4:5], v1, s12, v[10:11]
	v_lshl_add_u64 v[12:13], v[12:13], 0, s[6:7]
	v_lshl_add_u64 v[12:13], v[12:13], 0, v[56:57]
	v_add_co_u32_e32 v12, vcc, s95, v12
	s_nop 1
	v_addc_co_u32_e32 v13, vcc, 0, v13, vcc
	v_mov_b64_e32 v[12:13], v[134:135]
	v_mov_b64_e32 v[14:15], v[136:137]
	v_lshlrev_b32_e32 v22, 16, v12
	v_and_b32_e32 v23, 0xffff0000, v12
	v_pk_mul_f32 v[24:25], v[22:23], v[22:23]
	v_lshlrev_b32_e32 v12, 16, v13
	v_and_b32_e32 v13, 0xffff0000, v13
	v_pk_mul_f32 v[26:27], v[12:13], v[12:13]
	v_add_f32_e32 v1, v24, v25
	v_and_b32_e32 v16, 0xffff0000, v14
	v_lshlrev_b32_e32 v17, 16, v14
	v_add_f32_e32 v1, v26, v1
	v_pk_mul_f32 v[18:19], v[16:17], v[16:17]
	v_add_f32_e32 v1, v27, v1
	v_and_b32_e32 v14, 0xffff0000, v15
	v_lshlrev_b32_e32 v15, 16, v15
	v_add_f32_e32 v1, v19, v1
	v_pk_mul_f32 v[20:21], v[14:15], v[14:15]
	v_add_f32_e32 v1, v18, v1
	v_add_f32_e32 v1, v21, v1
	v_add_f32_e32 v1, v20, v1
	ds_bpermute_b32 v18, v87, v1
	s_waitcnt lgkmcnt(0)
	v_add_f32_e32 v1, v1, v18
	ds_bpermute_b32 v18, v88, v1
	s_waitcnt lgkmcnt(0)
	v_add_f32_e32 v1, v1, v18
	ds_bpermute_b32 v18, v89, v1
	s_waitcnt lgkmcnt(0)
	v_add_f32_e32 v1, v1, v18
	ds_bpermute_b32 v18, v90, v1
	s_waitcnt lgkmcnt(0)
; #define LAS __attribute__((address_space(3)))
; DI unsigned pk2(float lo, float hi) { f32x2 v = {lo, hi}; bf16x2_t b = __builtin_convertvector(v, bf16x2_t); return __builtin_bit_cast(unsigned, b); }
; DI float rstd_of(float ssq, float inv_n) { return 1.0f / sqrtf(ssq * inv_n + EPS); }
; DI void gate_unit(int un, int& cached_g, const bf16_t* Z, bf16_t* H, const float* Wsl, const float* gmb, const float* gmg, LAS unsigned char* lds, int tid, int wid, int lane) {
;     ...
;     for (int i = 0; i < 4; ++i) { const int idx = tid + NTHR * i, s = idx >> 4, ch = idx & 15;
;         const u32x4 w = *(const u32x4*)(Z + (size_t)(row0 + s) * INC + 2048 + g * 128 + ch * 8); float v[8]; unpack8(w, v);
;         float ss = 0.f;
; #pragma unroll
;         for (int j = 0; j < 8; ++j) ss += v[j] * v[j];
;         ss += __shfl_xor(ss, 1); ss += __shfl_xor(ss, 2); ss += __shfl_xor(ss, 4); ss += __shfl_xor(ss, 8);
;         const float rs = rstd_of(ss, 1.0f / 128.f);
; #pragma unroll
;         for (int j = 0; j < 8; j += 2) { const unsigned pw = pk2(v[j] * rs * gmg[ch * 8 + j], v[j + 1] * rs * gmg[ch * 8 + j + 1]);
;             *(LAS bf16_t*)(Gt + (ch * 8 + j) * 272 + ((s ^ (ch << 3)) << 1)) = (bf16_t)(pw & 0xffffu); *(LAS bf16_t*)(Gt + (ch * 8 + j + 1) * 272 + ((s ^ (ch << 3)) << 1)) = (bf16_t)(pw >> 16); } }
;     __syncthreads();
;     f32x16 acc[2];
; #pragma unroll
;     for (int i = 0; i < 16; ++i) { acc[0][i] = 0.f; acc[1][i] = 0.f; }
	v_add_f32_e32 v1, v1, v18
	v_fmamk_f32 v1, v1, 0x3c000000, v222
	v_rsq_f32_e32 v18, v1
	s_nop 0
	v_mul_f32_e32 v19, v1, v18
	v_fma_f32 v19, -v19, v18, 1.0
	v_mul_f32_e32 v19, 0.5, v19
	v_fmac_f32_e32 v18, v19, v18
	v_pk_mul_f32 v[20:21], v[18:19], v[22:23] op_sel_hi:[0,1]
	v_add_u32_e32 v19, v103, v93
	v_pk_mul_f32 v[20:21], v[6:7], v[20:21]
	v_pk_mul_f32 v[12:13], v[18:19], v[12:13] op_sel_hi:[0,1]
	v_cvt_pk_bf16_f32 v1, v20, v21
	v_pk_mul_f32 v[12:13], v[8:9], v[12:13]
	ds_write_b16 v19, v1 offset:34816
	ds_write_b16_d16_hi v19, v1 offset:35088
	v_cvt_pk_bf16_f32 v1, v12, v13
	v_pk_mul_f32 v[12:13], v[18:19], v[16:17] op_sel_hi:[0,1]
	v_add_u32_e32 v20, v103, v94
	v_pk_mul_f32 v[12:13], v[2:3], v[12:13] op_sel:[0,1] op_sel_hi:[1,0]
	ds_write_b16 v20, v1 offset:34816
	ds_write_b16_d16_hi v19, v1 offset:35632
	v_cvt_pk_bf16_f32 v1, v12, v13
	v_pk_mul_f32 v[12:13], v[18:19], v[14:15] op_sel_hi:[0,1]
	v_pk_mul_f32 v[12:13], v[4:5], v[12:13] op_sel:[0,1] op_sel_hi:[1,0]
	ds_write_b16 v20, v1 offset:35360
	ds_write_b16_d16_hi v19, v1 offset:36176
	v_cvt_pk_bf16_f32 v1, v12, v13
	ds_write_b16 v20, v1 offset:35904
	ds_write_b16_d16_hi v19, v1 offset:36720
	v_add_u32_e32 v1, s15, v104
	v_mad_i64_i32 v[12:13], s[4:5], v1, s12, v[10:11]
	v_lshl_add_u64 v[12:13], v[12:13], 0, s[6:7]
	v_lshl_add_u64 v[12:13], v[12:13], 0, v[56:57]
	v_add_co_u32_e32 v12, vcc, s95, v12
	s_nop 1
	v_addc_co_u32_e32 v13, vcc, 0, v13, vcc
	v_mov_b64_e32 v[12:13], v[138:139]
	v_mov_b64_e32 v[14:15], v[140:141]
	v_lshlrev_b32_e32 v22, 16, v12
	v_and_b32_e32 v23, 0xffff0000, v12
	v_pk_mul_f32 v[24:25], v[22:23], v[22:23]
	v_lshlrev_b32_e32 v12, 16, v13
	v_and_b32_e32 v13, 0xffff0000, v13
	v_pk_mul_f32 v[26:27], v[12:13], v[12:13]
	v_add_f32_e32 v1, v24, v25
	v_and_b32_e32 v16, 0xffff0000, v14
	v_lshlrev_b32_e32 v17, 16, v14
	v_add_f32_e32 v1, v26, v1
	v_pk_mul_f32 v[18:19], v[16:17], v[16:17]
	v_add_f32_e32 v1, v27, v1
	v_and_b32_e32 v14, 0xffff0000, v15
	v_lshlrev_b32_e32 v15, 16, v15
	v_add_f32_e32 v1, v19, v1
	v_pk_mul_f32 v[20:21], v[14:15], v[14:15]
	v_add_f32_e32 v1, v18, v1
	v_add_f32_e32 v1, v21, v1
	v_add_f32_e32 v1, v20, v1
	ds_bpermute_b32 v18, v87, v1
	v_mov_b32_e32 v26, v0
	v_mov_b32_e32 v27, v0
	s_waitcnt lgkmcnt(0)
	v_add_f32_e32 v1, v1, v18
	ds_bpermute_b32 v18, v88, v1
	s_waitcnt lgkmcnt(0)
	v_add_f32_e32 v1, v1, v18
	ds_bpermute_b32 v18, v89, v1
	s_waitcnt lgkmcnt(0)
	v_add_f32_e32 v1, v1, v18
	ds_bpermute_b32 v18, v90, v1
	s_waitcnt lgkmcnt(0)
	v_add_f32_e32 v1, v1, v18
	v_fmamk_f32 v1, v1, 0x3c000000, v222
	v_rsq_f32_e32 v18, v1
	s_nop 0
	v_mul_f32_e32 v19, v1, v18
	v_fma_f32 v19, -v19, v18, 1.0
	v_mul_f32_e32 v19, 0.5, v19
	v_fmac_f32_e32 v18, v19, v18
	v_pk_mul_f32 v[20:21], v[18:19], v[22:23] op_sel_hi:[0,1]
	v_add_u32_e32 v19, v105, v93
	v_pk_mul_f32 v[20:21], v[6:7], v[20:21]
	v_pk_mul_f32 v[12:13], v[18:19], v[12:13] op_sel_hi:[0,1]
	v_cvt_pk_bf16_f32 v1, v20, v21
	v_pk_mul_f32 v[12:13], v[8:9], v[12:13]
	ds_write_b16 v19, v1 offset:34816
	ds_write_b16_d16_hi v19, v1 offset:35088
	v_cvt_pk_bf16_f32 v1, v12, v13
	v_pk_mul_f32 v[12:13], v[18:19], v[16:17] op_sel_hi:[0,1]
	v_add_u32_e32 v20, v105, v94
	v_pk_mul_f32 v[12:13], v[2:3], v[12:13] op_sel:[0,1] op_sel_hi:[1,0]
	ds_write_b16 v20, v1 offset:34816
	ds_write_b16_d16_hi v19, v1 offset:35632
	v_cvt_pk_bf16_f32 v1, v12, v13
	v_pk_mul_f32 v[12:13], v[18:19], v[14:15] op_sel_hi:[0,1]
	v_pk_mul_f32 v[12:13], v[4:5], v[12:13] op_sel:[0,1] op_sel_hi:[1,0]
	ds_write_b16 v20, v1 offset:35360
	ds_write_b16_d16_hi v19, v1 offset:36176
	v_cvt_pk_bf16_f32 v1, v12, v13
	ds_write_b16 v20, v1 offset:35904
	ds_write_b16_d16_hi v19, v1 offset:36720
	v_add_u32_e32 v1, s15, v106
	v_mad_i64_i32 v[10:11], s[4:5], v1, s12, v[10:11]
	v_lshl_add_u64 v[10:11], v[10:11], 0, s[6:7]
	v_lshl_add_u64 v[10:11], v[10:11], 0, v[56:57]
	v_add_co_u32_e32 v10, vcc, s95, v10
	v_mov_b32_e32 v57, v95
	s_nop 0
	v_addc_co_u32_e32 v11, vcc, 0, v11, vcc
	v_mov_b64_e32 v[10:11], v[142:143]
	v_mov_b64_e32 v[12:13], v[144:145]
	v_lshlrev_b32_e32 v20, 16, v10
	v_and_b32_e32 v21, 0xffff0000, v10
	v_pk_mul_f32 v[22:23], v[20:21], v[20:21]
	v_lshlrev_b32_e32 v10, 16, v11
	v_and_b32_e32 v11, 0xffff0000, v11
	v_pk_mul_f32 v[24:25], v[10:11], v[10:11]
	v_add_f32_e32 v1, v22, v23
	v_and_b32_e32 v14, 0xffff0000, v12
	v_lshlrev_b32_e32 v15, 16, v12
	v_add_f32_e32 v1, v24, v1
	v_pk_mul_f32 v[16:17], v[14:15], v[14:15]
	v_add_f32_e32 v1, v25, v1
	v_and_b32_e32 v12, 0xffff0000, v13
	v_lshlrev_b32_e32 v13, 16, v13
	v_add_f32_e32 v1, v17, v1
	v_pk_mul_f32 v[18:19], v[12:13], v[12:13]
	v_add_f32_e32 v1, v16, v1
	v_add_f32_e32 v1, v19, v1
	v_add_f32_e32 v1, v18, v1
	ds_bpermute_b32 v16, v87, v1
	v_mov_b32_e32 v23, v0
	v_mov_b32_e32 v24, v0
	v_mov_b32_e32 v25, v0
	s_waitcnt lgkmcnt(0)
	v_add_f32_e32 v1, v1, v16
	ds_bpermute_b32 v16, v88, v1
	s_waitcnt lgkmcnt(0)
	v_add_f32_e32 v1, v1, v16
	ds_bpermute_b32 v16, v89, v1
	s_waitcnt lgkmcnt(0)
	v_add_f32_e32 v1, v1, v16
	ds_bpermute_b32 v16, v90, v1
	s_waitcnt lgkmcnt(0)
	v_add_f32_e32 v1, v1, v16
	v_fmamk_f32 v1, v1, 0x3c000000, v222
	v_rsq_f32_e32 v16, v1
	s_nop 0
	v_mul_f32_e32 v17, v1, v16
	v_fma_f32 v17, -v17, v16, 1.0
	v_mul_f32_e32 v17, 0.5, v17
	v_fmac_f32_e32 v16, v17, v16
	s_mov_b32 s4, s30
	v_pk_mul_f32 v[18:19], v[16:17], v[20:21] op_sel_hi:[0,1]
	v_pk_mul_f32 v[6:7], v[6:7], v[18:19]
	v_add_u32_e32 v17, v107, v93
	v_cvt_pk_bf16_f32 v1, v6, v7
	v_pk_mul_f32 v[6:7], v[16:17], v[10:11] op_sel_hi:[0,1]
	v_pk_mul_f32 v[6:7], v[8:9], v[6:7]
	ds_write_b16 v17, v1 offset:34816
	ds_write_b16_d16_hi v17, v1 offset:35088
	v_cvt_pk_bf16_f32 v1, v6, v7
	v_pk_mul_f32 v[6:7], v[16:17], v[14:15] op_sel_hi:[0,1]
	v_add_u32_e32 v8, v107, v94
	v_pk_mul_f32 v[2:3], v[2:3], v[6:7] op_sel:[0,1] op_sel_hi:[1,0]
	ds_write_b16 v8, v1 offset:34816
	ds_write_b16_d16_hi v17, v1 offset:35632
	v_cvt_pk_bf16_f32 v1, v2, v3
	v_pk_mul_f32 v[2:3], v[16:17], v[12:13] op_sel_hi:[0,1]
	v_pk_mul_f32 v[2:3], v[4:5], v[2:3] op_sel:[0,1] op_sel_hi:[1,0]
	ds_write_b16 v8, v1 offset:35360
	ds_write_b16_d16_hi v17, v1 offset:36176
	v_cvt_pk_bf16_f32 v1, v2, v3
	ds_write_b16 v8, v1 offset:35904
	ds_write_b16_d16_hi v17, v1 offset:36720
	v_mov_b32_e32 v1, v0
	v_mov_b32_e32 v2, v0
	v_mov_b32_e32 v3, v0
	v_mov_b32_e32 v4, v0
	v_mov_b32_e32 v5, v0
	v_mov_b32_e32 v6, v0
	v_mov_b32_e32 v7, v0
	v_mov_b32_e32 v8, v0
	v_mov_b32_e32 v9, v0
	v_mov_b32_e32 v10, v0
	v_mov_b32_e32 v11, v0
	v_mov_b32_e32 v12, v0
	v_mov_b32_e32 v13, v0
	v_mov_b32_e32 v14, v0
	v_mov_b32_e32 v15, v0
	v_mov_b32_e32 v16, v0
	v_mov_b32_e32 v17, v0
	v_mov_b32_e32 v18, v0
	v_mov_b32_e32 v19, v0
	v_mov_b32_e32 v20, v0
	v_mov_b32_e32 v21, v0
	v_mov_b32_e32 v22, v0
	s_waitcnt lgkmcnt(0)
	s_barrier

; template <bool UPMAP = false>
; DI void transpose_item(const float* W, int K, int N, bf16_t* WT, const float* gain, LAS float* scr, int item, int lane) {
;     const int nblk = N / 32, kb = item / nblk, nb = item % nblk, k0 = 64 * kb, n0 = 32 * nb;
;     const int r0 = !UPMAP ? n0 : (n0 < DFF ? ((n0 >> 7) << 8) + (n0 & 127) : (((n0 - DFF) >> 7) << 8) + 128 + ((n0 - DFF) & 127));
; #pragma unroll
;     for (int i = 0; i < 32; ++i) { const int kk = 2 * i + (lane >> 5); float v = W[(size_t)(k0 + kk) * N + n0 + (lane & 31)]; if (gain) v *= gain[k0 + kk]; scr[kk * 33 + (lane & 31)] = v; }
.LBB0_2360:
	s_mul_hi_i32 s2, s34, 0x66666667
	s_lshr_b32 s3, s2, 31
	s_ashr_i32 s2, s2, 5
	s_add_i32 s2, s2, s3
	s_lshl_b32 s28, s2, 6
	s_mulk_i32 s2, 0xf600
	s_add_i32 s24, s31, s2
	s_ashr_i32 s25, s24, 31
	v_lshl_add_u64 v[4:5], s[24:25], 2, v[0:1]
	v_or_b32_e32 v6, s28, v10
	v_mad_i64_i32 v[8:9], s[2:3], v6, s65, v[4:5]
	v_mov_b32_e32 v102, 0x5000
	v_mov_b32_e32 v103, 0
	v_mov_b64_e32 v[100:101], v[8:9]
	v_lshl_add_u64 v[100:101], v[102:103], 0, v[100:101]
	global_load_dword v104, v[100:101], off
	v_lshl_add_u64 v[100:101], v[102:103], 0, v[100:101]
	global_load_dword v104, v[100:101], off
	v_lshl_add_u64 v[100:101], v[102:103], 0, v[100:101]
	global_load_dword v104, v[100:101], off
	v_lshl_add_u64 v[100:101], v[102:103], 0, v[100:101]
	global_load_dword v104, v[100:101], off
	v_lshl_add_u64 v[100:101], v[102:103], 0, v[100:101]
	global_load_dword v104, v[100:101], off
	v_lshl_add_u64 v[100:101], v[102:103], 0, v[100:101]
	global_load_dword v104, v[100:101], off
	v_lshl_add_u64 v[100:101], v[102:103], 0, v[100:101]
	global_load_dword v104, v[100:101], off
	v_lshl_add_u64 v[100:101], v[102:103], 0, v[100:101]
	global_load_dword v104, v[100:101], off
	v_lshl_add_u64 v[100:101], v[102:103], 0, v[100:101]
	global_load_dword v104, v[100:101], off
	v_lshl_add_u64 v[100:101], v[102:103], 0, v[100:101]
	global_load_dword v104, v[100:101], off
	v_lshl_add_u64 v[100:101], v[102:103], 0, v[100:101]
	global_load_dword v104, v[100:101], off
	v_lshl_add_u64 v[100:101], v[102:103], 0, v[100:101]
	global_load_dword v104, v[100:101], off
	v_lshl_add_u64 v[100:101], v[102:103], 0, v[100:101]
	global_load_dword v104, v[100:101], off
	v_lshl_add_u64 v[100:101], v[102:103], 0, v[100:101]
	global_load_dword v104, v[100:101], off
	v_lshl_add_u64 v[100:101], v[102:103], 0, v[100:101]
	global_load_dword v104, v[100:101], off
	v_lshl_add_u64 v[100:101], v[102:103], 0, v[100:101]
	global_load_dword v104, v[100:101], off
	v_lshl_add_u64 v[100:101], v[102:103], 0, v[100:101]
	global_load_dword v104, v[100:101], off
	v_lshl_add_u64 v[100:101], v[102:103], 0, v[100:101]
	global_load_dword v104, v[100:101], off
	v_lshl_add_u64 v[100:101], v[102:103], 0, v[100:101]
	global_load_dword v104, v[100:101], off
	v_lshl_add_u64 v[100:101], v[102:103], 0, v[100:101]
	global_load_dword v104, v[100:101], off
	v_lshl_add_u64 v[100:101], v[102:103], 0, v[100:101]
	global_load_dword v104, v[100:101], off
	v_lshl_add_u64 v[100:101], v[102:103], 0, v[100:101]
	global_load_dword v104, v[100:101], off
	v_lshl_add_u64 v[100:101], v[102:103], 0, v[100:101]
	global_load_dword v104, v[100:101], off
	v_lshl_add_u64 v[100:101], v[102:103], 0, v[100:101]
	global_load_dword v104, v[100:101], off
	v_lshl_add_u64 v[100:101], v[102:103], 0, v[100:101]
	global_load_dword v104, v[100:101], off
	v_lshl_add_u64 v[100:101], v[102:103], 0, v[100:101]
	global_load_dword v104, v[100:101], off
	v_lshl_add_u64 v[100:101], v[102:103], 0, v[100:101]
	global_load_dword v104, v[100:101], off
	v_lshl_add_u64 v[100:101], v[102:103], 0, v[100:101]
	global_load_dword v104, v[100:101], off
	v_lshl_add_u64 v[100:101], v[102:103], 0, v[100:101]
	global_load_dword v104, v[100:101], off
	v_lshl_add_u64 v[100:101], v[102:103], 0, v[100:101]
	global_load_dword v104, v[100:101], off
	v_lshl_add_u64 v[100:101], v[102:103], 0, v[100:101]
	global_load_dword v104, v[100:101], off
	global_load_dword v17, v[8:9], off
	v_ashrrev_i32_e32 v7, 31, v6
	v_cndmask_b32_e64 v8, 0, 1, s[14:15]
	v_cmp_ne_u32_e64 s[2:3], 1, v8
	s_andn2_b64 vcc, exec, s[14:15]
	v_lshl_add_u64 v[8:9], v[6:7], 2, s[10:11]
	s_cbranch_vccnz .LBB0_2362
	global_load_dword v7, v[8:9], off
	s_waitcnt vmcnt(0)
	v_mul_f32_e32 v17, v17, v7

; template <bool UPMAP = false>
; DI void transpose_item(const float* W, int K, int N, bf16_t* WT, const float* gain, LAS float* scr, int item, int lane) {
;     const int nblk = N / 32, kb = item / nblk, nb = item % nblk, k0 = 64 * kb, n0 = 32 * nb;
;     const int r0 = !UPMAP ? n0 : (n0 < DFF ? ((n0 >> 7) << 8) + (n0 & 127) : (((n0 - DFF) >> 7) << 8) + 128 + ((n0 - DFF) & 127));
; #pragma unroll
;     for (int i = 0; i < 32; ++i) { const int kk = 2 * i + (lane >> 5); float v = W[(size_t)(k0 + kk) * N + n0 + (lane & 31)]; if (gain) v *= gain[k0 + kk]; scr[kk * 33 + (lane & 31)] = v; }
;     asm volatile("s_waitcnt lgkmcnt(0)" ::: "memory");
; template <bool UPMAP = false>
; DI void convert_matrix(const float* W, int K, int N, bf16_t* WT, const float* gain, LAS float* scr, int gw, int ngw, int lane) {
;     ...
;     for (int it = gw; it < nitems; it += ngw) transpose_item<UPMAP>(W, K, N, WT, gain, scr, it, lane);
.LBB0_2426:
	s_ashr_i32 s0, s6, 31
	s_lshr_b32 s0, s0, 27
	s_add_i32 s0, s6, s0
	s_ashr_i32 s0, s0, 5
	s_lshl_b32 s2, s0, 6
	s_lshl_b32 s0, s0, 10
	s_sub_i32 s0, s4, s0
	v_or_b32_e32 v6, s2, v10
	s_ashr_i32 s1, s0, 31
	v_ashrrev_i32_e32 v7, 31, v6
	v_lshl_add_u64 v[4:5], s[0:1], 2, v[0:1]
	v_lshlrev_b64 v[12:13], 12, v[6:7]
	v_lshl_add_u64 v[12:13], v[4:5], 0, v[12:13]
	v_mov_b32_e32 v102, 0x2000
	v_mov_b32_e32 v103, 0
	v_mov_b64_e32 v[100:101], v[12:13]
	v_lshl_add_u64 v[100:101], v[102:103], 0, v[100:101]
	global_load_dword v104, v[100:101], off
	v_lshl_add_u64 v[100:101], v[102:103], 0, v[100:101]
	global_load_dword v104, v[100:101], off
	v_lshl_add_u64 v[100:101], v[102:103], 0, v[100:101]
	global_load_dword v104, v[100:101], off
	v_lshl_add_u64 v[100:101], v[102:103], 0, v[100:101]
	global_load_dword v104, v[100:101], off
	v_lshl_add_u64 v[100:101], v[102:103], 0, v[100:101]
	global_load_dword v104, v[100:101], off
	v_lshl_add_u64 v[100:101], v[102:103], 0, v[100:101]
	global_load_dword v104, v[100:101], off
	v_lshl_add_u64 v[100:101], v[102:103], 0, v[100:101]
	global_load_dword v104, v[100:101], off
	v_lshl_add_u64 v[100:101], v[102:103], 0, v[100:101]
	global_load_dword v104, v[100:101], off
	v_lshl_add_u64 v[100:101], v[102:103], 0, v[100:101]
	global_load_dword v104, v[100:101], off
	v_lshl_add_u64 v[100:101], v[102:103], 0, v[100:101]
	global_load_dword v104, v[100:101], off
	v_lshl_add_u64 v[100:101], v[102:103], 0, v[100:101]
	global_load_dword v104, v[100:101], off
	v_lshl_add_u64 v[100:101], v[102:103], 0, v[100:101]
	global_load_dword v104, v[100:101], off
	v_lshl_add_u64 v[100:101], v[102:103], 0, v[100:101]
	global_load_dword v104, v[100:101], off
	v_lshl_add_u64 v[100:101], v[102:103], 0, v[100:101]
	global_load_dword v104, v[100:101], off
	v_lshl_add_u64 v[100:101], v[102:103], 0, v[100:101]
	global_load_dword v104, v[100:101], off
	v_lshl_add_u64 v[100:101], v[102:103], 0, v[100:101]
	global_load_dword v104, v[100:101], off
	v_lshl_add_u64 v[100:101], v[102:103], 0, v[100:101]
	global_load_dword v104, v[100:101], off
	v_lshl_add_u64 v[100:101], v[102:103], 0, v[100:101]
	global_load_dword v104, v[100:101], off
	v_lshl_add_u64 v[100:101], v[102:103], 0, v[100:101]
	global_load_dword v104, v[100:101], off
	v_lshl_add_u64 v[100:101], v[102:103], 0, v[100:101]
	global_load_dword v104, v[100:101], off
	v_lshl_add_u64 v[100:101], v[102:103], 0, v[100:101]
	global_load_dword v104, v[100:101], off
	v_lshl_add_u64 v[100:101], v[102:103], 0, v[100:101]
	global_load_dword v104, v[100:101], off
	v_lshl_add_u64 v[100:101], v[102:103], 0, v[100:101]
	global_load_dword v104, v[100:101], off
	v_lshl_add_u64 v[100:101], v[102:103], 0, v[100:101]
	global_load_dword v104, v[100:101], off
	v_lshl_add_u64 v[100:101], v[102:103], 0, v[100:101]
	global_load_dword v104, v[100:101], off
	v_lshl_add_u64 v[100:101], v[102:103], 0, v[100:101]
	global_load_dword v104, v[100:101], off
	v_lshl_add_u64 v[100:101], v[102:103], 0, v[100:101]
	global_load_dword v104, v[100:101], off
	v_lshl_add_u64 v[100:101], v[102:103], 0, v[100:101]
	global_load_dword v104, v[100:101], off
	v_lshl_add_u64 v[100:101], v[102:103], 0, v[100:101]
	global_load_dword v104, v[100:101], off
	v_lshl_add_u64 v[100:101], v[102:103], 0, v[100:101]
	global_load_dword v104, v[100:101], off
	v_lshl_add_u64 v[100:101], v[102:103], 0, v[100:101]
	global_load_dword v104, v[100:101], off
	global_load_dword v7, v[12:13], off
	v_add_u32_e32 v12, 2, v6
	v_ashrrev_i32_e32 v13, 31, v12
	v_lshlrev_b64 v[12:13], 12, v[12:13]
	v_lshl_add_u64 v[12:13], v[4:5], 0, v[12:13]
	global_load_dword v12, v[12:13], off
	v_add_u32_e32 v14, 0x400, v9
	v_add_u32_e32 v30, s0, v11
	s_ashr_i32 s3, s2, 31
	v_ashrrev_i32_e32 v31, 31, v30
	v_lshlrev_b64 v[32:33], 11, v[30:31]
	s_add_i32 s6, s6, s79
	s_add_i32 s4, s4, s5
	s_cmpk_lt_i32 s6, 0x200
	s_waitcnt vmcnt(0)
	ds_write2_b32 v9, v7, v12 offset1:66
	v_or_b32_e32 v12, 4, v6
	v_ashrrev_i32_e32 v13, 31, v12
	v_lshlrev_b64 v[12:13], 12, v[12:13]
	v_lshl_add_u64 v[12:13], v[4:5], 0, v[12:13]
	global_load_dword v7, v[12:13], off
	v_add_u32_e32 v12, 6, v6
	v_ashrrev_i32_e32 v13, 31, v12
	v_lshlrev_b64 v[12:13], 12, v[12:13]
	v_lshl_add_u64 v[12:13], v[4:5], 0, v[12:13]
	global_load_dword v12, v[12:13], off
	s_waitcnt vmcnt(0)
	ds_write2_b32 v9, v7, v12 offset0:132 offset1:198
	v_or_b32_e32 v12, 8, v6
	v_ashrrev_i32_e32 v13, 31, v12
	v_lshlrev_b64 v[12:13], 12, v[12:13]
	v_lshl_add_u64 v[12:13], v[4:5], 0, v[12:13]
	global_load_dword v7, v[12:13], off
	v_add_u32_e32 v12, 10, v6
	v_ashrrev_i32_e32 v13, 31, v12
	v_lshlrev_b64 v[12:13], 12, v[12:13]
	v_lshl_add_u64 v[12:13], v[4:5], 0, v[12:13]
	global_load_dword v12, v[12:13], off
	s_waitcnt vmcnt(0)
	ds_write2_b32 v14, v7, v12 offset0:8 offset1:74
	v_or_b32_e32 v12, 12, v6
	v_ashrrev_i32_e32 v13, 31, v12
	v_lshlrev_b64 v[12:13], 12, v[12:13]
	v_lshl_add_u64 v[12:13], v[4:5], 0, v[12:13]
	global_load_dword v7, v[12:13], off
	v_add_u32_e32 v12, 14, v6
	v_ashrrev_i32_e32 v13, 31, v12
	v_lshlrev_b64 v[12:13], 12, v[12:13]
	v_lshl_add_u64 v[12:13], v[4:5], 0, v[12:13]
	global_load_dword v12, v[12:13], off
	s_waitcnt vmcnt(0)
	ds_write2_b32 v14, v7, v12 offset0:140 offset1:206
	v_or_b32_e32 v12, 16, v6
	v_ashrrev_i32_e32 v13, 31, v12
	v_lshlrev_b64 v[12:13], 12, v[12:13]
	v_lshl_add_u64 v[12:13], v[4:5], 0, v[12:13]
	global_load_dword v7, v[12:13], off
	v_add_u32_e32 v12, 18, v6
	v_ashrrev_i32_e32 v13, 31, v12
	v_lshlrev_b64 v[12:13], 12, v[12:13]
	v_lshl_add_u64 v[12:13], v[4:5], 0, v[12:13]
	global_load_dword v12, v[12:13], off
	v_add_u32_e32 v14, 0x800, v9
	s_waitcnt vmcnt(0)
; template <bool UPMAP = false>
; DI void transpose_item(const float* W, int K, int N, bf16_t* WT, const float* gain, LAS float* scr, int item, int lane) {
;     ...
; #pragma unroll
;     for (int i = 0; i < 32; ++i) { const int kk = 2 * i + (lane >> 5); float v = W[(size_t)(k0 + kk) * N + n0 + (lane & 31)]; if (gain) v *= gain[k0 + kk]; scr[kk * 33 + (lane & 31)] = v; }
	ds_write2_b32 v14, v7, v12 offset0:16 offset1:82
	v_or_b32_e32 v12, 20, v6
	v_ashrrev_i32_e32 v13, 31, v12
	v_lshlrev_b64 v[12:13], 12, v[12:13]
	v_lshl_add_u64 v[12:13], v[4:5], 0, v[12:13]
	global_load_dword v7, v[12:13], off
	v_add_u32_e32 v12, 22, v6
	v_ashrrev_i32_e32 v13, 31, v12
	v_lshlrev_b64 v[12:13], 12, v[12:13]
	v_lshl_add_u64 v[12:13], v[4:5], 0, v[12:13]
	global_load_dword v12, v[12:13], off
	s_waitcnt vmcnt(0)
	ds_write2_b32 v14, v7, v12 offset0:148 offset1:214
	v_or_b32_e32 v12, 24, v6
	v_ashrrev_i32_e32 v13, 31, v12
	v_lshlrev_b64 v[12:13], 12, v[12:13]
	v_lshl_add_u64 v[12:13], v[4:5], 0, v[12:13]
	global_load_dword v7, v[12:13], off
	v_add_u32_e32 v12, 26, v6
	v_ashrrev_i32_e32 v13, 31, v12
	v_lshlrev_b64 v[12:13], 12, v[12:13]
	v_lshl_add_u64 v[12:13], v[4:5], 0, v[12:13]
	global_load_dword v12, v[12:13], off
	v_add_u32_e32 v14, 0xc00, v9
	s_waitcnt vmcnt(0)
	ds_write2_b32 v14, v7, v12 offset0:24 offset1:90
	v_or_b32_e32 v12, 28, v6
	v_ashrrev_i32_e32 v13, 31, v12
	v_lshlrev_b64 v[12:13], 12, v[12:13]
	v_lshl_add_u64 v[12:13], v[4:5], 0, v[12:13]
	global_load_dword v7, v[12:13], off
	v_add_u32_e32 v12, 30, v6
	v_ashrrev_i32_e32 v13, 31, v12
	v_lshlrev_b64 v[12:13], 12, v[12:13]
	v_lshl_add_u64 v[12:13], v[4:5], 0, v[12:13]
	global_load_dword v12, v[12:13], off
	s_waitcnt vmcnt(0)
	ds_write2_b32 v14, v7, v12 offset0:156 offset1:222
	v_or_b32_e32 v12, 32, v6
	v_ashrrev_i32_e32 v13, 31, v12
	v_lshlrev_b64 v[12:13], 12, v[12:13]
	v_lshl_add_u64 v[12:13], v[4:5], 0, v[12:13]
	global_load_dword v7, v[12:13], off
	v_add_u32_e32 v12, 34, v6
	v_ashrrev_i32_e32 v13, 31, v12
	v_lshlrev_b64 v[12:13], 12, v[12:13]
	v_lshl_add_u64 v[12:13], v[4:5], 0, v[12:13]
	global_load_dword v12, v[12:13], off
	v_add_u32_e32 v14, 0x1000, v9
	s_waitcnt vmcnt(0)
	ds_write2_b32 v14, v7, v12 offset0:32 offset1:98
	v_or_b32_e32 v12, 36, v6
	v_ashrrev_i32_e32 v13, 31, v12
	v_lshlrev_b64 v[12:13], 12, v[12:13]
	v_lshl_add_u64 v[12:13], v[4:5], 0, v[12:13]
	global_load_dword v7, v[12:13], off
	v_add_u32_e32 v12, 38, v6
	v_ashrrev_i32_e32 v13, 31, v12
	v_lshlrev_b64 v[12:13], 12, v[12:13]
	v_lshl_add_u64 v[12:13], v[4:5], 0, v[12:13]
	global_load_dword v12, v[12:13], off
	s_waitcnt vmcnt(0)
	ds_write2_b32 v14, v7, v12 offset0:164 offset1:230
	v_or_b32_e32 v12, 40, v6
	v_ashrrev_i32_e32 v13, 31, v12
	v_lshlrev_b64 v[12:13], 12, v[12:13]
	v_lshl_add_u64 v[12:13], v[4:5], 0, v[12:13]
	global_load_dword v7, v[12:13], off
	v_add_u32_e32 v12, 42, v6
	v_ashrrev_i32_e32 v13, 31, v12
	v_lshlrev_b64 v[12:13], 12, v[12:13]
	v_lshl_add_u64 v[12:13], v[4:5], 0, v[12:13]
	global_load_dword v12, v[12:13], off
	v_add_u32_e32 v14, 0x1400, v9
	s_waitcnt vmcnt(0)
	ds_write2_b32 v14, v7, v12 offset0:40 offset1:106
	v_or_b32_e32 v12, 44, v6
	v_ashrrev_i32_e32 v13, 31, v12
	v_lshlrev_b64 v[12:13], 12, v[12:13]
	v_lshl_add_u64 v[12:13], v[4:5], 0, v[12:13]
	global_load_dword v7, v[12:13], off
	v_add_u32_e32 v12, 46, v6
	v_ashrrev_i32_e32 v13, 31, v12
	v_lshlrev_b64 v[12:13], 12, v[12:13]
	v_lshl_add_u64 v[12:13], v[4:5], 0, v[12:13]
	global_load_dword v12, v[12:13], off
	s_waitcnt vmcnt(0)
	ds_write2_b32 v14, v7, v12 offset0:172 offset1:238
	v_or_b32_e32 v12, 48, v6
	v_ashrrev_i32_e32 v13, 31, v12
	v_lshlrev_b64 v[12:13], 12, v[12:13]
	v_lshl_add_u64 v[12:13], v[4:5], 0, v[12:13]
	global_load_dword v7, v[12:13], off
	v_add_u32_e32 v12, 50, v6
	v_ashrrev_i32_e32 v13, 31, v12
	v_lshlrev_b64 v[12:13], 12, v[12:13]
	v_lshl_add_u64 v[12:13], v[4:5], 0, v[12:13]
	global_load_dword v12, v[12:13], off
	v_add_u32_e32 v14, 0x1800, v9
	s_waitcnt vmcnt(0)
; #define LAS __attribute__((address_space(3)))
; DI unsigned pk2(float lo, float hi) { f32x2 v = {lo, hi}; bf16x2_t b = __builtin_convertvector(v, bf16x2_t); return __builtin_bit_cast(unsigned, b); }
; template <bool UPMAP = false>
; DI void transpose_item(const float* W, int K, int N, bf16_t* WT, const float* gain, LAS float* scr, int item, int lane) {
;     ...
;     for (int i = 0; i < 32; ++i) { const int kk = 2 * i + (lane >> 5); float v = W[(size_t)(k0 + kk) * N + n0 + (lane & 31)]; if (gain) v *= gain[k0 + kk]; scr[kk * 33 + (lane & 31)] = v; }
;     asm volatile("s_waitcnt lgkmcnt(0)" ::: "memory");
;     const int c = lane & 7;
; #pragma unroll
;     for (int j = 0; j < 4; ++j) { const int n = (lane >> 3) + 8 * j; const LAS float* s = scr + (8 * c) * 33 + n;
;         u32x4 o; o.x = pk2(s[0 * 33], s[1 * 33]); o.y = pk2(s[2 * 33], s[3 * 33]); o.z = pk2(s[4 * 33], s[5 * 33]); o.w = pk2(s[6 * 33], s[7 * 33]);
;         *(u32x4*)(WT + (size_t)(r0 + n) * K + k0 + 8 * c) = o; }
;     asm volatile("s_waitcnt lgkmcnt(0)" ::: "memory");
; }
	ds_write2_b32 v14, v7, v12 offset0:48 offset1:114
	v_or_b32_e32 v12, 52, v6
	v_ashrrev_i32_e32 v13, 31, v12
	v_lshlrev_b64 v[12:13], 12, v[12:13]
	v_lshl_add_u64 v[12:13], v[4:5], 0, v[12:13]
	global_load_dword v7, v[12:13], off
	v_add_u32_e32 v12, 54, v6
	v_ashrrev_i32_e32 v13, 31, v12
	v_lshlrev_b64 v[12:13], 12, v[12:13]
	v_lshl_add_u64 v[12:13], v[4:5], 0, v[12:13]
	global_load_dword v12, v[12:13], off
	s_waitcnt vmcnt(0)
	ds_write2_b32 v14, v7, v12 offset0:180 offset1:246
	v_or_b32_e32 v12, 56, v6
	v_ashrrev_i32_e32 v13, 31, v12
	v_lshlrev_b64 v[12:13], 12, v[12:13]
	v_lshl_add_u64 v[12:13], v[4:5], 0, v[12:13]
	global_load_dword v7, v[12:13], off
	v_add_u32_e32 v12, 58, v6
	v_ashrrev_i32_e32 v13, 31, v12
	v_lshlrev_b64 v[12:13], 12, v[12:13]
	v_lshl_add_u64 v[12:13], v[4:5], 0, v[12:13]
	global_load_dword v13, v[12:13], off
	v_add_u32_e32 v12, 0x1c00, v9
	v_or_b32_e32 v14, 60, v6
	v_add_u32_e32 v6, 62, v6
	v_ashrrev_i32_e32 v15, 31, v14
	v_lshlrev_b64 v[14:15], 12, v[14:15]
	v_lshl_add_u64 v[14:15], v[4:5], 0, v[14:15]
	s_waitcnt vmcnt(0)
	ds_write2_b32 v12, v7, v13 offset0:56 offset1:122
	v_ashrrev_i32_e32 v7, 31, v6
	v_lshlrev_b64 v[6:7], 12, v[6:7]
	v_lshl_add_u64 v[4:5], v[4:5], 0, v[6:7]
	global_load_dword v13, v[14:15], off
	s_nop 0
	global_load_dword v4, v[4:5], off
	s_waitcnt vmcnt(0)
	ds_write2_b32 v12, v13, v4 offset0:188 offset1:254
	s_waitcnt lgkmcnt(0)
	ds_read2_b32 v[14:15], v8 offset0:33 offset1:41
	ds_read2_b32 v[16:17], v8 offset1:8
	ds_read2_b32 v[18:19], v8 offset0:66 offset1:74
	ds_read2_b32 v[20:21], v8 offset0:99 offset1:107
	ds_read2_b32 v[22:23], v8 offset0:132 offset1:140
	ds_read2_b32 v[24:25], v8 offset0:165 offset1:173
	ds_read2_b32 v[26:27], v8 offset0:198 offset1:206
	ds_read2_b32 v[28:29], v8 offset0:231 offset1:239
	v_lshl_add_u64 v[12:13], s[2:3], 1, v[2:3]
	s_waitcnt lgkmcnt(6)
	v_cvt_pk_bf16_f32 v4, v16, v14
	s_waitcnt lgkmcnt(4)
	v_cvt_pk_bf16_f32 v5, v18, v20
	s_waitcnt lgkmcnt(2)
	v_cvt_pk_bf16_f32 v6, v22, v24
	s_waitcnt lgkmcnt(0)
	v_cvt_pk_bf16_f32 v7, v26, v28
	v_lshl_add_u64 v[32:33], v[12:13], 0, v[32:33]
	v_add_u32_e32 v14, 8, v30
	global_store_dwordx4 v[32:33], v[4:7], off
	v_add_u32_e32 v32, 16, v30
	v_ashrrev_i32_e32 v33, 31, v32
	v_cvt_pk_bf16_f32 v4, v17, v15
	v_ashrrev_i32_e32 v15, 31, v14
	v_lshlrev_b64 v[14:15], 11, v[14:15]
	v_cvt_pk_bf16_f32 v5, v19, v21
	v_cvt_pk_bf16_f32 v6, v23, v25
	v_cvt_pk_bf16_f32 v7, v27, v29
	v_lshl_add_u64 v[14:15], v[12:13], 0, v[14:15]
	global_store_dwordx4 v[14:15], v[4:7], off
	ds_read2_b32 v[14:15], v8 offset0:49 offset1:57
	ds_read2_b32 v[16:17], v8 offset0:16 offset1:24
	ds_read2_b32 v[18:19], v8 offset0:82 offset1:90
	ds_read2_b32 v[20:21], v8 offset0:115 offset1:123
	ds_read2_b32 v[22:23], v8 offset0:148 offset1:156
	ds_read2_b32 v[24:25], v8 offset0:181 offset1:189
	ds_read2_b32 v[26:27], v8 offset0:214 offset1:222
	ds_read2_b32 v[28:29], v8 offset0:247 offset1:255
	v_lshlrev_b64 v[32:33], 11, v[32:33]
	s_waitcnt lgkmcnt(6)
	v_cvt_pk_bf16_f32 v4, v16, v14
	s_waitcnt lgkmcnt(4)
	v_cvt_pk_bf16_f32 v5, v18, v20
	s_waitcnt lgkmcnt(2)
	v_cvt_pk_bf16_f32 v6, v22, v24
	s_waitcnt lgkmcnt(0)
	v_cvt_pk_bf16_f32 v7, v26, v28
	v_lshl_add_u64 v[32:33], v[12:13], 0, v[32:33]
	v_add_u32_e32 v14, 24, v30
	global_store_dwordx4 v[32:33], v[4:7], off
	s_nop 1
	v_cvt_pk_bf16_f32 v4, v17, v15
	v_ashrrev_i32_e32 v15, 31, v14
	v_lshlrev_b64 v[14:15], 11, v[14:15]
	v_cvt_pk_bf16_f32 v5, v19, v21
	v_cvt_pk_bf16_f32 v6, v23, v25
	v_cvt_pk_bf16_f32 v7, v27, v29
	v_lshl_add_u64 v[12:13], v[12:13], 0, v[14:15]
	global_store_dwordx4 v[12:13], v[4:7], off
	s_waitcnt lgkmcnt(0)
	s_cbranch_scc1 .LBB0_2426

; template <bool UPMAP = false>
; DI void transpose_item(const float* W, int K, int N, bf16_t* WT, const float* gain, LAS float* scr, int item, int lane) {
;     const int nblk = N / 32, kb = item / nblk, nb = item % nblk, k0 = 64 * kb, n0 = 32 * nb;
;     const int r0 = !UPMAP ? n0 : (n0 < DFF ? ((n0 >> 7) << 8) + (n0 & 127) : (((n0 - DFF) >> 7) << 8) + 128 + ((n0 - DFF) & 127));
; #pragma unroll
;     for (int i = 0; i < 32; ++i) { const int kk = 2 * i + (lane >> 5); float v = W[(size_t)(k0 + kk) * N + n0 + (lane & 31)]; if (gain) v *= gain[k0 + kk]; scr[kk * 33 + (lane & 31)] = v; }
.LBB0_2527:
	s_ashr_i32 s2, s34, 31
	s_lshr_b32 s2, s2, 27
	s_add_i32 s2, s34, s2
	s_ashr_i32 s2, s2, 5
	s_lshl_b32 s28, s2, 6
	s_lshl_b32 s29, s2, 10
	s_sub_i32 s2, s31, s29
	v_or_b32_e32 v8, s28, v10
	s_ashr_i32 s3, s2, 31
	v_ashrrev_i32_e32 v9, 31, v8
	v_lshl_add_u64 v[4:5], s[2:3], 2, v[0:1]
	v_lshlrev_b64 v[6:7], 12, v[8:9]
	v_lshl_add_u64 v[6:7], v[4:5], 0, v[6:7]
	v_mov_b32_e32 v102, 0x2000
	v_mov_b32_e32 v103, 0
	v_mov_b64_e32 v[100:101], v[6:7]
	v_lshl_add_u64 v[100:101], v[102:103], 0, v[100:101]
	global_load_dword v104, v[100:101], off
	v_lshl_add_u64 v[100:101], v[102:103], 0, v[100:101]
	global_load_dword v104, v[100:101], off
	v_lshl_add_u64 v[100:101], v[102:103], 0, v[100:101]
	global_load_dword v104, v[100:101], off
	v_lshl_add_u64 v[100:101], v[102:103], 0, v[100:101]
	global_load_dword v104, v[100:101], off
	v_lshl_add_u64 v[100:101], v[102:103], 0, v[100:101]
	global_load_dword v104, v[100:101], off
	v_lshl_add_u64 v[100:101], v[102:103], 0, v[100:101]
	global_load_dword v104, v[100:101], off
	v_lshl_add_u64 v[100:101], v[102:103], 0, v[100:101]
	global_load_dword v104, v[100:101], off
	v_lshl_add_u64 v[100:101], v[102:103], 0, v[100:101]
	global_load_dword v104, v[100:101], off
	v_lshl_add_u64 v[100:101], v[102:103], 0, v[100:101]
	global_load_dword v104, v[100:101], off
	v_lshl_add_u64 v[100:101], v[102:103], 0, v[100:101]
	global_load_dword v104, v[100:101], off
	v_lshl_add_u64 v[100:101], v[102:103], 0, v[100:101]
	global_load_dword v104, v[100:101], off
	v_lshl_add_u64 v[100:101], v[102:103], 0, v[100:101]
	global_load_dword v104, v[100:101], off
	v_lshl_add_u64 v[100:101], v[102:103], 0, v[100:101]
	global_load_dword v104, v[100:101], off
	v_lshl_add_u64 v[100:101], v[102:103], 0, v[100:101]
	global_load_dword v104, v[100:101], off
	v_lshl_add_u64 v[100:101], v[102:103], 0, v[100:101]
	global_load_dword v104, v[100:101], off
	v_lshl_add_u64 v[100:101], v[102:103], 0, v[100:101]
	global_load_dword v104, v[100:101], off
	v_lshl_add_u64 v[100:101], v[102:103], 0, v[100:101]
	global_load_dword v104, v[100:101], off
	v_lshl_add_u64 v[100:101], v[102:103], 0, v[100:101]
	global_load_dword v104, v[100:101], off
	v_lshl_add_u64 v[100:101], v[102:103], 0, v[100:101]
	global_load_dword v104, v[100:101], off
	v_lshl_add_u64 v[100:101], v[102:103], 0, v[100:101]
	global_load_dword v104, v[100:101], off
	v_lshl_add_u64 v[100:101], v[102:103], 0, v[100:101]
	global_load_dword v104, v[100:101], off
	v_lshl_add_u64 v[100:101], v[102:103], 0, v[100:101]
	global_load_dword v104, v[100:101], off
	v_lshl_add_u64 v[100:101], v[102:103], 0, v[100:101]
	global_load_dword v104, v[100:101], off
	v_lshl_add_u64 v[100:101], v[102:103], 0, v[100:101]
	global_load_dword v104, v[100:101], off
	v_lshl_add_u64 v[100:101], v[102:103], 0, v[100:101]
	global_load_dword v104, v[100:101], off
	v_lshl_add_u64 v[100:101], v[102:103], 0, v[100:101]
	global_load_dword v104, v[100:101], off
	v_lshl_add_u64 v[100:101], v[102:103], 0, v[100:101]
	global_load_dword v104, v[100:101], off
	v_lshl_add_u64 v[100:101], v[102:103], 0, v[100:101]
	global_load_dword v104, v[100:101], off
	v_lshl_add_u64 v[100:101], v[102:103], 0, v[100:101]
	global_load_dword v104, v[100:101], off
	v_lshl_add_u64 v[100:101], v[102:103], 0, v[100:101]
	global_load_dword v104, v[100:101], off
	v_lshl_add_u64 v[100:101], v[102:103], 0, v[100:101]
	global_load_dword v104, v[100:101], off
	global_load_dword v17, v[6:7], off
	v_cndmask_b32_e64 v6, 0, 1, s[24:25]
	v_cmp_ne_u32_e64 s[2:3], 1, v6
	s_andn2_b64 vcc, exec, s[24:25]
	v_lshl_add_u64 v[6:7], v[8:9], 2, s[14:15]
	s_cbranch_vccnz .LBB0_2529
	global_load_dword v9, v[6:7], off
	s_waitcnt vmcnt(0)
	v_mul_f32_e32 v17, v17, v9

; template <bool UPMAP = false>
; DI void transpose_item(const float* W, int K, int N, bf16_t* WT, const float* gain, LAS float* scr, int item, int lane) {
;     const int nblk = N / 32, kb = item / nblk, nb = item % nblk, k0 = 64 * kb, n0 = 32 * nb;
;     const int r0 = !UPMAP ? n0 : (n0 < DFF ? ((n0 >> 7) << 8) + (n0 & 127) : (((n0 - DFF) >> 7) << 8) + 128 + ((n0 - DFF) & 127));
; #pragma unroll
;     for (int i = 0; i < 32; ++i) { const int kk = 2 * i + (lane >> 5); float v = W[(size_t)(k0 + kk) * N + n0 + (lane & 31)]; if (gain) v *= gain[k0 + kk]; scr[kk * 33 + (lane & 31)] = v; }
.LBB0_2594:
	s_ashr_i32 s24, s31, 31
	s_lshr_b32 s24, s24, 27
	s_add_i32 s24, s31, s24
	s_ashr_i32 s25, s24, 5
	s_lshl_b32 s24, s25, 6
	s_lshl_b32 s25, s25, 10
	s_sub_i32 s34, s28, s25
	v_or_b32_e32 v8, s24, v10
	s_ashr_i32 s35, s34, 31
	v_ashrrev_i32_e32 v9, 31, v8
	v_lshl_add_u64 v[4:5], s[34:35], 2, v[0:1]
	v_lshlrev_b64 v[6:7], 12, v[8:9]
	v_lshl_add_u64 v[6:7], v[4:5], 0, v[6:7]
	v_mov_b32_e32 v102, 0x2000
	v_mov_b32_e32 v103, 0
	v_mov_b64_e32 v[100:101], v[6:7]
	v_lshl_add_u64 v[100:101], v[102:103], 0, v[100:101]
	global_load_dword v104, v[100:101], off
	v_lshl_add_u64 v[100:101], v[102:103], 0, v[100:101]
	global_load_dword v104, v[100:101], off
	v_lshl_add_u64 v[100:101], v[102:103], 0, v[100:101]
	global_load_dword v104, v[100:101], off
	v_lshl_add_u64 v[100:101], v[102:103], 0, v[100:101]
	global_load_dword v104, v[100:101], off
	v_lshl_add_u64 v[100:101], v[102:103], 0, v[100:101]
	global_load_dword v104, v[100:101], off
	v_lshl_add_u64 v[100:101], v[102:103], 0, v[100:101]
	global_load_dword v104, v[100:101], off
	v_lshl_add_u64 v[100:101], v[102:103], 0, v[100:101]
	global_load_dword v104, v[100:101], off
	v_lshl_add_u64 v[100:101], v[102:103], 0, v[100:101]
	global_load_dword v104, v[100:101], off
	v_lshl_add_u64 v[100:101], v[102:103], 0, v[100:101]
	global_load_dword v104, v[100:101], off
	v_lshl_add_u64 v[100:101], v[102:103], 0, v[100:101]
	global_load_dword v104, v[100:101], off
	v_lshl_add_u64 v[100:101], v[102:103], 0, v[100:101]
	global_load_dword v104, v[100:101], off
	v_lshl_add_u64 v[100:101], v[102:103], 0, v[100:101]
	global_load_dword v104, v[100:101], off
	v_lshl_add_u64 v[100:101], v[102:103], 0, v[100:101]
	global_load_dword v104, v[100:101], off
	v_lshl_add_u64 v[100:101], v[102:103], 0, v[100:101]
	global_load_dword v104, v[100:101], off
	v_lshl_add_u64 v[100:101], v[102:103], 0, v[100:101]
	global_load_dword v104, v[100:101], off
	v_lshl_add_u64 v[100:101], v[102:103], 0, v[100:101]
	global_load_dword v104, v[100:101], off
	v_lshl_add_u64 v[100:101], v[102:103], 0, v[100:101]
	global_load_dword v104, v[100:101], off
	v_lshl_add_u64 v[100:101], v[102:103], 0, v[100:101]
	global_load_dword v104, v[100:101], off
	v_lshl_add_u64 v[100:101], v[102:103], 0, v[100:101]
	global_load_dword v104, v[100:101], off
	v_lshl_add_u64 v[100:101], v[102:103], 0, v[100:101]
	global_load_dword v104, v[100:101], off
	v_lshl_add_u64 v[100:101], v[102:103], 0, v[100:101]
	global_load_dword v104, v[100:101], off
	v_lshl_add_u64 v[100:101], v[102:103], 0, v[100:101]
	global_load_dword v104, v[100:101], off
	v_lshl_add_u64 v[100:101], v[102:103], 0, v[100:101]
	global_load_dword v104, v[100:101], off
	v_lshl_add_u64 v[100:101], v[102:103], 0, v[100:101]
	global_load_dword v104, v[100:101], off
	v_lshl_add_u64 v[100:101], v[102:103], 0, v[100:101]
	global_load_dword v104, v[100:101], off
	v_lshl_add_u64 v[100:101], v[102:103], 0, v[100:101]
	global_load_dword v104, v[100:101], off
	v_lshl_add_u64 v[100:101], v[102:103], 0, v[100:101]
	global_load_dword v104, v[100:101], off
	v_lshl_add_u64 v[100:101], v[102:103], 0, v[100:101]
	global_load_dword v104, v[100:101], off
	v_lshl_add_u64 v[100:101], v[102:103], 0, v[100:101]
	global_load_dword v104, v[100:101], off
	v_lshl_add_u64 v[100:101], v[102:103], 0, v[100:101]
	global_load_dword v104, v[100:101], off
	v_lshl_add_u64 v[100:101], v[102:103], 0, v[100:101]
	global_load_dword v104, v[100:101], off
	global_load_dword v17, v[6:7], off
	v_cndmask_b32_e64 v6, 0, 1, s[14:15]
	v_cmp_ne_u32_e64 s[40:41], 1, v6
	s_andn2_b64 vcc, exec, s[14:15]
	v_lshl_add_u64 v[6:7], v[8:9], 2, s[10:11]
	s_cbranch_vccnz .LBB0_2596
	global_load_dword v9, v[6:7], off
	s_waitcnt vmcnt(0)
	v_mul_f32_e32 v17, v17, v9

; template <bool UPMAP = false>
; DI void transpose_item(const float* W, int K, int N, bf16_t* WT, const float* gain, LAS float* scr, int item, int lane) {
;     const int nblk = N / 32, kb = item / nblk, nb = item % nblk, k0 = 64 * kb, n0 = 32 * nb;
;     const int r0 = !UPMAP ? n0 : (n0 < DFF ? ((n0 >> 7) << 8) + (n0 & 127) : (((n0 - DFF) >> 7) << 8) + 128 + ((n0 - DFF) & 127));
; #pragma unroll
;     for (int i = 0; i < 32; ++i) { const int kk = 2 * i + (lane >> 5); float v = W[(size_t)(k0 + kk) * N + n0 + (lane & 31)]; if (gain) v *= gain[k0 + kk]; scr[kk * 33 + (lane & 31)] = v; }
.LBB0_2661:
	s_ashr_i32 s14, s28, 31
	s_lshr_b32 s14, s14, 27
	s_add_i32 s14, s28, s14
	s_ashr_i32 s15, s14, 5
	s_lshl_b32 s14, s15, 6
	s_lshl_b32 s15, s15, 10
	s_sub_i32 s34, s24, s15
	v_or_b32_e32 v8, s14, v10
	s_ashr_i32 s35, s34, 31
	v_ashrrev_i32_e32 v9, 31, v8
	v_lshl_add_u64 v[4:5], s[34:35], 2, v[0:1]
	v_lshlrev_b64 v[6:7], 12, v[8:9]
	v_lshl_add_u64 v[6:7], v[4:5], 0, v[6:7]
	v_mov_b32_e32 v102, 0x2000
	v_mov_b32_e32 v103, 0
	v_mov_b64_e32 v[100:101], v[6:7]
	v_lshl_add_u64 v[100:101], v[102:103], 0, v[100:101]
	global_load_dword v104, v[100:101], off
	v_lshl_add_u64 v[100:101], v[102:103], 0, v[100:101]
	global_load_dword v104, v[100:101], off
	v_lshl_add_u64 v[100:101], v[102:103], 0, v[100:101]
	global_load_dword v104, v[100:101], off
	v_lshl_add_u64 v[100:101], v[102:103], 0, v[100:101]
	global_load_dword v104, v[100:101], off
	v_lshl_add_u64 v[100:101], v[102:103], 0, v[100:101]
	global_load_dword v104, v[100:101], off
	v_lshl_add_u64 v[100:101], v[102:103], 0, v[100:101]
	global_load_dword v104, v[100:101], off
	v_lshl_add_u64 v[100:101], v[102:103], 0, v[100:101]
	global_load_dword v104, v[100:101], off
	v_lshl_add_u64 v[100:101], v[102:103], 0, v[100:101]
	global_load_dword v104, v[100:101], off
	v_lshl_add_u64 v[100:101], v[102:103], 0, v[100:101]
	global_load_dword v104, v[100:101], off
	v_lshl_add_u64 v[100:101], v[102:103], 0, v[100:101]
	global_load_dword v104, v[100:101], off
	v_lshl_add_u64 v[100:101], v[102:103], 0, v[100:101]
	global_load_dword v104, v[100:101], off
	v_lshl_add_u64 v[100:101], v[102:103], 0, v[100:101]
	global_load_dword v104, v[100:101], off
	v_lshl_add_u64 v[100:101], v[102:103], 0, v[100:101]
	global_load_dword v104, v[100:101], off
	v_lshl_add_u64 v[100:101], v[102:103], 0, v[100:101]
	global_load_dword v104, v[100:101], off
	v_lshl_add_u64 v[100:101], v[102:103], 0, v[100:101]
	global_load_dword v104, v[100:101], off
	v_lshl_add_u64 v[100:101], v[102:103], 0, v[100:101]
	global_load_dword v104, v[100:101], off
	v_lshl_add_u64 v[100:101], v[102:103], 0, v[100:101]
	global_load_dword v104, v[100:101], off
	v_lshl_add_u64 v[100:101], v[102:103], 0, v[100:101]
	global_load_dword v104, v[100:101], off
	v_lshl_add_u64 v[100:101], v[102:103], 0, v[100:101]
	global_load_dword v104, v[100:101], off
	v_lshl_add_u64 v[100:101], v[102:103], 0, v[100:101]
	global_load_dword v104, v[100:101], off
	v_lshl_add_u64 v[100:101], v[102:103], 0, v[100:101]
	global_load_dword v104, v[100:101], off
	v_lshl_add_u64 v[100:101], v[102:103], 0, v[100:101]
	global_load_dword v104, v[100:101], off
	v_lshl_add_u64 v[100:101], v[102:103], 0, v[100:101]
	global_load_dword v104, v[100:101], off
	v_lshl_add_u64 v[100:101], v[102:103], 0, v[100:101]
	global_load_dword v104, v[100:101], off
	v_lshl_add_u64 v[100:101], v[102:103], 0, v[100:101]
	global_load_dword v104, v[100:101], off
	v_lshl_add_u64 v[100:101], v[102:103], 0, v[100:101]
	global_load_dword v104, v[100:101], off
	v_lshl_add_u64 v[100:101], v[102:103], 0, v[100:101]
	global_load_dword v104, v[100:101], off
	v_lshl_add_u64 v[100:101], v[102:103], 0, v[100:101]
	global_load_dword v104, v[100:101], off
	v_lshl_add_u64 v[100:101], v[102:103], 0, v[100:101]
	global_load_dword v104, v[100:101], off
	v_lshl_add_u64 v[100:101], v[102:103], 0, v[100:101]
	global_load_dword v104, v[100:101], off
	v_lshl_add_u64 v[100:101], v[102:103], 0, v[100:101]
	global_load_dword v104, v[100:101], off
	global_load_dword v17, v[6:7], off
	v_cndmask_b32_e64 v6, 0, 1, s[10:11]
	v_cmp_ne_u32_e64 s[40:41], 1, v6
	s_andn2_b64 vcc, exec, s[10:11]
	v_lshl_add_u64 v[6:7], v[8:9], 2, s[8:9]
	s_cbranch_vccnz .LBB0_2663
	global_load_dword v9, v[6:7], off
	s_waitcnt vmcnt(0)
	v_mul_f32_e32 v17, v17, v9

; template <bool UPMAP = false>
; DI void transpose_item(const float* W, int K, int N, bf16_t* WT, const float* gain, LAS float* scr, int item, int lane) {
;     const int nblk = N / 32, kb = item / nblk, nb = item % nblk, k0 = 64 * kb, n0 = 32 * nb;
;     const int r0 = !UPMAP ? n0 : (n0 < DFF ? ((n0 >> 7) << 8) + (n0 & 127) : (((n0 - DFF) >> 7) << 8) + 128 + ((n0 - DFF) & 127));
; #pragma unroll
;     for (int i = 0; i < 32; ++i) { const int kk = 2 * i + (lane >> 5); float v = W[(size_t)(k0 + kk) * N + n0 + (lane & 31)]; if (gain) v *= gain[k0 + kk]; scr[kk * 33 + (lane & 31)] = v; }
.LBB0_2947:
	s_mul_hi_i32 s2, s33, 0x2e8ba2e9
	s_lshr_b32 s3, s2, 31
	s_ashr_i32 s11, s2, 5
	s_add_i32 s11, s11, s3
	s_mul_i32 s2, s11, 0xffffea00
	s_add_i32 s14, s28, s2
	s_lshl_b32 s10, s11, 6
	s_ashr_i32 s15, s14, 31
	v_lshl_add_u64 v[4:5], s[14:15], 2, v[0:1]
	v_or_b32_e32 v6, s10, v10
	s_movk_i32 s15, 0x5800
	v_mad_i64_i32 v[8:9], s[2:3], v6, s15, v[4:5]
	v_mov_b32_e32 v102, 0xb000
	v_mov_b32_e32 v103, 0
	v_mov_b64_e32 v[100:101], v[8:9]
	v_lshl_add_u64 v[100:101], v[102:103], 0, v[100:101]
	global_load_dword v104, v[100:101], off
	v_lshl_add_u64 v[100:101], v[102:103], 0, v[100:101]
	global_load_dword v104, v[100:101], off
	v_lshl_add_u64 v[100:101], v[102:103], 0, v[100:101]
	global_load_dword v104, v[100:101], off
	v_lshl_add_u64 v[100:101], v[102:103], 0, v[100:101]
	global_load_dword v104, v[100:101], off
	v_lshl_add_u64 v[100:101], v[102:103], 0, v[100:101]
	global_load_dword v104, v[100:101], off
	v_lshl_add_u64 v[100:101], v[102:103], 0, v[100:101]
	global_load_dword v104, v[100:101], off
	v_lshl_add_u64 v[100:101], v[102:103], 0, v[100:101]
	global_load_dword v104, v[100:101], off
	v_lshl_add_u64 v[100:101], v[102:103], 0, v[100:101]
	global_load_dword v104, v[100:101], off
	v_lshl_add_u64 v[100:101], v[102:103], 0, v[100:101]
	global_load_dword v104, v[100:101], off
	v_lshl_add_u64 v[100:101], v[102:103], 0, v[100:101]
	global_load_dword v104, v[100:101], off
	v_lshl_add_u64 v[100:101], v[102:103], 0, v[100:101]
	global_load_dword v104, v[100:101], off
	v_lshl_add_u64 v[100:101], v[102:103], 0, v[100:101]
	global_load_dword v104, v[100:101], off
	v_lshl_add_u64 v[100:101], v[102:103], 0, v[100:101]
	global_load_dword v104, v[100:101], off
	v_lshl_add_u64 v[100:101], v[102:103], 0, v[100:101]
	global_load_dword v104, v[100:101], off
	v_lshl_add_u64 v[100:101], v[102:103], 0, v[100:101]
	global_load_dword v104, v[100:101], off
	v_lshl_add_u64 v[100:101], v[102:103], 0, v[100:101]
	global_load_dword v104, v[100:101], off
	v_lshl_add_u64 v[100:101], v[102:103], 0, v[100:101]
	global_load_dword v104, v[100:101], off
	v_lshl_add_u64 v[100:101], v[102:103], 0, v[100:101]
	global_load_dword v104, v[100:101], off
	v_lshl_add_u64 v[100:101], v[102:103], 0, v[100:101]
	global_load_dword v104, v[100:101], off
	v_lshl_add_u64 v[100:101], v[102:103], 0, v[100:101]
	global_load_dword v104, v[100:101], off
	v_lshl_add_u64 v[100:101], v[102:103], 0, v[100:101]
	global_load_dword v104, v[100:101], off
	v_lshl_add_u64 v[100:101], v[102:103], 0, v[100:101]
	global_load_dword v104, v[100:101], off
	v_lshl_add_u64 v[100:101], v[102:103], 0, v[100:101]
	global_load_dword v104, v[100:101], off
	v_lshl_add_u64 v[100:101], v[102:103], 0, v[100:101]
	global_load_dword v104, v[100:101], off
	v_lshl_add_u64 v[100:101], v[102:103], 0, v[100:101]
	global_load_dword v104, v[100:101], off
	v_lshl_add_u64 v[100:101], v[102:103], 0, v[100:101]
	global_load_dword v104, v[100:101], off
	v_lshl_add_u64 v[100:101], v[102:103], 0, v[100:101]
	global_load_dword v104, v[100:101], off
	v_lshl_add_u64 v[100:101], v[102:103], 0, v[100:101]
	global_load_dword v104, v[100:101], off
	v_lshl_add_u64 v[100:101], v[102:103], 0, v[100:101]
	global_load_dword v104, v[100:101], off
	v_lshl_add_u64 v[100:101], v[102:103], 0, v[100:101]
	global_load_dword v104, v[100:101], off
	v_lshl_add_u64 v[100:101], v[102:103], 0, v[100:101]
	global_load_dword v104, v[100:101], off
	global_load_dword v17, v[8:9], off
	v_ashrrev_i32_e32 v7, 31, v6
	v_cndmask_b32_e64 v8, 0, 1, s[8:9]
	v_cmp_ne_u32_e64 s[2:3], 1, v8
	s_andn2_b64 vcc, exec, s[8:9]
	v_lshl_add_u64 v[8:9], v[6:7], 2, s[4:5]
	s_cbranch_vccnz .LBB0_2949
	global_load_dword v7, v[8:9], off
	s_waitcnt vmcnt(0)
	v_mul_f32_e32 v17, v17, v7

; template <bool UPMAP = false>
; DI void transpose_item(const float* W, int K, int N, bf16_t* WT, const float* gain, LAS float* scr, int item, int lane) {
;     const int nblk = N / 32, kb = item / nblk, nb = item % nblk, k0 = 64 * kb, n0 = 32 * nb;
;     const int r0 = !UPMAP ? n0 : (n0 < DFF ? ((n0 >> 7) << 8) + (n0 & 127) : (((n0 - DFF) >> 7) << 8) + 128 + ((n0 - DFF) & 127));
; #pragma unroll
;     for (int i = 0; i < 32; ++i) { const int kk = 2 * i + (lane >> 5); float v = W[(size_t)(k0 + kk) * N + n0 + (lane & 31)]; if (gain) v *= gain[k0 + kk]; scr[kk * 33 + (lane & 31)] = v; }
;     asm volatile("s_waitcnt lgkmcnt(0)" ::: "memory");
; template <bool UPMAP = false>
; DI void convert_matrix(const float* W, int K, int N, bf16_t* WT, const float* gain, LAS float* scr, int gw, int ngw, int lane) {
;     ...
;     for (int it = gw; it < nitems; it += ngw) transpose_item<UPMAP>(W, K, N, WT, gain, scr, it, lane);
.LBB0_3013:
	s_ashr_i32 s0, s6, 31
	s_lshr_b32 s0, s0, 27
	s_add_i32 s0, s6, s0
	s_ashr_i32 s0, s0, 5
	s_lshl_b32 s2, s0, 6
	s_lshl_b32 s0, s0, 10
	s_sub_i32 s0, s4, s0
	v_or_b32_e32 v6, s2, v10
	s_ashr_i32 s1, s0, 31
	v_ashrrev_i32_e32 v7, 31, v6
	v_lshl_add_u64 v[4:5], s[0:1], 2, v[0:1]
	v_lshlrev_b64 v[12:13], 12, v[6:7]
	v_lshl_add_u64 v[12:13], v[4:5], 0, v[12:13]
	v_mov_b32_e32 v102, 0x2000
	v_mov_b32_e32 v103, 0
	v_mov_b64_e32 v[100:101], v[12:13]
	v_lshl_add_u64 v[100:101], v[102:103], 0, v[100:101]
	global_load_dword v104, v[100:101], off
	v_lshl_add_u64 v[100:101], v[102:103], 0, v[100:101]
	global_load_dword v104, v[100:101], off
	v_lshl_add_u64 v[100:101], v[102:103], 0, v[100:101]
	global_load_dword v104, v[100:101], off
	v_lshl_add_u64 v[100:101], v[102:103], 0, v[100:101]
	global_load_dword v104, v[100:101], off
	v_lshl_add_u64 v[100:101], v[102:103], 0, v[100:101]
	global_load_dword v104, v[100:101], off
	v_lshl_add_u64 v[100:101], v[102:103], 0, v[100:101]
	global_load_dword v104, v[100:101], off
	v_lshl_add_u64 v[100:101], v[102:103], 0, v[100:101]
	global_load_dword v104, v[100:101], off
	v_lshl_add_u64 v[100:101], v[102:103], 0, v[100:101]
	global_load_dword v104, v[100:101], off
	v_lshl_add_u64 v[100:101], v[102:103], 0, v[100:101]
	global_load_dword v104, v[100:101], off
	v_lshl_add_u64 v[100:101], v[102:103], 0, v[100:101]
	global_load_dword v104, v[100:101], off
	v_lshl_add_u64 v[100:101], v[102:103], 0, v[100:101]
	global_load_dword v104, v[100:101], off
	v_lshl_add_u64 v[100:101], v[102:103], 0, v[100:101]
	global_load_dword v104, v[100:101], off
	v_lshl_add_u64 v[100:101], v[102:103], 0, v[100:101]
	global_load_dword v104, v[100:101], off
	v_lshl_add_u64 v[100:101], v[102:103], 0, v[100:101]
	global_load_dword v104, v[100:101], off
	v_lshl_add_u64 v[100:101], v[102:103], 0, v[100:101]
	global_load_dword v104, v[100:101], off
	v_lshl_add_u64 v[100:101], v[102:103], 0, v[100:101]
	global_load_dword v104, v[100:101], off
	v_lshl_add_u64 v[100:101], v[102:103], 0, v[100:101]
	global_load_dword v104, v[100:101], off
	v_lshl_add_u64 v[100:101], v[102:103], 0, v[100:101]
	global_load_dword v104, v[100:101], off
	v_lshl_add_u64 v[100:101], v[102:103], 0, v[100:101]
	global_load_dword v104, v[100:101], off
	v_lshl_add_u64 v[100:101], v[102:103], 0, v[100:101]
	global_load_dword v104, v[100:101], off
	v_lshl_add_u64 v[100:101], v[102:103], 0, v[100:101]
	global_load_dword v104, v[100:101], off
	v_lshl_add_u64 v[100:101], v[102:103], 0, v[100:101]
	global_load_dword v104, v[100:101], off
	v_lshl_add_u64 v[100:101], v[102:103], 0, v[100:101]
	global_load_dword v104, v[100:101], off
	v_lshl_add_u64 v[100:101], v[102:103], 0, v[100:101]
	global_load_dword v104, v[100:101], off
	v_lshl_add_u64 v[100:101], v[102:103], 0, v[100:101]
	global_load_dword v104, v[100:101], off
	v_lshl_add_u64 v[100:101], v[102:103], 0, v[100:101]
	global_load_dword v104, v[100:101], off
	v_lshl_add_u64 v[100:101], v[102:103], 0, v[100:101]
	global_load_dword v104, v[100:101], off
	v_lshl_add_u64 v[100:101], v[102:103], 0, v[100:101]
	global_load_dword v104, v[100:101], off
	v_lshl_add_u64 v[100:101], v[102:103], 0, v[100:101]
	global_load_dword v104, v[100:101], off
	v_lshl_add_u64 v[100:101], v[102:103], 0, v[100:101]
	global_load_dword v104, v[100:101], off
	v_lshl_add_u64 v[100:101], v[102:103], 0, v[100:101]
	global_load_dword v104, v[100:101], off
	global_load_dword v7, v[12:13], off
	v_add_u32_e32 v12, 2, v6
	v_ashrrev_i32_e32 v13, 31, v12
	v_lshlrev_b64 v[12:13], 12, v[12:13]
	v_lshl_add_u64 v[12:13], v[4:5], 0, v[12:13]
	global_load_dword v12, v[12:13], off
	v_add_u32_e32 v14, 0x400, v9
	s_ashr_i32 s3, s2, 31
	v_add_u32_e32 v32, s0, v11
	s_add_i32 s6, s6, s79
	s_add_i32 s4, s4, s5
	s_cmpk_lt_i32 s6, 0x580
	s_waitcnt vmcnt(0)
	ds_write2_b32 v9, v7, v12 offset1:66
	v_or_b32_e32 v12, 4, v6
	v_ashrrev_i32_e32 v13, 31, v12
	v_lshlrev_b64 v[12:13], 12, v[12:13]
	v_lshl_add_u64 v[12:13], v[4:5], 0, v[12:13]
	global_load_dword v7, v[12:13], off
	v_add_u32_e32 v12, 6, v6
	v_ashrrev_i32_e32 v13, 31, v12
	v_lshlrev_b64 v[12:13], 12, v[12:13]
	v_lshl_add_u64 v[12:13], v[4:5], 0, v[12:13]
	global_load_dword v12, v[12:13], off
	s_waitcnt vmcnt(0)
	ds_write2_b32 v9, v7, v12 offset0:132 offset1:198
	v_or_b32_e32 v12, 8, v6
	v_ashrrev_i32_e32 v13, 31, v12
	v_lshlrev_b64 v[12:13], 12, v[12:13]
	v_lshl_add_u64 v[12:13], v[4:5], 0, v[12:13]
	global_load_dword v7, v[12:13], off
	v_add_u32_e32 v12, 10, v6
	v_ashrrev_i32_e32 v13, 31, v12
	v_lshlrev_b64 v[12:13], 12, v[12:13]
	v_lshl_add_u64 v[12:13], v[4:5], 0, v[12:13]
	global_load_dword v12, v[12:13], off
	s_waitcnt vmcnt(0)
	ds_write2_b32 v14, v7, v12 offset0:8 offset1:74
	v_or_b32_e32 v12, 12, v6
	v_ashrrev_i32_e32 v13, 31, v12
	v_lshlrev_b64 v[12:13], 12, v[12:13]
	v_lshl_add_u64 v[12:13], v[4:5], 0, v[12:13]
	global_load_dword v7, v[12:13], off
	v_add_u32_e32 v12, 14, v6
	v_ashrrev_i32_e32 v13, 31, v12
	v_lshlrev_b64 v[12:13], 12, v[12:13]
	v_lshl_add_u64 v[12:13], v[4:5], 0, v[12:13]
	global_load_dword v12, v[12:13], off
	s_waitcnt vmcnt(0)
	ds_write2_b32 v14, v7, v12 offset0:140 offset1:206
	v_or_b32_e32 v12, 16, v6
	v_ashrrev_i32_e32 v13, 31, v12
	v_lshlrev_b64 v[12:13], 12, v[12:13]
	v_lshl_add_u64 v[12:13], v[4:5], 0, v[12:13]
	global_load_dword v7, v[12:13], off
	v_add_u32_e32 v12, 18, v6
	v_ashrrev_i32_e32 v13, 31, v12
	v_lshlrev_b64 v[12:13], 12, v[12:13]
	v_lshl_add_u64 v[12:13], v[4:5], 0, v[12:13]
	global_load_dword v12, v[12:13], off
	v_add_u32_e32 v14, 0x800, v9
	s_waitcnt vmcnt(0)
; #define LAS __attribute__((address_space(3)))
; DI unsigned pk2(float lo, float hi) { f32x2 v = {lo, hi}; bf16x2_t b = __builtin_convertvector(v, bf16x2_t); return __builtin_bit_cast(unsigned, b); }
; template <bool UPMAP = false>
; DI void transpose_item(const float* W, int K, int N, bf16_t* WT, const float* gain, LAS float* scr, int item, int lane) {
;     ...
;     for (int i = 0; i < 32; ++i) { const int kk = 2 * i + (lane >> 5); float v = W[(size_t)(k0 + kk) * N + n0 + (lane & 31)]; if (gain) v *= gain[k0 + kk]; scr[kk * 33 + (lane & 31)] = v; }
;     asm volatile("s_waitcnt lgkmcnt(0)" ::: "memory");
;     const int c = lane & 7;
; #pragma unroll
;     for (int j = 0; j < 4; ++j) { const int n = (lane >> 3) + 8 * j; const LAS float* s = scr + (8 * c) * 33 + n;
;         u32x4 o; o.x = pk2(s[0 * 33], s[1 * 33]); o.y = pk2(s[2 * 33], s[3 * 33]); o.z = pk2(s[4 * 33], s[5 * 33]); o.w = pk2(s[6 * 33], s[7 * 33]);
;         *(u32x4*)(WT + (size_t)(r0 + n) * K + k0 + 8 * c) = o; }
;     asm volatile("s_waitcnt lgkmcnt(0)" ::: "memory");
; }
	ds_write2_b32 v14, v7, v12 offset0:16 offset1:82
	v_or_b32_e32 v12, 20, v6
	v_ashrrev_i32_e32 v13, 31, v12
	v_lshlrev_b64 v[12:13], 12, v[12:13]
	v_lshl_add_u64 v[12:13], v[4:5], 0, v[12:13]
	global_load_dword v7, v[12:13], off
	v_add_u32_e32 v12, 22, v6
	v_ashrrev_i32_e32 v13, 31, v12
	v_lshlrev_b64 v[12:13], 12, v[12:13]
	v_lshl_add_u64 v[12:13], v[4:5], 0, v[12:13]
	global_load_dword v12, v[12:13], off
	s_waitcnt vmcnt(0)
	ds_write2_b32 v14, v7, v12 offset0:148 offset1:214
	v_or_b32_e32 v12, 24, v6
	v_ashrrev_i32_e32 v13, 31, v12
	v_lshlrev_b64 v[12:13], 12, v[12:13]
	v_lshl_add_u64 v[12:13], v[4:5], 0, v[12:13]
	global_load_dword v7, v[12:13], off
	v_add_u32_e32 v12, 26, v6
	v_ashrrev_i32_e32 v13, 31, v12
	v_lshlrev_b64 v[12:13], 12, v[12:13]
	v_lshl_add_u64 v[12:13], v[4:5], 0, v[12:13]
	global_load_dword v12, v[12:13], off
	v_add_u32_e32 v14, 0xc00, v9
	s_waitcnt vmcnt(0)
	ds_write2_b32 v14, v7, v12 offset0:24 offset1:90
	v_or_b32_e32 v12, 28, v6
	v_ashrrev_i32_e32 v13, 31, v12
	v_lshlrev_b64 v[12:13], 12, v[12:13]
	v_lshl_add_u64 v[12:13], v[4:5], 0, v[12:13]
	global_load_dword v7, v[12:13], off
	v_add_u32_e32 v12, 30, v6
	v_ashrrev_i32_e32 v13, 31, v12
	v_lshlrev_b64 v[12:13], 12, v[12:13]
	v_lshl_add_u64 v[12:13], v[4:5], 0, v[12:13]
	global_load_dword v12, v[12:13], off
	s_waitcnt vmcnt(0)
	ds_write2_b32 v14, v7, v12 offset0:156 offset1:222
	v_or_b32_e32 v12, 32, v6
	v_ashrrev_i32_e32 v13, 31, v12
	v_lshlrev_b64 v[12:13], 12, v[12:13]
	v_lshl_add_u64 v[12:13], v[4:5], 0, v[12:13]
	global_load_dword v7, v[12:13], off
	v_add_u32_e32 v12, 34, v6
	v_ashrrev_i32_e32 v13, 31, v12
	v_lshlrev_b64 v[12:13], 12, v[12:13]
	v_lshl_add_u64 v[12:13], v[4:5], 0, v[12:13]
	global_load_dword v12, v[12:13], off
	v_add_u32_e32 v14, 0x1000, v9
	s_waitcnt vmcnt(0)
	ds_write2_b32 v14, v7, v12 offset0:32 offset1:98
	v_or_b32_e32 v12, 36, v6
	v_ashrrev_i32_e32 v13, 31, v12
	v_lshlrev_b64 v[12:13], 12, v[12:13]
	v_lshl_add_u64 v[12:13], v[4:5], 0, v[12:13]
	global_load_dword v7, v[12:13], off
	v_add_u32_e32 v12, 38, v6
	v_ashrrev_i32_e32 v13, 31, v12
	v_lshlrev_b64 v[12:13], 12, v[12:13]
	v_lshl_add_u64 v[12:13], v[4:5], 0, v[12:13]
	global_load_dword v12, v[12:13], off
	s_waitcnt vmcnt(0)
	ds_write2_b32 v14, v7, v12 offset0:164 offset1:230
	v_or_b32_e32 v12, 40, v6
	v_ashrrev_i32_e32 v13, 31, v12
	v_lshlrev_b64 v[12:13], 12, v[12:13]
	v_lshl_add_u64 v[12:13], v[4:5], 0, v[12:13]
	global_load_dword v7, v[12:13], off
	v_add_u32_e32 v12, 42, v6
	v_ashrrev_i32_e32 v13, 31, v12
	v_lshlrev_b64 v[12:13], 12, v[12:13]
	v_lshl_add_u64 v[12:13], v[4:5], 0, v[12:13]
	global_load_dword v12, v[12:13], off
	v_add_u32_e32 v14, 0x1400, v9
	s_waitcnt vmcnt(0)
	ds_write2_b32 v14, v7, v12 offset0:40 offset1:106
	v_or_b32_e32 v12, 44, v6
	v_ashrrev_i32_e32 v13, 31, v12
	v_lshlrev_b64 v[12:13], 12, v[12:13]
	v_lshl_add_u64 v[12:13], v[4:5], 0, v[12:13]
	global_load_dword v7, v[12:13], off
	v_add_u32_e32 v12, 46, v6
	v_ashrrev_i32_e32 v13, 31, v12
	v_lshlrev_b64 v[12:13], 12, v[12:13]
	v_lshl_add_u64 v[12:13], v[4:5], 0, v[12:13]
	global_load_dword v12, v[12:13], off
	s_waitcnt vmcnt(0)
	ds_write2_b32 v14, v7, v12 offset0:172 offset1:238
	v_or_b32_e32 v12, 48, v6
	v_ashrrev_i32_e32 v13, 31, v12
	v_lshlrev_b64 v[12:13], 12, v[12:13]
	v_lshl_add_u64 v[12:13], v[4:5], 0, v[12:13]
	global_load_dword v7, v[12:13], off
	v_add_u32_e32 v12, 50, v6
	v_ashrrev_i32_e32 v13, 31, v12
	v_lshlrev_b64 v[12:13], 12, v[12:13]
	v_lshl_add_u64 v[12:13], v[4:5], 0, v[12:13]
	global_load_dword v12, v[12:13], off
	v_add_u32_e32 v14, 0x1800, v9
	s_waitcnt vmcnt(0)
	ds_write2_b32 v14, v7, v12 offset0:48 offset1:114
	v_or_b32_e32 v12, 52, v6
	v_ashrrev_i32_e32 v13, 31, v12
	v_lshlrev_b64 v[12:13], 12, v[12:13]
	v_lshl_add_u64 v[12:13], v[4:5], 0, v[12:13]
	global_load_dword v7, v[12:13], off
	v_add_u32_e32 v12, 54, v6
	v_ashrrev_i32_e32 v13, 31, v12
	v_lshlrev_b64 v[12:13], 12, v[12:13]
	v_lshl_add_u64 v[12:13], v[4:5], 0, v[12:13]
	global_load_dword v12, v[12:13], off
	s_waitcnt vmcnt(0)
	ds_write2_b32 v14, v7, v12 offset0:180 offset1:246
	v_or_b32_e32 v12, 56, v6
	v_ashrrev_i32_e32 v13, 31, v12
	v_lshlrev_b64 v[12:13], 12, v[12:13]
	v_lshl_add_u64 v[12:13], v[4:5], 0, v[12:13]
	global_load_dword v7, v[12:13], off
	v_add_u32_e32 v12, 58, v6
	v_ashrrev_i32_e32 v13, 31, v12
	v_lshlrev_b64 v[12:13], 12, v[12:13]
	v_lshl_add_u64 v[12:13], v[4:5], 0, v[12:13]
	global_load_dword v13, v[12:13], off
	v_add_u32_e32 v12, 0x1c00, v9
	v_or_b32_e32 v14, 60, v6
	v_add_u32_e32 v6, 62, v6
	v_ashrrev_i32_e32 v15, 31, v14
	v_lshlrev_b64 v[14:15], 12, v[14:15]
	v_lshl_add_u64 v[14:15], v[4:5], 0, v[14:15]
	s_waitcnt vmcnt(0)
	ds_write2_b32 v12, v7, v13 offset0:56 offset1:122
	v_ashrrev_i32_e32 v7, 31, v6
	v_lshlrev_b64 v[6:7], 12, v[6:7]
	v_lshl_add_u64 v[4:5], v[4:5], 0, v[6:7]
	global_load_dword v13, v[14:15], off
	s_nop 0
	global_load_dword v4, v[4:5], off
	s_waitcnt vmcnt(0)
	ds_write2_b32 v12, v13, v4 offset0:188 offset1:254
	s_waitcnt lgkmcnt(0)
	ds_read2_b32 v[14:15], v8 offset0:33 offset1:41
	ds_read2_b32 v[16:17], v8 offset1:8
	ds_read2_b32 v[18:19], v8 offset0:66 offset1:74
	ds_read2_b32 v[20:21], v8 offset0:99 offset1:107
	ds_read2_b32 v[22:23], v8 offset0:132 offset1:140
	ds_read2_b32 v[24:25], v8 offset0:165 offset1:173
	ds_read2_b32 v[26:27], v8 offset0:198 offset1:206
	ds_read2_b32 v[28:29], v8 offset0:231 offset1:239
	v_lshl_add_u64 v[12:13], s[2:3], 1, v[2:3]
	s_waitcnt lgkmcnt(6)
	v_cvt_pk_bf16_f32 v4, v16, v14
	s_waitcnt lgkmcnt(4)
	v_cvt_pk_bf16_f32 v5, v18, v20
	s_waitcnt lgkmcnt(2)
	v_cvt_pk_bf16_f32 v6, v22, v24
	s_waitcnt lgkmcnt(0)
	v_cvt_pk_bf16_f32 v7, v26, v28
	v_mad_i64_i32 v[30:31], s[0:1], v32, s65, v[12:13]
	v_add_u32_e32 v14, 8, v32
	global_store_dwordx4 v[30:31], v[4:7], off
	s_nop 1
	v_cvt_pk_bf16_f32 v4, v17, v15
	v_cvt_pk_bf16_f32 v5, v19, v21
	v_cvt_pk_bf16_f32 v6, v23, v25
	v_cvt_pk_bf16_f32 v7, v27, v29
	v_mad_i64_i32 v[14:15], s[0:1], v14, s65, v[12:13]
	global_store_dwordx4 v[14:15], v[4:7], off
	ds_read2_b32 v[14:15], v8 offset0:49 offset1:57
	ds_read2_b32 v[16:17], v8 offset0:16 offset1:24
	ds_read2_b32 v[18:19], v8 offset0:82 offset1:90
	ds_read2_b32 v[20:21], v8 offset0:115 offset1:123
	ds_read2_b32 v[22:23], v8 offset0:148 offset1:156
	ds_read2_b32 v[24:25], v8 offset0:181 offset1:189
	ds_read2_b32 v[26:27], v8 offset0:214 offset1:222
	ds_read2_b32 v[28:29], v8 offset0:247 offset1:255
	s_waitcnt lgkmcnt(6)
	v_cvt_pk_bf16_f32 v4, v16, v14
	v_add_u32_e32 v14, 16, v32
	s_waitcnt lgkmcnt(4)
	v_cvt_pk_bf16_f32 v5, v18, v20
	s_waitcnt lgkmcnt(2)
	v_cvt_pk_bf16_f32 v6, v22, v24
	s_waitcnt lgkmcnt(0)
	v_cvt_pk_bf16_f32 v7, v26, v28
	v_mad_i64_i32 v[30:31], s[0:1], v14, s65, v[12:13]
	v_add_u32_e32 v14, 24, v32
	global_store_dwordx4 v[30:31], v[4:7], off
	v_mad_i64_i32 v[12:13], s[0:1], v14, s65, v[12:13]
	s_nop 0
	v_cvt_pk_bf16_f32 v4, v17, v15
	v_cvt_pk_bf16_f32 v5, v19, v21
	v_cvt_pk_bf16_f32 v6, v23, v25
	v_cvt_pk_bf16_f32 v7, v27, v29
	global_store_dwordx4 v[12:13], v[4:7], off
	s_waitcnt lgkmcnt(0)
	s_cbranch_scc1 .LBB0_3013
